# Differential attention: one unit serves both 64-column V halves (shared Q.K^T + softmax); second V ring in LDS, second P.V pass into v[224:255], O epilogue run twice; 4 units per workgroup
# speedup vs baseline: 1.0434x; 1.0358x over previous
.LBB0_229:
	v_lshlrev_b32_e32 v225, 2, v206
	v_add_u32_e32 v225, 0x1b000, v225
	ds_write_b32 v225, v254
	s_mov_b32 s26, 0xffff0000
	s_mov_b32 s9, 0
	v_mov_b32_e32 v1, 0
	s_mov_b64 s[10:11], 0x12000000
	s_mov_b64 s[12:13], 0x14000000
	s_mov_b64 s[14:15], 0x12010000
	s_mov_b64 s[16:17], 0x10000000
	s_brev_b32 s51, 8
	s_mov_b64 s[18:19], 0x12020000
	s_mov_b64 s[20:21], 0x30000
	s_mov_b64 s[22:23], 0x10000
	s_mov_b64 s[24:25], 0x50000
	s_mov_b32 s27, -1
	s_mov_b32 s52, 0x41000000
	s_mov_b64 s[28:29], 0x20000
	s_mov_b64 s[30:31], 0x40000
	s_mov_b64 s[34:35], 0x1c000000
	v_mov_b32_e32 v207, 0xff800000
	s_branch .LBB0_231

.LBB0_231:
	s_lshl_b32 s3, s50, 4
	s_ashr_i32 s2, s50, 5
	s_and_b32 s4, s3, 0x180
	s_and_b32 s5, s3, 64
	s_lshl_b32 s3, s50, 5
	s_mov_b32 s6, 0
	s_and_b32 s7, s3, 0x380
	s_ashr_i32 s3, s2, 31
	s_lshl_b64 s[36:37], s[2:3], 12
	s_lshl_b64 s[2:3], s[2:3], 21
	s_and_b32 s53, s50, 3
	s_lshl_b32 s54, s4, 1
	s_lshl_b32 s55, s5, 1
	s_lshl_b32 s56, s6, 1
	s_lshl_b64 s[38:39], s[2:3], 1
	s_lshl_b32 s57, s7, 1
	s_mov_b32 s58, s9
	s_branch .LBB0_233
.LBB0_232:
	s_or_b64 exec, exec, s[2:3]
	s_waitcnt lgkmcnt(0)
	s_mov_b32 s101, 0
	v_mov_b32_e32 v51, v2
.Lattn_ep_0:
	ds_read_b128 v[4:7], v2 offset:49280
	ds_read_b128 v[8:11], v2 offset:49312
	s_add_u32 s4, s42, s57
	s_addc_u32 s5, s43, 0
	s_lshl_b32 s6, s59, 12
	s_waitcnt lgkmcnt(1)
	v_rcp_f32_e32 v0, v4
	v_rcp_f32_e32 v3, v5
	v_rcp_f32_e32 v12, v6
	v_rcp_f32_e32 v13, v7
	s_waitcnt lgkmcnt(0)
	v_rcp_f32_e32 v14, v8
	ds_read_b128 v[4:7], v2 offset:49344
	v_rcp_f32_e32 v15, v9
	v_rcp_f32_e32 v48, v10
	v_rcp_f32_e32 v49, v11
	ds_read_b128 v[8:11], v2 offset:49376
	s_waitcnt lgkmcnt(1)
	v_rcp_f32_e32 v2, v4
	v_rcp_f32_e32 v4, v5
	v_rcp_f32_e32 v5, v6
	v_rcp_f32_e32 v6, v7
	s_waitcnt lgkmcnt(0)
	v_rcp_f32_e32 v7, v8
	v_rcp_f32_e32 v8, v9
	v_rcp_f32_e32 v9, v10
	v_rcp_f32_e32 v10, v11
	s_add_i32 s6, s6, 0
	v_lshlrev_b32_e32 v11, 1, v210
	v_lshlrev_b32_e32 v50, 9, v211
	v_mul_f32_e32 v32, v32, v0
	v_mul_f32_e32 v0, v16, v0
	v_add3_u32 v11, s6, v11, v50
	v_cvt_pk_bf16_f32 v0, v0, s0
	ds_write_b16 v11, v0 offset:51264
	v_mul_f32_e32 v0, v33, v3
	v_cvt_pk_bf16_f32 v0, v0, s0
	ds_write_b16 v11, v0 offset:51328
	v_mul_f32_e32 v0, v17, v3
	v_cvt_pk_bf16_f32 v0, v0, s0
	ds_write_b16 v11, v0 offset:51392
	v_mul_f32_e32 v0, v34, v12
	v_cvt_pk_bf16_f32 v0, v0, s0
	ds_write_b16 v11, v0 offset:51456
	v_mul_f32_e32 v0, v18, v12
	v_cvt_pk_bf16_f32 v0, v0, s0
	ds_write_b16 v11, v0 offset:51520
	v_mul_f32_e32 v0, v35, v13
	v_cvt_pk_bf16_f32 v0, v0, s0
	ds_write_b16 v11, v0 offset:51584
	v_mul_f32_e32 v0, v19, v13
	v_cvt_pk_bf16_f32 v0, v0, s0
	ds_write_b16 v11, v0 offset:51648
	v_mul_f32_e32 v0, v36, v14
	v_cvt_pk_bf16_f32 v0, v0, s0
	ds_write_b16 v11, v0 offset:52224
	v_mul_f32_e32 v0, v20, v14
	v_cvt_pk_bf16_f32 v0, v0, s0
	ds_write_b16 v11, v0 offset:52288
	v_mul_f32_e32 v0, v37, v15
	v_cvt_pk_bf16_f32 v0, v0, s0
	ds_write_b16 v11, v0 offset:52352
	v_mul_f32_e32 v0, v21, v15
	v_cvt_pk_bf16_f32 v0, v0, s0
	ds_write_b16 v11, v0 offset:52416
	v_mul_f32_e32 v0, v38, v48
	v_cvt_pk_bf16_f32 v0, v0, s0
	ds_write_b16 v11, v0 offset:52480
	v_mul_f32_e32 v0, v22, v48
	v_cvt_pk_bf16_f32 v0, v0, s0
	ds_write_b16 v11, v0 offset:52544
	v_mul_f32_e32 v0, v39, v49
	v_cvt_pk_bf16_f32 v0, v0, s0
	ds_write_b16 v11, v0 offset:52608
	v_mul_f32_e32 v0, v23, v49
	v_cvt_pk_bf16_f32 v0, v0, s0
	ds_write_b16 v11, v0 offset:52672
	v_mul_f32_e32 v0, v40, v2
	v_cvt_pk_bf16_f32 v0, v0, s0
	ds_write_b16 v11, v0 offset:53248
	v_mul_f32_e32 v0, v24, v2
	v_cvt_pk_bf16_f32 v0, v0, s0
	ds_write_b16 v11, v0 offset:53312
	v_mul_f32_e32 v0, v41, v4
	v_cvt_pk_bf16_f32 v0, v0, s0
	ds_write_b16 v11, v0 offset:53376
	v_mul_f32_e32 v0, v25, v4
	v_cvt_pk_bf16_f32 v0, v0, s0
	ds_write_b16 v11, v0 offset:53440
	v_mul_f32_e32 v0, v42, v5
	v_cvt_pk_bf16_f32 v0, v0, s0
	ds_write_b16 v11, v0 offset:53504
	v_mul_f32_e32 v0, v26, v5
	v_cvt_pk_bf16_f32 v0, v0, s0
	ds_write_b16 v11, v0 offset:53568
	v_mul_f32_e32 v0, v43, v6
	v_cvt_pk_bf16_f32 v0, v0, s0
	ds_write_b16 v11, v0 offset:53632
	v_mul_f32_e32 v0, v27, v6
	v_cvt_pk_bf16_f32 v0, v0, s0
	ds_write_b16 v11, v0 offset:53696
	v_mul_f32_e32 v0, v44, v7
	v_cvt_pk_bf16_f32 v0, v0, s0
	ds_write_b16 v11, v0 offset:54272
	v_mul_f32_e32 v0, v28, v7
	v_cvt_pk_bf16_f32 v0, v0, s0
	ds_write_b16 v11, v0 offset:54336
	v_mul_f32_e32 v0, v45, v8
	v_cvt_pk_bf16_f32 v0, v0, s0
	ds_write_b16 v11, v0 offset:54400
	v_mul_f32_e32 v0, v29, v8
	v_cvt_pk_bf16_f32 v0, v0, s0
	ds_write_b16 v11, v0 offset:54464
	v_mul_f32_e32 v0, v46, v9
	v_cvt_pk_bf16_f32 v0, v0, s0
	ds_write_b16 v11, v0 offset:54528
	v_mul_f32_e32 v0, v30, v9
	v_cvt_pk_bf16_f32 v0, v0, s0
	ds_write_b16 v11, v0 offset:54592
	v_mul_f32_e32 v0, v47, v10
	v_cvt_pk_bf16_f32 v0, v0, s0
	ds_write_b16 v11, v0 offset:54656
	v_mul_f32_e32 v0, v31, v10
	v_cvt_pk_bf16_f32 v0, v0, s0
	s_lshl_b64 s[2:3], s[40:41], 11
	ds_write_b16 v11, v0 offset:54720
	v_lshlrev_b32_e32 v0, 1, v209
	v_cvt_pk_bf16_f32 v32, v32, s0
	s_add_u32 s2, s4, s2
	v_and_b32_e32 v0, 0x70, v0
	ds_write_b16 v11, v32 offset:51200
	s_addc_u32 s3, s5, s3
	v_lshrrev_b32_e32 v14, 3, v208
	v_add_u32_e32 v15, s6, v0
	s_waitcnt lgkmcnt(0)
	v_lshl_add_u64 v[2:3], s[2:3], 0, v[0:1]
	v_lshl_add_u32 v0, v14, 7, v15
	v_or_b32_e32 v16, 8, v14
	v_lshl_add_u64 v[10:11], v[2:3], 0, s[34:35]
	ds_read_b128 v[2:5], v0 offset:51200
	v_lshl_add_u32 v6, v16, 7, v15
	ds_read_b128 v[6:9], v6 offset:51200
	v_lshlrev_b32_e32 v0, 11, v14
	v_lshl_add_u64 v[12:13], v[10:11], 0, v[0:1]
	v_lshlrev_b32_e32 v0, 11, v16
	s_waitcnt lgkmcnt(1)
	global_store_dwordx4 v[12:13], v[2:5], off
	s_add_i32 s58, s58, 1
	s_cmp_eq_u32 s58, 4
	v_lshl_add_u64 v[2:3], v[10:11], 0, v[0:1]
	v_or_b32_e32 v0, 16, v14
	s_waitcnt lgkmcnt(0)
	global_store_dwordx4 v[2:3], v[6:9], off
	v_lshl_add_u32 v2, v0, 7, v15
	v_or_b32_e32 v14, 24, v14
	ds_read_b128 v[2:5], v2 offset:51200
	v_lshl_add_u32 v6, v14, 7, v15
	ds_read_b128 v[6:9], v6 offset:51200
	v_lshlrev_b32_e32 v0, 11, v0
	v_lshl_add_u64 v[12:13], v[10:11], 0, v[0:1]
	v_lshlrev_b32_e32 v0, 11, v14
	s_waitcnt lgkmcnt(1)
	global_store_dwordx4 v[12:13], v[2:5], off
	s_nop 1
	v_lshl_add_u64 v[2:3], v[10:11], 0, v[0:1]
	s_waitcnt lgkmcnt(0)
	global_store_dwordx4 v[2:3], v[6:9], off
	s_nop 1
	s_cmp_lg_u32 s101, 0
	s_cbranch_scc1 .Lattn_ep_done_0
	s_mov_b32 s101, 1
	v_mov_b32_e32 v16, v240
	v_mov_b32_e32 v17, v241
	v_mov_b32_e32 v18, v242
	v_mov_b32_e32 v19, v243
	v_mov_b32_e32 v20, v244
	v_mov_b32_e32 v21, v245
	v_mov_b32_e32 v22, v246
	v_mov_b32_e32 v23, v247
	v_mov_b32_e32 v24, v248
	v_mov_b32_e32 v25, v249
	v_mov_b32_e32 v26, v250
	v_mov_b32_e32 v27, v251
	v_mov_b32_e32 v28, v252
	v_mov_b32_e32 v29, v253
	v_mov_b32_e32 v30, v254
	v_mov_b32_e32 v31, v255
	v_mov_b32_e32 v32, v224
	v_mov_b32_e32 v33, v225
	v_mov_b32_e32 v34, v226
	v_mov_b32_e32 v35, v227
	v_mov_b32_e32 v36, v228
	v_mov_b32_e32 v37, v229
	v_mov_b32_e32 v38, v230
	v_mov_b32_e32 v39, v231
	v_mov_b32_e32 v40, v232
	v_mov_b32_e32 v41, v233
	v_mov_b32_e32 v42, v234
	v_mov_b32_e32 v43, v235
	v_mov_b32_e32 v44, v236
	v_mov_b32_e32 v45, v237
	v_mov_b32_e32 v46, v238
	v_mov_b32_e32 v47, v239
	v_mov_b32_e32 v2, v51
	s_add_u32 s57, s57, 0x80
	s_sub_u32 s58, s58, 1
	s_branch .Lattn_ep_0
.Lattn_ep_done_0:
	s_sub_u32 s57, s57, 0x80
	s_cmp_eq_u32 s58, 4
	s_waitcnt lgkmcnt(0)
	s_barrier
	s_cbranch_scc1 .LBB0_230
.LBB0_233:
	v_mov_b64_e32 v[224:225], 0
	v_mov_b64_e32 v[226:227], 0
	v_mov_b64_e32 v[228:229], 0
	v_mov_b64_e32 v[230:231], 0
	v_mov_b64_e32 v[232:233], 0
	v_mov_b64_e32 v[234:235], 0
	v_mov_b64_e32 v[236:237], 0
	v_mov_b64_e32 v[238:239], 0
	v_mov_b64_e32 v[240:241], 0
	v_mov_b64_e32 v[242:243], 0
	v_mov_b64_e32 v[244:245], 0
	v_mov_b64_e32 v[246:247], 0
	v_mov_b64_e32 v[248:249], 0
	v_mov_b64_e32 v[250:251], 0
	v_mov_b64_e32 v[252:253], 0
	v_mov_b64_e32 v[254:255], 0
	s_mov_b64 s[2:3], s[0:1]
	s_load_dwordx2 s[2:3], s[2:3], 0xf0
	s_and_b32 s4, s58, 2
	s_lshl_b32 s4, s4, 1
	s_and_b32 s8, s58, 1
	s_or_b32 s4, s4, s53
	s_mov_b64 s[6:7], s[0:1]
	s_waitcnt lgkmcnt(0)
	s_add_u32 s2, s2, s54
	s_addc_u32 s3, s3, 0
	s_add_u32 s45, s2, s55
	s_addc_u32 s46, s3, 0
	s_add_u32 s47, s2, s56
	v_mov_b32_e32 v36, v206
	s_addc_u32 s48, s3, 0
	s_lshl_b32 s2, s4, 8
	v_readfirstlane_b32 s5, v36
	s_ashr_i32 s59, s5, 6
	s_xor_b32 s3, s2, 0xf00
	s_cmp_eq_u32 s8, 0
	s_cselect_b32 s44, s2, s3
	s_lshl_b32 s8, s59, 5
	s_or_b32 s2, s36, s44
	s_ashr_i32 s3, s8, 31
	s_add_u32 s40, s2, s8
	s_addc_u32 s41, s37, s3
	s_lshl_b64 s[2:3], s[40:41], 10
	s_add_u32 s2, s45, s2
	s_addc_u32 s3, s46, s3
	s_load_dwordx2 s[42:43], s[6:7], 0xf0
	s_add_u32 s6, s45, s38
	v_and_b32_e32 v208, 63, v36
	s_addc_u32 s7, s46, s39
	s_add_u32 s46, s47, s38
	v_lshlrev_b32_e32 v0, 10, v208
	s_addc_u32 s47, s48, s39
	v_lshl_add_u64 v[2:3], s[6:7], 0, v[0:1]
	s_lshl_b32 s6, s59, 3
	s_lshl_b32 s4, s59, 4
	v_bfe_u32 v0, v36, 2, 4
	s_ashr_i32 s7, s6, 31
	v_and_or_b32 v0, s4, 48, v0
	s_ashr_i32 s4, s5, 3
	v_lshl_add_u64 v[4:5], s[6:7], 1, v[2:3]
	s_and_b32 s6, s4, 0xffffffe0
	v_lshlrev_b32_e32 v0, 10, v0
	s_ashr_i32 s7, s6, 31
	v_lshlrev_b32_e32 v209, 3, v36
	s_lshl_b32 s4, s59, 10
	v_lshl_add_u64 v[2:3], s[46:47], 0, v[0:1]
	v_and_b32_e32 v212, 24, v209
	s_cmp_lg_u32 0, -1
	v_and_b32_e32 v210, 31, v36
	v_lshl_add_u64 v[2:3], s[6:7], 1, v[2:3]
	v_lshlrev_b32_e32 v0, 1, v212
	s_cselect_b32 s6, 0, 0
	v_bfe_u32 v211, v36, 5, 1
	v_lshl_add_u64 v[196:197], v[4:5], 0, s[10:11]
	v_lshl_add_u64 v[2:3], v[2:3], 0, v[0:1]
	s_add_i32 s61, s4, s6
	s_mov_b32 s6, m0
	s_mov_b32 m0, s61
	s_nop 0
	global_load_lds_dwordx4 v[196:197], off
	s_mov_b32 m0, s6
	v_lshlrev_b32_e32 v0, 10, v210
	v_lshl_add_u64 v[34:35], v[2:3], 0, s[12:13]
	s_add_i32 s62, s61, 0x6000
	s_add_i32 s99, s62, 0xf000
	s_mov_b32 s6, m0
	s_mov_b32 m0, s62
	s_nop 0
	global_load_lds_dwordx4 v[34:35], off
	s_mov_b32 m0, s99
	v_lshl_add_u64 v[2:3], v[34:35], 0, 64
	v_lshl_add_u64 v[2:3], v[2:3], 0, 64
	global_load_lds_dwordx4 v[2:3], off
	s_mov_b32 m0, s6
	v_lshl_add_u64 v[2:3], v[4:5], 0, s[14:15]
	v_lshl_or_b32 v0, v211, 4, v0
	s_add_i32 s6, s61, 0x2000
	s_mov_b32 s7, m0
	s_mov_b32 m0, s6
	s_nop 0
	global_load_lds_dwordx4 v[2:3], off
	s_mov_b32 m0, s7
	v_lshl_add_u64 v[2:3], s[2:3], 0, v[0:1]
	v_add_co_u32_e32 v6, vcc, s51, v2
	v_lshlrev_b32_e32 v0, 10, v211
	s_nop 0
	v_addc_co_u32_e32 v7, vcc, 0, v3, vcc
	global_load_dwordx4 v[144:147], v[6:7], off
	v_lshl_add_u64 v[6:7], v[2:3], 0, s[16:17]
	global_load_dwordx4 v[136:139], v[6:7], off offset:32
	global_load_dwordx4 v[132:135], v[6:7], off offset:64
	global_load_dwordx4 v[128:131], v[6:7], off offset:96
	v_mov_b32_e32 v2, v1
	v_lshlrev_b32_e32 v3, 4, v210
	v_lshl_add_u64 v[4:5], v[4:5], 0, s[18:19]
	s_add_i32 s2, s61, 0x4000
	s_mov_b32 s3, m0
	s_mov_b32 m0, s2
	s_nop 0
	global_load_lds_dwordx4 v[4:5], off
	s_mov_b32 m0, s3
	v_add3_u32 v219, 0, v0, v3
	s_waitcnt vmcnt(3) lgkmcnt(0)
	s_barrier
	ds_read_b128 v[38:41], v219
	v_mov_b32_e32 v3, v2
	v_mov_b32_e32 v4, v2
	v_mov_b32_e32 v5, v2
	v_mov_b32_e32 v6, v2
	v_mov_b32_e32 v7, v2
	v_mov_b32_e32 v8, v2
	v_mov_b32_e32 v9, v2
	s_waitcnt vmcnt(13)
	v_mov_b32_e32 v10, v2
	v_mov_b32_e32 v11, v2
	v_mov_b32_e32 v12, v2
	v_mov_b32_e32 v13, v2
	s_waitcnt vmcnt(12)
	v_mov_b32_e32 v14, v2
	v_mov_b32_e32 v15, v2
	v_mov_b32_e32 v16, v2
	v_mov_b32_e32 v17, v2
	s_cmp_lg_u32 s44, 0
	s_cselect_b64 s[2:3], -1, 0
	v_lshlrev_b32_e32 v214, 2, v211
	v_or_b32_e32 v217, s8, v210
	s_and_b64 vcc, exec, s[2:3]
	s_waitcnt vmcnt(3) lgkmcnt(0)
	v_mfma_f32_32x32x16_bf16 v[18:33], v[38:41], v[144:147], v[2:17]
	ds_read_b128 v[38:41], v219 offset:512
	s_waitcnt lgkmcnt(0)
	v_mfma_f32_32x32x16_bf16 v[2:17], v[38:41], v[144:147], v[2:17]
	ds_read_b128 v[38:41], v219 offset:2048
	s_waitcnt vmcnt(2) lgkmcnt(0)
	v_mfma_f32_32x32x16_bf16 v[18:33], v[38:41], v[136:139], v[18:33]
	ds_read_b128 v[38:41], v219 offset:2560
	s_waitcnt lgkmcnt(0)
	v_mfma_f32_32x32x16_bf16 v[2:17], v[38:41], v[136:139], v[2:17]
	ds_read_b128 v[38:41], v219 offset:4096
	s_waitcnt vmcnt(1) lgkmcnt(0)
	v_mfma_f32_32x32x16_bf16 v[18:33], v[38:41], v[132:135], v[18:33]
	ds_read_b128 v[38:41], v219 offset:4608
	s_waitcnt lgkmcnt(0)
	v_mfma_f32_32x32x16_bf16 v[2:17], v[38:41], v[132:135], v[2:17]
	ds_read_b128 v[38:41], v219 offset:6144
	s_waitcnt vmcnt(0) lgkmcnt(0)
	v_mfma_f32_32x32x16_bf16 v[18:33], v[38:41], v[128:131], v[18:33]
	ds_read_b128 v[38:41], v219 offset:6656
	s_waitcnt lgkmcnt(0)
	v_mfma_f32_32x32x16_bf16 v[2:17], v[38:41], v[128:131], v[2:17]
	s_nop 15
	s_nop 7
	s_cbranch_vccnz .LBB0_235
	v_or_b32_e32 v0, 32, v214
	v_cmp_le_i32_e32 vcc, v0, v217
	v_or_b32_e32 v0, 33, v214
	s_nop 7
	v_cndmask_b32_e32 v2, v207, v2, vcc
	v_cmp_lt_i32_e32 vcc, v214, v217
	s_nop 1
	v_cndmask_b32_e32 v19, v207, v19, vcc
	v_cmp_le_i32_e32 vcc, v214, v217
	s_nop 1
	v_cndmask_b32_e32 v18, v207, v18, vcc
	v_cmp_le_i32_e32 vcc, v0, v217
	v_or_b32_e32 v0, 2, v214
	s_nop 0
	v_cndmask_b32_e32 v3, v207, v3, vcc
	v_cmp_le_i32_e32 vcc, v0, v217
	v_or_b32_e32 v0, 34, v214
	s_nop 0
	v_cndmask_b32_e32 v20, v207, v20, vcc
	v_cmp_le_i32_e32 vcc, v0, v217
	v_or_b32_e32 v0, 3, v214
	s_nop 0
	v_cndmask_b32_e32 v4, v207, v4, vcc
	v_cmp_le_i32_e32 vcc, v0, v217
	v_or_b32_e32 v0, 35, v214
	s_nop 0
	v_cndmask_b32_e32 v21, v207, v21, vcc
	v_cmp_le_i32_e32 vcc, v0, v217
	v_or_b32_e32 v0, 8, v214
	s_nop 0
	v_cndmask_b32_e32 v5, v207, v5, vcc
	v_cmp_le_i32_e32 vcc, v0, v217
	v_or_b32_e32 v0, 40, v214
	s_nop 0
	v_cndmask_b32_e32 v22, v207, v22, vcc
	v_cmp_le_i32_e32 vcc, v0, v217
	v_or_b32_e32 v0, 9, v214
	s_nop 0
	v_cndmask_b32_e32 v6, v207, v6, vcc
	v_cmp_le_i32_e32 vcc, v0, v217
	v_or_b32_e32 v0, 41, v214
	s_nop 0
	v_cndmask_b32_e32 v23, v207, v23, vcc
	v_cmp_le_i32_e32 vcc, v0, v217
	v_or_b32_e32 v0, 10, v214
	s_nop 0
	v_cndmask_b32_e32 v7, v207, v7, vcc
	v_cmp_le_i32_e32 vcc, v0, v217
	v_or_b32_e32 v0, 42, v214
	s_nop 0
	v_cndmask_b32_e32 v24, v207, v24, vcc
	v_cmp_le_i32_e32 vcc, v0, v217
	v_or_b32_e32 v0, 11, v214
	s_nop 0
	v_cndmask_b32_e32 v8, v207, v8, vcc
	v_cmp_le_i32_e32 vcc, v0, v217
	v_or_b32_e32 v0, 43, v214
	s_nop 0
	v_cndmask_b32_e32 v25, v207, v25, vcc
	v_cmp_le_i32_e32 vcc, v0, v217
	v_or_b32_e32 v0, 16, v214
	s_nop 0
	v_cndmask_b32_e32 v9, v207, v9, vcc
	v_cmp_le_i32_e32 vcc, v0, v217
	v_or_b32_e32 v0, 48, v214
	s_nop 0
	v_cndmask_b32_e32 v26, v207, v26, vcc
	v_cmp_le_i32_e32 vcc, v0, v217
	v_or_b32_e32 v0, 17, v214
	s_nop 0
	v_cndmask_b32_e32 v10, v207, v10, vcc
	v_cmp_le_i32_e32 vcc, v0, v217
	v_or_b32_e32 v0, 49, v214
	s_nop 0
	v_cndmask_b32_e32 v27, v207, v27, vcc
	v_cmp_le_i32_e32 vcc, v0, v217
	v_or_b32_e32 v0, 18, v214
	s_nop 0
	v_cndmask_b32_e32 v11, v207, v11, vcc
	v_cmp_le_i32_e32 vcc, v0, v217
	v_or_b32_e32 v0, 50, v214
	s_nop 0
	v_cndmask_b32_e32 v28, v207, v28, vcc
	v_cmp_le_i32_e32 vcc, v0, v217
	v_or_b32_e32 v0, 19, v214
	s_nop 0
	v_cndmask_b32_e32 v12, v207, v12, vcc
	v_cmp_le_i32_e32 vcc, v0, v217
	v_or_b32_e32 v0, 51, v214
	s_nop 0
	v_cndmask_b32_e32 v29, v207, v29, vcc
	v_cmp_le_i32_e32 vcc, v0, v217
	v_or_b32_e32 v0, 24, v214
	s_nop 0
	v_cndmask_b32_e32 v13, v207, v13, vcc
	v_cmp_le_i32_e32 vcc, v0, v217
	v_or_b32_e32 v0, 56, v214
	s_nop 0
	v_cndmask_b32_e32 v30, v207, v30, vcc
	v_cmp_le_i32_e32 vcc, v0, v217
	v_or_b32_e32 v0, 25, v214
	s_nop 0
	v_cndmask_b32_e32 v14, v207, v14, vcc
	v_cmp_le_i32_e32 vcc, v0, v217
	v_or_b32_e32 v0, 57, v214
	s_nop 0
	v_cndmask_b32_e32 v31, v207, v31, vcc
	v_cmp_le_i32_e32 vcc, v0, v217
	v_or_b32_e32 v0, 26, v214
	s_nop 0
	v_cndmask_b32_e32 v15, v207, v15, vcc
	v_cmp_le_i32_e32 vcc, v0, v217
	v_or_b32_e32 v0, 58, v214
	s_nop 0
	v_cndmask_b32_e32 v32, v207, v32, vcc
	v_cmp_le_i32_e32 vcc, v0, v217
	v_or_b32_e32 v0, 27, v214
	s_nop 0
	v_cndmask_b32_e32 v16, v207, v16, vcc
	v_cmp_le_i32_e32 vcc, v0, v217
	v_or_b32_e32 v0, 59, v214
	s_nop 0
	v_cndmask_b32_e32 v33, v207, v33, vcc
	v_cmp_le_i32_e32 vcc, v0, v217
	s_nop 1
	v_cndmask_b32_e32 v17, v207, v17, vcc
.LBB0_235:
	v_lshlrev_b32_e32 v0, 1, v36
	v_and_b32_e32 v215, 32, v0
	v_lshlrev_b32_e32 v0, 4, v36
	v_and_b32_e32 v0, 0xc0, v0
	v_lshl_or_b32 v213, v211, 8, v0
	v_add_u32_e32 v0, 0, v215
	v_add3_u32 v220, v0, v212, v213
	v_max3_f32 v0, v18, v19, v2
	v_max3_f32 v36, v20, v21, v3
	s_and_b32 s5, s5, 0x3fffffc0
	v_max3_f32 v0, v0, v4, v5
	v_max3_f32 v36, v36, v24, v25
	s_add_i32 s6, s44, 0x100
	v_max3_f32 v0, v0, v22, v23
	v_max3_f32 v36, v36, v8, v9
	s_lshl_b32 s5, s5, 2
	v_max3_f32 v0, v0, v6, v7
	v_max3_f32 v36, v36, v28, v29
	s_add_i32 s60, s5, 0
	v_max3_f32 v0, v0, v26, v27
	v_max3_f32 v36, v36, v12, v13
	s_lshr_b32 s63, s6, 6
	v_max3_f32 v0, v0, v10, v11
	v_max3_f32 v36, v36, v32, v33
	s_cmp_lg_u32 0, -1
	v_max3_f32 v0, v0, v30, v31
	v_max3_f32 v36, v36, v16, v17
	v_lshl_add_u64 v[198:199], v[34:35], 0, s[22:23]
	v_max3_f32 v0, v0, v14, v15
	s_mov_b32 s8, 1
	v_max_f32_e32 v0, v0, v36
	s_mov_b32 s45, 0
	v_mov_b32_e32 v36, v0
	s_nop 1
	v_permlane32_swap_b32_e32 v0, v36
	v_max_f32_e32 v0, v0, v36
	v_lshlrev_b32_e32 v221, 4, v211
	v_add_f32_e32 v218, v1, v0
	v_sub_f32_e32 v2, v2, v0
	v_sub_f32_e32 v3, v3, v0
	v_sub_f32_e32 v18, v18, v0
	v_sub_f32_e32 v19, v19, v0
	v_sub_f32_e32 v20, v20, v0
	s_nop 0
	v_xor_b32_e32 v48, 0x80000000, v218
	v_mov_b32_e32 v49, v48
	v_mov_b32_e32 v50, v48
	v_mov_b32_e32 v51, v48
	v_mov_b32_e32 v52, v48
	v_mov_b32_e32 v53, v48
	v_mov_b32_e32 v54, v48
	v_mov_b32_e32 v55, v48
	v_mov_b32_e32 v56, v48
	v_mov_b32_e32 v57, v48
	v_mov_b32_e32 v58, v48
	v_mov_b32_e32 v59, v48
	v_mov_b32_e32 v60, v48
	v_mov_b32_e32 v61, v48
	v_mov_b32_e32 v62, v48
	v_mov_b32_e32 v63, v48
	s_waitcnt vmcnt(0) lgkmcnt(0)
	s_barrier
	v_exp_f32_e32 v64, v2
	v_exp_f32_e32 v65, v3
	v_lshl_add_u64 v[2:3], v[196:197], 0, s[20:21]
	s_mov_b32 s5, m0
	s_mov_b32 m0, s61
	s_nop 0
	global_load_lds_dwordx4 v[2:3], off
	s_mov_b32 m0, s5
	s_cselect_b32 s5, 0, 0
	s_add_i32 s4, s5, s4
	s_add_i32 s4, s4, 0x8000
	s_add_i32 s100, s4, 0xf000
	s_mov_b32 s5, m0
	s_mov_b32 m0, s4
	s_nop 0
	global_load_lds_dwordx4 v[198:199], off
	s_mov_b32 m0, s100
	v_lshl_add_u64 v[2:3], v[198:199], 0, 64
	v_lshl_add_u64 v[2:3], v[2:3], 0, 64
	global_load_lds_dwordx4 v[2:3], off
	s_mov_b32 m0, s5
	ds_read_b128 v[188:191], v219 offset:8192
	ds_read_b128 v[184:187], v219 offset:8704
	ds_read_b128 v[180:183], v219 offset:10240
	ds_read_b128 v[176:179], v219 offset:10752
	ds_read_b128 v[172:175], v219 offset:12288
	ds_read_b128 v[168:171], v219 offset:12800
	ds_read_b128 v[164:167], v219 offset:14336
	ds_read_b128 v[160:163], v219 offset:14848
	v_sub_f32_e32 v4, v4, v0
	v_sub_f32_e32 v21, v21, v0
	v_sub_f32_e32 v5, v5, v0
	v_sub_f32_e32 v22, v22, v0
	v_sub_f32_e32 v6, v6, v0
	v_sub_f32_e32 v23, v23, v0
	v_sub_f32_e32 v7, v7, v0
	v_sub_f32_e32 v24, v24, v0
	v_sub_f32_e32 v8, v8, v0
	v_sub_f32_e32 v25, v25, v0
	v_sub_f32_e32 v9, v9, v0
	v_sub_f32_e32 v26, v26, v0
	v_sub_f32_e32 v10, v10, v0
	v_sub_f32_e32 v27, v27, v0
	v_sub_f32_e32 v11, v11, v0
	v_sub_f32_e32 v28, v28, v0
	v_sub_f32_e32 v12, v12, v0
	v_sub_f32_e32 v29, v29, v0
	v_sub_f32_e32 v13, v13, v0
	v_sub_f32_e32 v30, v30, v0
	v_sub_f32_e32 v14, v14, v0
	v_sub_f32_e32 v31, v31, v0
	v_sub_f32_e32 v15, v15, v0
	v_sub_f32_e32 v32, v32, v0
	v_sub_f32_e32 v16, v16, v0
	v_sub_f32_e32 v33, v33, v0
	v_sub_f32_e32 v0, v17, v0
	v_exp_f32_e32 v80, v18
	v_exp_f32_e32 v81, v19
	v_exp_f32_e32 v82, v20
	v_exp_f32_e32 v83, v21
	v_exp_f32_e32 v84, v22
	v_exp_f32_e32 v85, v23
	v_exp_f32_e32 v86, v24
	v_exp_f32_e32 v87, v25
	v_exp_f32_e32 v88, v26
	v_exp_f32_e32 v89, v27
	v_exp_f32_e32 v90, v28
	v_exp_f32_e32 v91, v29
	v_exp_f32_e32 v92, v30
	v_exp_f32_e32 v93, v31
	v_exp_f32_e32 v94, v32
	v_exp_f32_e32 v95, v33
	v_exp_f32_e32 v66, v4
	v_exp_f32_e32 v67, v5
	v_exp_f32_e32 v68, v6
	v_exp_f32_e32 v69, v7
	v_exp_f32_e32 v70, v8
	v_exp_f32_e32 v71, v9
	v_exp_f32_e32 v72, v10
	v_exp_f32_e32 v73, v11
	v_exp_f32_e32 v74, v12
	v_exp_f32_e32 v75, v13
	v_exp_f32_e32 v76, v14
	v_exp_f32_e32 v77, v15
	v_exp_f32_e32 v78, v16
	v_exp_f32_e32 v79, v0
	s_waitcnt vmcnt(2) lgkmcnt(0)
	s_barrier
	s_andn2_b64 vcc, exec, s[2:3]
	v_cmp_gt_u32_e64 s[4:5], 32, v208
	v_lshl_add_u32 v216, v210, 2, s60
	s_cbranch_vccnz .LBB0_251
	v_mov_b32_e32 v14, v1
	v_mov_b32_e32 v15, v1
	v_lshl_add_u64 v[200:201], v[34:35], 0, s[20:21]
	v_mov_b32_e32 v0, v1
	v_mov_b32_e32 v2, v1
	v_mov_b32_e32 v3, v1
	v_mov_b32_e32 v4, v1
	v_mov_b32_e32 v5, v1
	v_mov_b32_e32 v6, v1
	v_mov_b32_e32 v7, v1
	v_mov_b32_e32 v8, v1
	v_mov_b32_e32 v9, v1
	v_mov_b32_e32 v10, v1
	v_mov_b32_e32 v11, v1
	v_mov_b32_e32 v12, v1
	v_mov_b32_e32 v13, v1
	v_mov_b64_e32 v[46:47], v[14:15]
	v_mov_b64_e32 v[30:31], v[14:15]
	s_add_i32 s46, s63, -5
	v_lshl_add_u64 v[202:203], v[196:197], 0, s[24:25]
	s_mov_b32 s2, 0
	s_movk_i32 s45, 0x4000
	s_movk_i32 s47, 0x2000
	v_mov_b32_e32 v222, 0
	v_mov_b64_e32 v[44:45], v[12:13]
	v_mov_b64_e32 v[42:43], v[10:11]
	v_mov_b64_e32 v[40:41], v[8:9]
	v_mov_b64_e32 v[38:39], v[6:7]
	v_mov_b64_e32 v[36:37], v[4:5]
	v_mov_b64_e32 v[34:35], v[2:3]
	v_mov_b64_e32 v[32:33], v[0:1]
	v_mov_b64_e32 v[28:29], v[12:13]
	v_mov_b64_e32 v[26:27], v[10:11]
	v_mov_b64_e32 v[24:25], v[8:9]
	v_mov_b64_e32 v[22:23], v[6:7]
	v_mov_b64_e32 v[20:21], v[4:5]
	v_mov_b64_e32 v[18:19], v[2:3]
	v_mov_b64_e32 v[16:17], v[0:1]
.LBB0_237:
	v_add_u32_e32 v0, s2, v220
	s_mov_b32 s98, s2
	ds_read_b64_tr_b16 v[192:193], v0 offset:24576
	ds_read_b64_tr_b16 v[194:195], v0 offset:25088
	s_waitcnt lgkmcnt(9)
	v_mfma_f32_32x32x16_bf16 v[112:127], v[188:191], v[144:147], v[48:63]
	v_add_f32_e32 v2, v80, v81
	v_add_f32_e32 v2, v82, v2
	v_add_f32_e32 v2, v83, v2
	v_add_f32_e32 v2, v84, v2
	v_add_f32_e32 v2, v85, v2
	v_cvt_pk_bf16_f32 v156, v80, v81
	v_cvt_pk_bf16_f32 v157, v82, v83
	ds_read_b64_tr_b16 v[188:189], v0 offset:28672
	ds_read_b64_tr_b16 v[190:191], v0 offset:29184
	s_waitcnt lgkmcnt(10)
	v_mfma_f32_32x32x16_bf16 v[96:111], v[184:187], v[144:147], v[48:63]
	v_add_f32_e32 v2, v86, v2
	v_add_f32_e32 v2, v87, v2
	v_add_f32_e32 v2, v88, v2
	v_add_f32_e32 v2, v89, v2
	v_cvt_pk_bf16_f32 v158, v84, v85
	v_cvt_pk_bf16_f32 v159, v86, v87
	ds_read_b64_tr_b16 v[184:185], v0 offset:25600
	ds_read_b64_tr_b16 v[186:187], v0 offset:26112
	s_waitcnt lgkmcnt(11)
	v_mfma_f32_32x32x16_bf16 v[112:127], v[180:183], v[136:139], v[112:127]
	v_add_f32_e32 v2, v90, v2
	v_add_f32_e32 v2, v91, v2
	v_add_f32_e32 v2, v92, v2
	v_add_f32_e32 v2, v93, v2
	v_cvt_pk_bf16_f32 v152, v88, v89
	v_cvt_pk_bf16_f32 v153, v90, v91
	ds_read_b64_tr_b16 v[84:85], v0 offset:29696
	ds_read_b64_tr_b16 v[86:87], v0 offset:30208
	s_waitcnt lgkmcnt(12)
	v_mfma_f32_32x32x16_bf16 v[96:111], v[176:179], v[136:139], v[96:111]
	v_add_f32_e32 v2, v94, v2
	v_add_f32_e32 v2, v95, v2
	v_add_f32_e32 v2, v64, v2
	v_add_f32_e32 v2, v65, v2
	v_cvt_pk_bf16_f32 v154, v92, v93
	v_cvt_pk_bf16_f32 v155, v94, v95
	ds_read_b64_tr_b16 v[80:81], v0 offset:26624
	ds_read_b64_tr_b16 v[82:83], v0 offset:27136
	s_waitcnt lgkmcnt(13)
	v_mfma_f32_32x32x16_bf16 v[112:127], v[172:175], v[132:135], v[112:127]
	v_add_f32_e32 v2, v66, v2
	v_add_f32_e32 v2, v67, v2
	v_add_f32_e32 v2, v68, v2
	v_add_f32_e32 v2, v69, v2
	v_cvt_pk_bf16_f32 v148, v64, v65
	v_cvt_pk_bf16_f32 v149, v66, v67
	ds_read_b64_tr_b16 v[10:11], v0 offset:30720
	ds_read_b64_tr_b16 v[12:13], v0 offset:31232
	s_waitcnt lgkmcnt(14)
	v_mfma_f32_32x32x16_bf16 v[96:111], v[168:171], v[132:135], v[96:111]
	v_add_f32_e32 v2, v70, v2
	v_add_f32_e32 v2, v71, v2
	v_add_f32_e32 v2, v72, v2
	v_add_f32_e32 v2, v73, v2
	v_cvt_pk_bf16_f32 v150, v68, v69
	v_cvt_pk_bf16_f32 v151, v70, v71
	ds_read_b64_tr_b16 v[6:7], v0 offset:27648
	ds_read_b64_tr_b16 v[8:9], v0 offset:28160
	s_waitcnt lgkmcnt(14)
	v_mfma_f32_32x32x16_bf16 v[112:127], v[164:167], v[128:131], v[112:127]
	v_add_f32_e32 v2, v74, v2
	v_add_f32_e32 v2, v75, v2
	v_add_f32_e32 v2, v76, v2
	v_add_f32_e32 v14, v77, v2
	v_cvt_pk_bf16_f32 v140, v72, v73
	v_cvt_pk_bf16_f32 v141, v74, v75
	ds_read_b64_tr_b16 v[2:3], v0 offset:31744
	ds_read_b64_tr_b16 v[4:5], v0 offset:32256
	v_mfma_f32_32x32x16_bf16 v[96:111], v[160:163], v[128:131], v[96:111]
	v_add_f32_e32 v0, v78, v14
	v_add_f32_e32 v0, v79, v0
	v_add_f32_e32 v0, 0, v0
	v_cvt_pk_bf16_f32 v142, v76, v77
	v_cvt_pk_bf16_f32 v143, v78, v79
	v_lshl_add_u64 v[14:15], v[202:203], 0, s[26:27]
	s_add_i32 s2, s47, s61
	s_mov_b32 s3, m0
	s_mov_b32 m0, s2
	s_nop 0
	global_load_lds_dwordx4 v[14:15], off
	s_mov_b32 m0, s3
	v_lshl_add_u64 v[14:15], v[200:201], 0, s[26:27]
	s_add_i32 s2, s45, s62
	s_add_i32 s100, s45, s99
	s_mov_b32 s3, m0
	s_mov_b32 m0, s2
	s_nop 0
	global_load_lds_dwordx4 v[14:15], off
	s_mov_b32 m0, s100
	v_lshl_add_u64 v[64:65], v[14:15], 0, 64
	v_lshl_add_u64 v[64:65], v[64:65], 0, 64
	global_load_lds_dwordx4 v[64:65], off
	s_mov_b32 m0, s3
	v_max_f32_e32 v14, v113, v113
	v_max_f32_e32 v15, v112, v112
	v_max_f32_e32 v14, v15, v14
	v_max3_f32 v15, v114, v115, v97
	v_max3_f32 v14, v14, v96, v98
	v_max3_f32 v14, v14, v99, v116
	v_max3_f32 v15, v15, v118, v119
	v_max3_f32 v14, v14, v117, v100
	v_max3_f32 v15, v15, v102, v103
	v_max3_f32 v14, v14, v101, v120
	v_max3_f32 v15, v15, v122, v123
	v_max3_f32 v14, v14, v121, v104
	v_max3_f32 v15, v15, v106, v107
	v_max3_f32 v14, v14, v105, v124
	v_max3_f32 v15, v15, v126, v127
	v_max3_f32 v64, v14, v125, v108
	v_max3_f32 v15, v15, v110, v111
	v_add_f32_e32 v14, v222, v0
	v_max3_f32 v0, v64, v109, v15
	v_mov_b32_e32 v15, v0
	s_nop 1
	v_permlane32_swap_b32_e32 v0, v15
	v_max_f32_e32 v15, v15, v15
	v_max_f32_e32 v0, v0, v0
	v_max_f32_e32 v0, v0, v15
	v_cmp_lt_f32_e32 vcc, s52, v0
	s_cmp_lg_u64 vcc, 0
	s_cselect_b64 s[2:3], -1, 0
	s_cbranch_vccnz .LBB0_245
.LBB0_238:
	s_waitcnt lgkmcnt(14)
	v_mfma_f32_32x32x16_bf16 v[32:47], v[156:159], v[192:195], v[32:47]
	v_exp_f32_e32 v112, v112
	v_exp_f32_e32 v113, v113
	v_exp_f32_e32 v114, v114
	v_exp_f32_e32 v115, v115
	s_waitcnt lgkmcnt(12)
	v_mfma_f32_32x32x16_bf16 v[16:31], v[156:159], v[188:191], v[16:31]
	v_exp_f32_e32 v116, v116
	v_exp_f32_e32 v117, v117
	v_exp_f32_e32 v118, v118
	v_exp_f32_e32 v119, v119
	v_add_u32_e32 v0, s45, v219
	ds_read_b128 v[64:67], v0
	ds_read_b128 v[160:163], v0 offset:512
	s_waitcnt lgkmcnt(12)
	v_mfma_f32_32x32x16_bf16 v[32:47], v[152:155], v[184:187], v[32:47]
	v_exp_f32_e32 v120, v120
	v_exp_f32_e32 v121, v121
	v_exp_f32_e32 v122, v122
	v_exp_f32_e32 v123, v123
	ds_read_b128 v[192:195], v0 offset:2048
	ds_read_b128 v[184:187], v0 offset:2560
	s_waitcnt lgkmcnt(12)
	v_mfma_f32_32x32x16_bf16 v[16:31], v[152:155], v[84:87], v[16:31]
	v_exp_f32_e32 v124, v124
	v_exp_f32_e32 v125, v125
	v_exp_f32_e32 v126, v126
	v_exp_f32_e32 v127, v127
	ds_read_b128 v[188:191], v0 offset:4096
	ds_read_b128 v[176:179], v0 offset:4608
	s_waitcnt lgkmcnt(12)
	v_mfma_f32_32x32x16_bf16 v[32:47], v[148:151], v[80:83], v[32:47]
	v_exp_f32_e32 v96, v96
	v_exp_f32_e32 v97, v97
	v_exp_f32_e32 v98, v98
	v_exp_f32_e32 v99, v99
	ds_read_b128 v[180:183], v0 offset:6144
	ds_read_b128 v[172:175], v0 offset:6656
	s_waitcnt lgkmcnt(12)
	v_mfma_f32_32x32x16_bf16 v[16:31], v[148:151], v[10:13], v[16:31]
	v_exp_f32_e32 v100, v100
	v_exp_f32_e32 v101, v101
	v_exp_f32_e32 v102, v102
	v_exp_f32_e32 v103, v103
	s_waitcnt lgkmcnt(10)
	v_mfma_f32_32x32x16_bf16 v[32:47], v[140:143], v[6:9], v[32:47]
	v_exp_f32_e32 v104, v104
	v_exp_f32_e32 v105, v105
	v_exp_f32_e32 v106, v106
	v_exp_f32_e32 v107, v107
	s_waitcnt lgkmcnt(8)
	v_mfma_f32_32x32x16_bf16 v[16:31], v[140:143], v[2:5], v[16:31]
	v_add_u32_e32 v0, s98, v220
	v_add_u32_e32 v0, 0xf000, v0
	ds_read_b64_tr_b16 v[2:3], v0 offset:24576
	ds_read_b64_tr_b16 v[4:5], v0 offset:25088
	ds_read_b64_tr_b16 v[6:7], v0 offset:28672
	ds_read_b64_tr_b16 v[8:9], v0 offset:29184
	ds_read_b64_tr_b16 v[10:11], v0 offset:25600
	ds_read_b64_tr_b16 v[12:13], v0 offset:26112
	ds_read_b64_tr_b16 v[68:69], v0 offset:29696
	ds_read_b64_tr_b16 v[70:71], v0 offset:30208
	ds_read_b64_tr_b16 v[72:73], v0 offset:26624
	ds_read_b64_tr_b16 v[74:75], v0 offset:27136
	ds_read_b64_tr_b16 v[76:77], v0 offset:30720
	ds_read_b64_tr_b16 v[78:79], v0 offset:31232
	ds_read_b64_tr_b16 v[80:81], v0 offset:27648
	ds_read_b64_tr_b16 v[82:83], v0 offset:28160
	ds_read_b64_tr_b16 v[84:85], v0 offset:31744
	ds_read_b64_tr_b16 v[86:87], v0 offset:32256
	s_waitcnt lgkmcnt(14)
	v_mfma_f32_32x32x16_bf16 v[224:239], v[156:159], v[2:5], v[224:239]
	s_waitcnt lgkmcnt(12)
	v_mfma_f32_32x32x16_bf16 v[240:255], v[156:159], v[6:9], v[240:255]
	s_waitcnt lgkmcnt(10)
	v_mfma_f32_32x32x16_bf16 v[224:239], v[152:155], v[10:13], v[224:239]
	s_waitcnt lgkmcnt(8)
	v_mfma_f32_32x32x16_bf16 v[240:255], v[152:155], v[68:71], v[240:255]
	s_waitcnt lgkmcnt(6)
	v_mfma_f32_32x32x16_bf16 v[224:239], v[148:151], v[72:75], v[224:239]
	s_waitcnt lgkmcnt(4)
	v_mfma_f32_32x32x16_bf16 v[240:255], v[148:151], v[76:79], v[240:255]
	s_waitcnt lgkmcnt(2)
	v_mfma_f32_32x32x16_bf16 v[224:239], v[140:143], v[80:83], v[224:239]
	s_waitcnt lgkmcnt(0)
	v_mfma_f32_32x32x16_bf16 v[240:255], v[140:143], v[84:87], v[240:255]
	v_exp_f32_e32 v108, v108
	v_exp_f32_e32 v109, v109
	v_exp_f32_e32 v110, v110
	v_exp_f32_e32 v111, v111
	s_waitcnt vmcnt(2) lgkmcnt(0)
	s_barrier
	s_andn2_b64 vcc, exec, s[2:3]
	v_add_u32_e32 v0, s60, v221
	s_cbranch_vccnz .LBB0_240
	s_waitcnt lgkmcnt(0)
	ds_read_b128 v[2:5], v0 offset:49248
	ds_read_b128 v[6:9], v0 offset:49216
	ds_read_b128 v[10:13], v0 offset:49184
	ds_read_b128 v[68:71], v0 offset:49152
	s_waitcnt lgkmcnt(3)
	v_pk_mul_f32 v[44:45], v[44:45], v[2:3]
	v_pk_mul_f32 v[236:237], v[236:237], v[2:3]
	s_waitcnt lgkmcnt(2)
	v_pk_mul_f32 v[40:41], v[40:41], v[6:7]
	v_pk_mul_f32 v[232:233], v[232:233], v[6:7]
	s_waitcnt lgkmcnt(1)
	v_pk_mul_f32 v[36:37], v[36:37], v[10:11]
	v_pk_mul_f32 v[228:229], v[228:229], v[10:11]
	v_pk_mul_f32 v[46:47], v[46:47], v[4:5]
	v_pk_mul_f32 v[238:239], v[238:239], v[4:5]
	v_pk_mul_f32 v[42:43], v[42:43], v[8:9]
	v_pk_mul_f32 v[234:235], v[234:235], v[8:9]
	v_pk_mul_f32 v[38:39], v[38:39], v[12:13]
	v_pk_mul_f32 v[230:231], v[230:231], v[12:13]
	s_waitcnt lgkmcnt(0)
	v_pk_mul_f32 v[34:35], v[34:35], v[70:71]
	v_pk_mul_f32 v[226:227], v[226:227], v[70:71]
	v_pk_mul_f32 v[32:33], v[32:33], v[68:69]
	v_pk_mul_f32 v[224:225], v[224:225], v[68:69]
	v_pk_mul_f32 v[28:29], v[28:29], v[2:3]
	v_pk_mul_f32 v[252:253], v[252:253], v[2:3]
	v_pk_mul_f32 v[24:25], v[24:25], v[6:7]
	v_pk_mul_f32 v[248:249], v[248:249], v[6:7]
	v_pk_mul_f32 v[20:21], v[20:21], v[10:11]
	v_pk_mul_f32 v[244:245], v[244:245], v[10:11]
	v_pk_mul_f32 v[30:31], v[30:31], v[4:5]
	v_pk_mul_f32 v[254:255], v[254:255], v[4:5]
	v_pk_mul_f32 v[26:27], v[26:27], v[8:9]
	v_pk_mul_f32 v[250:251], v[250:251], v[8:9]
	v_pk_mul_f32 v[22:23], v[22:23], v[12:13]
	v_pk_mul_f32 v[246:247], v[246:247], v[12:13]
	v_pk_mul_f32 v[18:19], v[18:19], v[70:71]
	v_pk_mul_f32 v[242:243], v[242:243], v[70:71]
	v_pk_mul_f32 v[16:17], v[16:17], v[68:69]
	v_pk_mul_f32 v[240:241], v[240:241], v[68:69]
.LBB0_240:
	s_add_i32 s2, s45, 0x2000
	s_cmpk_lg_i32 s45, 0x4000
	s_cselect_b32 s64, s2, 0
	v_add_u32_e32 v4, s47, v220
	s_mov_b32 s98, s47
	ds_read_b64_tr_b16 v[168:169], v4 offset:24576
	ds_read_b64_tr_b16 v[170:171], v4 offset:25088
	s_waitcnt lgkmcnt(9)
	v_mfma_f32_32x32x16_bf16 v[80:95], v[64:67], v[144:147], v[48:63]
	v_add_f32_e32 v2, v112, v113
	v_add_f32_e32 v2, v114, v2
	v_add_f32_e32 v2, v115, v2
	v_add_f32_e32 v2, v116, v2
	v_add_f32_e32 v2, v117, v2
	v_cvt_pk_bf16_f32 v156, v112, v113
	v_cvt_pk_bf16_f32 v157, v114, v115
	ds_read_b64_tr_b16 v[164:165], v4 offset:28672
	ds_read_b64_tr_b16 v[166:167], v4 offset:29184
	s_waitcnt lgkmcnt(10)
	v_mfma_f32_32x32x16_bf16 v[64:79], v[160:163], v[144:147], v[48:63]
	v_add_f32_e32 v2, v118, v2
	v_add_f32_e32 v2, v119, v2
	v_add_f32_e32 v2, v120, v2
	v_add_f32_e32 v2, v121, v2
	v_cvt_pk_bf16_f32 v158, v116, v117
	v_cvt_pk_bf16_f32 v159, v118, v119
	ds_read_b64_tr_b16 v[160:161], v4 offset:25600
	ds_read_b64_tr_b16 v[162:163], v4 offset:26112
	s_waitcnt lgkmcnt(11)
	v_mfma_f32_32x32x16_bf16 v[80:95], v[192:195], v[136:139], v[80:95]
	v_add_f32_e32 v2, v122, v2
	v_add_f32_e32 v2, v123, v2
	v_add_f32_e32 v2, v124, v2
	v_add_f32_e32 v2, v125, v2
	v_cvt_pk_bf16_f32 v152, v120, v121
	v_cvt_pk_bf16_f32 v153, v122, v123
	ds_read_b64_tr_b16 v[116:117], v4 offset:29696
	ds_read_b64_tr_b16 v[118:119], v4 offset:30208
	s_waitcnt lgkmcnt(12)
	v_mfma_f32_32x32x16_bf16 v[64:79], v[184:187], v[136:139], v[64:79]
	v_add_f32_e32 v2, v126, v2
	v_add_f32_e32 v2, v127, v2
	v_add_f32_e32 v2, v96, v2
	v_add_f32_e32 v2, v97, v2
	v_cvt_pk_bf16_f32 v154, v124, v125
	v_cvt_pk_bf16_f32 v155, v126, v127
	ds_read_b64_tr_b16 v[112:113], v4 offset:26624
	ds_read_b64_tr_b16 v[114:115], v4 offset:27136
	s_waitcnt lgkmcnt(13)
	v_mfma_f32_32x32x16_bf16 v[80:95], v[188:191], v[132:135], v[80:95]
	v_add_f32_e32 v2, v98, v2
	v_add_f32_e32 v2, v99, v2
	v_add_f32_e32 v2, v100, v2
	v_add_f32_e32 v2, v101, v2
	v_cvt_pk_bf16_f32 v148, v96, v97
	v_cvt_pk_bf16_f32 v149, v98, v99
	ds_read_b64_tr_b16 v[10:11], v4 offset:30720
	ds_read_b64_tr_b16 v[12:13], v4 offset:31232
	s_waitcnt lgkmcnt(14)
	v_mfma_f32_32x32x16_bf16 v[64:79], v[176:179], v[132:135], v[64:79]
	v_add_f32_e32 v2, v102, v2
	v_add_f32_e32 v2, v103, v2
	v_add_f32_e32 v2, v104, v2
	v_add_f32_e32 v2, v105, v2
	v_cvt_pk_bf16_f32 v150, v100, v101
	v_cvt_pk_bf16_f32 v151, v102, v103
	ds_read_b64_tr_b16 v[6:7], v4 offset:27648
	ds_read_b64_tr_b16 v[8:9], v4 offset:28160
	s_waitcnt lgkmcnt(14)
	v_mfma_f32_32x32x16_bf16 v[80:95], v[180:183], v[128:131], v[80:95]
	v_add_f32_e32 v2, v106, v2
	v_add_f32_e32 v2, v107, v2
	v_add_f32_e32 v2, v108, v2
	v_add_f32_e32 v15, v109, v2
	v_cvt_pk_bf16_f32 v140, v104, v105
	v_cvt_pk_bf16_f32 v141, v106, v107
	ds_read_b64_tr_b16 v[2:3], v4 offset:31744
	ds_read_b64_tr_b16 v[4:5], v4 offset:32256
	v_mfma_f32_32x32x16_bf16 v[64:79], v[172:175], v[128:131], v[64:79]
	v_add_f32_e32 v15, v110, v15
	v_add_f32_e32 v15, v111, v15
	v_add_f32_e32 v15, 0, v15
	v_cvt_pk_bf16_f32 v142, v108, v109
	v_cvt_pk_bf16_f32 v143, v110, v111
	v_max_f32_e32 v96, v81, v81
	v_max_f32_e32 v97, v80, v80
	v_max_f32_e32 v96, v97, v96
	s_nop 3
	v_max3_f32 v97, v82, v83, v65
	v_max3_f32 v96, v96, v64, v66
	v_max3_f32 v96, v96, v67, v84
	v_max3_f32 v97, v97, v86, v87
	v_max3_f32 v96, v96, v85, v68
	v_max3_f32 v97, v97, v70, v71
	v_max3_f32 v96, v96, v69, v88
	v_max3_f32 v97, v97, v90, v91
	v_max3_f32 v96, v96, v89, v72
	v_max3_f32 v97, v97, v74, v75
	v_max3_f32 v96, v96, v73, v92
	v_max3_f32 v97, v97, v94, v95
	v_max3_f32 v96, v96, v93, v76
	v_max3_f32 v97, v97, v78, v79
	v_add_f32_e32 v222, v14, v15
	v_max3_f32 v14, v96, v77, v97
	v_mov_b32_e32 v15, v14
	s_nop 1
	v_permlane32_swap_b32_e32 v14, v15
	v_max_f32_e32 v15, v15, v15
	v_max_f32_e32 v14, v14, v14
	s_add_i32 s2, s45, s61
	s_mov_b32 s3, m0
	s_mov_b32 m0, s2
	s_nop 0
	global_load_lds_dwordx4 v[202:203], off
	s_mov_b32 m0, s3
	v_max_f32_e32 v14, v14, v15
	s_add_i32 s2, s64, s62
	s_add_i32 s100, s64, s99
	s_mov_b32 s3, m0
	s_mov_b32 m0, s2
	s_nop 0
	global_load_lds_dwordx4 v[200:201], off
	s_mov_b32 m0, s100
	v_lshl_add_u64 v[96:97], v[200:201], 0, 64
	v_lshl_add_u64 v[96:97], v[96:97], 0, 64
	global_load_lds_dwordx4 v[96:97], off
	s_mov_b32 m0, s3
	v_cmp_lt_f32_e32 vcc, s52, v14
	s_cmp_lg_u64 vcc, 0
	s_cselect_b64 s[2:3], -1, 0
	s_cbranch_vccnz .LBB0_248
.LBB0_241:
	s_waitcnt lgkmcnt(14)
	v_mfma_f32_32x32x16_bf16 v[32:47], v[156:159], v[168:171], v[32:47]
	v_exp_f32_e32 v80, v80
	v_exp_f32_e32 v81, v81
	v_exp_f32_e32 v82, v82
	v_exp_f32_e32 v83, v83
	s_waitcnt lgkmcnt(12)
	v_mfma_f32_32x32x16_bf16 v[16:31], v[156:159], v[164:167], v[16:31]
	v_exp_f32_e32 v84, v84
	v_exp_f32_e32 v85, v85
	v_exp_f32_e32 v86, v86
	v_exp_f32_e32 v87, v87
	v_add_u32_e32 v14, s64, v219
	ds_read_b128 v[188:191], v14
	ds_read_b128 v[184:187], v14 offset:512
	s_waitcnt lgkmcnt(12)
	v_mfma_f32_32x32x16_bf16 v[32:47], v[152:155], v[160:163], v[32:47]
	v_exp_f32_e32 v88, v88
	v_exp_f32_e32 v89, v89
	v_exp_f32_e32 v90, v90
	v_exp_f32_e32 v91, v91
	ds_read_b128 v[180:183], v14 offset:2048
	ds_read_b128 v[176:179], v14 offset:2560
	s_waitcnt lgkmcnt(12)
	v_mfma_f32_32x32x16_bf16 v[16:31], v[152:155], v[116:119], v[16:31]
	v_exp_f32_e32 v92, v92
	v_exp_f32_e32 v93, v93
	v_exp_f32_e32 v94, v94
	v_exp_f32_e32 v95, v95
	ds_read_b128 v[172:175], v14 offset:4096
	ds_read_b128 v[168:171], v14 offset:4608
	s_waitcnt lgkmcnt(12)
	v_mfma_f32_32x32x16_bf16 v[32:47], v[148:151], v[112:115], v[32:47]
	v_exp_f32_e32 v64, v64
	v_exp_f32_e32 v65, v65
	v_exp_f32_e32 v66, v66
	v_exp_f32_e32 v67, v67
	ds_read_b128 v[164:167], v14 offset:6144
	ds_read_b128 v[160:163], v14 offset:6656
	s_waitcnt lgkmcnt(12)
	v_mfma_f32_32x32x16_bf16 v[16:31], v[148:151], v[10:13], v[16:31]
	v_exp_f32_e32 v68, v68
	v_exp_f32_e32 v69, v69
	v_exp_f32_e32 v70, v70
	v_exp_f32_e32 v71, v71
	s_waitcnt lgkmcnt(10)
	v_mfma_f32_32x32x16_bf16 v[32:47], v[140:143], v[6:9], v[32:47]
	v_exp_f32_e32 v72, v72
	v_exp_f32_e32 v73, v73
	v_exp_f32_e32 v74, v74
	v_exp_f32_e32 v75, v75
	s_waitcnt lgkmcnt(8)
	v_mfma_f32_32x32x16_bf16 v[16:31], v[140:143], v[2:5], v[16:31]
	v_add_u32_e32 v14, s98, v220
	v_add_u32_e32 v14, 0xf000, v14
	ds_read_b64_tr_b16 v[2:3], v14 offset:24576
	ds_read_b64_tr_b16 v[4:5], v14 offset:25088
	ds_read_b64_tr_b16 v[6:7], v14 offset:28672
	ds_read_b64_tr_b16 v[8:9], v14 offset:29184
	ds_read_b64_tr_b16 v[10:11], v14 offset:25600
	ds_read_b64_tr_b16 v[12:13], v14 offset:26112
	ds_read_b64_tr_b16 v[96:97], v14 offset:29696
	ds_read_b64_tr_b16 v[98:99], v14 offset:30208
	ds_read_b64_tr_b16 v[100:101], v14 offset:26624
	ds_read_b64_tr_b16 v[102:103], v14 offset:27136
	ds_read_b64_tr_b16 v[104:105], v14 offset:30720
	ds_read_b64_tr_b16 v[106:107], v14 offset:31232
	ds_read_b64_tr_b16 v[108:109], v14 offset:27648
	ds_read_b64_tr_b16 v[110:111], v14 offset:28160
	ds_read_b64_tr_b16 v[112:113], v14 offset:31744
	ds_read_b64_tr_b16 v[114:115], v14 offset:32256
	s_waitcnt lgkmcnt(14)
	v_mfma_f32_32x32x16_bf16 v[224:239], v[156:159], v[2:5], v[224:239]
	s_waitcnt lgkmcnt(12)
	v_mfma_f32_32x32x16_bf16 v[240:255], v[156:159], v[6:9], v[240:255]
	s_waitcnt lgkmcnt(10)
	v_mfma_f32_32x32x16_bf16 v[224:239], v[152:155], v[10:13], v[224:239]
	s_waitcnt lgkmcnt(8)
	v_mfma_f32_32x32x16_bf16 v[240:255], v[152:155], v[96:99], v[240:255]
	s_waitcnt lgkmcnt(6)
	v_mfma_f32_32x32x16_bf16 v[224:239], v[148:151], v[100:103], v[224:239]
	s_waitcnt lgkmcnt(4)
	v_mfma_f32_32x32x16_bf16 v[240:255], v[148:151], v[104:107], v[240:255]
	s_waitcnt lgkmcnt(2)
	v_mfma_f32_32x32x16_bf16 v[224:239], v[140:143], v[108:111], v[224:239]
	s_waitcnt lgkmcnt(0)
	v_mfma_f32_32x32x16_bf16 v[240:255], v[140:143], v[112:115], v[240:255]
	v_exp_f32_e32 v76, v76
	v_exp_f32_e32 v77, v77
	v_exp_f32_e32 v78, v78
	v_exp_f32_e32 v79, v79
	s_waitcnt vmcnt(2) lgkmcnt(0)
	s_barrier
	s_andn2_b64 vcc, exec, s[2:3]
	s_cbranch_vccnz .LBB0_243
	s_waitcnt lgkmcnt(0)
	ds_read_b128 v[2:5], v0 offset:49248
	ds_read_b128 v[6:9], v0 offset:49216
	ds_read_b128 v[10:13], v0 offset:49184
	ds_read_b128 v[96:99], v0 offset:49152
	s_waitcnt lgkmcnt(3)
	v_pk_mul_f32 v[44:45], v[44:45], v[2:3]
	v_pk_mul_f32 v[236:237], v[236:237], v[2:3]
	s_waitcnt lgkmcnt(2)
	v_pk_mul_f32 v[40:41], v[40:41], v[6:7]
	v_pk_mul_f32 v[232:233], v[232:233], v[6:7]
	s_waitcnt lgkmcnt(1)
	v_pk_mul_f32 v[36:37], v[36:37], v[10:11]
	v_pk_mul_f32 v[228:229], v[228:229], v[10:11]
	v_pk_mul_f32 v[46:47], v[46:47], v[4:5]
	v_pk_mul_f32 v[238:239], v[238:239], v[4:5]
	v_pk_mul_f32 v[42:43], v[42:43], v[8:9]
	v_pk_mul_f32 v[234:235], v[234:235], v[8:9]
	v_pk_mul_f32 v[38:39], v[38:39], v[12:13]
	v_pk_mul_f32 v[230:231], v[230:231], v[12:13]
	s_waitcnt lgkmcnt(0)
	v_pk_mul_f32 v[34:35], v[34:35], v[98:99]
	v_pk_mul_f32 v[226:227], v[226:227], v[98:99]
	v_pk_mul_f32 v[32:33], v[32:33], v[96:97]
	v_pk_mul_f32 v[224:225], v[224:225], v[96:97]
	v_pk_mul_f32 v[28:29], v[28:29], v[2:3]
	v_pk_mul_f32 v[252:253], v[252:253], v[2:3]
	v_pk_mul_f32 v[24:25], v[24:25], v[6:7]
	v_pk_mul_f32 v[248:249], v[248:249], v[6:7]
	v_pk_mul_f32 v[20:21], v[20:21], v[10:11]
	v_pk_mul_f32 v[244:245], v[244:245], v[10:11]
	v_pk_mul_f32 v[30:31], v[30:31], v[4:5]
	v_pk_mul_f32 v[254:255], v[254:255], v[4:5]
	v_pk_mul_f32 v[26:27], v[26:27], v[8:9]
	v_pk_mul_f32 v[250:251], v[250:251], v[8:9]
	v_pk_mul_f32 v[22:23], v[22:23], v[12:13]
	v_pk_mul_f32 v[246:247], v[246:247], v[12:13]
	v_pk_mul_f32 v[18:19], v[18:19], v[98:99]
	v_pk_mul_f32 v[242:243], v[242:243], v[98:99]
	v_pk_mul_f32 v[16:17], v[16:17], v[96:97]
	v_pk_mul_f32 v[240:241], v[240:241], v[96:97]

.LBB0_254:
	v_add_u32_e32 v4, s45, v220
	s_mov_b32 s98, s45
	ds_read_b64_tr_b16 v[196:197], v4 offset:24576
	ds_read_b64_tr_b16 v[198:199], v4 offset:25088
	s_waitcnt lgkmcnt(9)
	v_mfma_f32_32x32x16_bf16 v[112:127], v[188:191], v[144:147], v[48:63]
	v_add_f32_e32 v2, v80, v81
	v_add_f32_e32 v2, v82, v2
	v_add_f32_e32 v2, v83, v2
	v_add_f32_e32 v2, v84, v2
	v_add_f32_e32 v2, v85, v2
	v_cvt_pk_bf16_f32 v156, v80, v81
	v_cvt_pk_bf16_f32 v157, v82, v83
	ds_read_b64_tr_b16 v[188:189], v4 offset:28672
	ds_read_b64_tr_b16 v[190:191], v4 offset:29184
	s_waitcnt lgkmcnt(10)
	v_mfma_f32_32x32x16_bf16 v[96:111], v[184:187], v[144:147], v[48:63]
	v_add_f32_e32 v2, v86, v2
	v_add_f32_e32 v2, v87, v2
	v_add_f32_e32 v2, v88, v2
	v_add_f32_e32 v2, v89, v2
	v_cvt_pk_bf16_f32 v158, v84, v85
	v_cvt_pk_bf16_f32 v159, v86, v87
	ds_read_b64_tr_b16 v[192:193], v4 offset:25600
	ds_read_b64_tr_b16 v[194:195], v4 offset:26112
	s_waitcnt lgkmcnt(11)
	v_mfma_f32_32x32x16_bf16 v[112:127], v[180:183], v[136:139], v[112:127]
	v_add_f32_e32 v2, v90, v2
	v_add_f32_e32 v2, v91, v2
	v_add_f32_e32 v2, v92, v2
	v_add_f32_e32 v2, v93, v2
	v_cvt_pk_bf16_f32 v152, v88, v89
	v_cvt_pk_bf16_f32 v153, v90, v91
	ds_read_b64_tr_b16 v[84:85], v4 offset:29696
	ds_read_b64_tr_b16 v[86:87], v4 offset:30208
	s_waitcnt lgkmcnt(12)
	v_mfma_f32_32x32x16_bf16 v[96:111], v[176:179], v[136:139], v[96:111]
	v_add_f32_e32 v2, v94, v2
	v_add_f32_e32 v2, v95, v2
	v_add_f32_e32 v2, v64, v2
	v_add_f32_e32 v2, v65, v2
	v_cvt_pk_bf16_f32 v154, v92, v93
	v_cvt_pk_bf16_f32 v155, v94, v95
	ds_read_b64_tr_b16 v[80:81], v4 offset:26624
	ds_read_b64_tr_b16 v[82:83], v4 offset:27136
	s_waitcnt lgkmcnt(13)
	v_mfma_f32_32x32x16_bf16 v[112:127], v[172:175], v[132:135], v[112:127]
	v_add_f32_e32 v2, v66, v2
	v_add_f32_e32 v2, v67, v2
	v_add_f32_e32 v2, v68, v2
	v_add_f32_e32 v2, v69, v2
	v_cvt_pk_bf16_f32 v148, v64, v65
	v_cvt_pk_bf16_f32 v149, v66, v67
	ds_read_b64_tr_b16 v[10:11], v4 offset:30720
	ds_read_b64_tr_b16 v[12:13], v4 offset:31232
	s_waitcnt lgkmcnt(14)
	v_mfma_f32_32x32x16_bf16 v[96:111], v[168:171], v[132:135], v[96:111]
	v_add_f32_e32 v2, v70, v2
	v_add_f32_e32 v2, v71, v2
	v_add_f32_e32 v2, v72, v2
	v_add_f32_e32 v2, v73, v2
	v_cvt_pk_bf16_f32 v150, v68, v69
	v_cvt_pk_bf16_f32 v151, v70, v71
	ds_read_b64_tr_b16 v[6:7], v4 offset:27648
	ds_read_b64_tr_b16 v[8:9], v4 offset:28160
	s_waitcnt lgkmcnt(14)
	v_mfma_f32_32x32x16_bf16 v[112:127], v[164:167], v[128:131], v[112:127]
	v_add_f32_e32 v2, v74, v2
	v_add_f32_e32 v2, v75, v2
	v_add_f32_e32 v2, v76, v2
	v_add_f32_e32 v64, v77, v2
	v_cvt_pk_bf16_f32 v140, v72, v73
	v_cvt_pk_bf16_f32 v141, v74, v75
	ds_read_b64_tr_b16 v[2:3], v4 offset:31744
	ds_read_b64_tr_b16 v[4:5], v4 offset:32256
	v_mfma_f32_32x32x16_bf16 v[96:111], v[160:163], v[128:131], v[96:111]
	v_add_f32_e32 v64, v78, v64
	v_add_f32_e32 v64, v79, v64
	v_add_f32_e32 v64, 0, v64
	v_cvt_pk_bf16_f32 v142, v76, v77
	v_cvt_pk_bf16_f32 v143, v78, v79
	s_add_i32 s2, s46, 1
	s_cmp_ge_u32 s2, s63
	s_cselect_b64 s[2:3], -1, 0
	s_and_b64 vcc, exec, s[2:3]
	s_cbranch_vccnz .LBB0_256
	s_add_i32 s6, s64, s61
	v_lshl_add_u64 v[66:67], v[204:205], 0, s[26:27]
	s_mov_b32 s7, m0
	s_mov_b32 m0, s6
	s_nop 0
	global_load_lds_dwordx4 v[66:67], off
	s_mov_b32 m0, s7
.LBB0_256:
	s_add_i32 s8, s67, s46
	s_add_i32 s6, s65, s62
	s_add_i32 s100, s65, s99
	s_add_i32 s7, s8, 2
	s_cmp_lt_i32 s7, 0
	s_mov_b32 s7, m0
	s_mov_b32 m0, s6
	s_nop 0
	global_load_lds_dwordx4 v[14:15], off
	s_mov_b32 m0, s100
	v_lshl_add_u64 v[66:67], v[14:15], 0, 64
	v_lshl_add_u64 v[66:67], v[66:67], 0, 64
	global_load_lds_dwordx4 v[66:67], off
	s_mov_b32 m0, s7
	s_cbranch_scc1 .LBB0_258
	v_add_u32_e32 v66, 0xffffffa5, v0
	v_add_u32_e32 v65, 0xffffff85, v0
	v_cmp_le_i32_e32 vcc, v66, v217
	s_nop 1
	v_cndmask_b32_e32 v96, v207, v96, vcc
	v_cmp_lt_i32_e32 vcc, v65, v217
	s_nop 1
	v_cndmask_b32_e32 v113, v207, v113, vcc
	v_cmp_le_i32_e32 vcc, v65, v217
	v_add_u32_e32 v65, 0xffffffa6, v0
	s_nop 0
	v_cndmask_b32_e32 v112, v207, v112, vcc
	v_cmp_le_i32_e32 vcc, v65, v217
	v_add_u32_e32 v65, 0xffffff87, v0
	s_nop 0
	v_cndmask_b32_e32 v97, v207, v97, vcc
	v_cmp_le_i32_e32 vcc, v65, v217
	v_add_u32_e32 v65, 0xffffffa7, v0
	s_nop 0
	v_cndmask_b32_e32 v114, v207, v114, vcc
	v_cmp_le_i32_e32 vcc, v65, v217
	v_add_u32_e32 v65, 0xffffff88, v0
	s_nop 0
	v_cndmask_b32_e32 v98, v207, v98, vcc
	v_cmp_le_i32_e32 vcc, v65, v217
	v_add_u32_e32 v65, 0xffffffa8, v0
	s_nop 0
	v_cndmask_b32_e32 v115, v207, v115, vcc
	v_cmp_le_i32_e32 vcc, v65, v217
	v_add_u32_e32 v65, 0xffffff8d, v0
	s_nop 0
	v_cndmask_b32_e32 v99, v207, v99, vcc
	v_cmp_le_i32_e32 vcc, v65, v217
	v_add_u32_e32 v65, 0xffffffad, v0
	s_nop 0
	v_cndmask_b32_e32 v116, v207, v116, vcc
	v_cmp_le_i32_e32 vcc, v65, v217
	v_add_u32_e32 v65, 0xffffff8e, v0
	s_nop 0
	v_cndmask_b32_e32 v100, v207, v100, vcc
	v_cmp_le_i32_e32 vcc, v65, v217
	v_add_u32_e32 v65, 0xffffffae, v0
	s_nop 0
	v_cndmask_b32_e32 v117, v207, v117, vcc
	v_cmp_le_i32_e32 vcc, v65, v217
	v_add_u32_e32 v65, 0xffffff8f, v0
	s_nop 0
	v_cndmask_b32_e32 v101, v207, v101, vcc
	v_cmp_le_i32_e32 vcc, v65, v217
	v_add_u32_e32 v65, 0xffffffaf, v0
	s_nop 0
	v_cndmask_b32_e32 v118, v207, v118, vcc
	v_cmp_le_i32_e32 vcc, v65, v217
	v_add_u32_e32 v65, 0xffffff90, v0
	s_nop 0
	v_cndmask_b32_e32 v102, v207, v102, vcc
	v_cmp_le_i32_e32 vcc, v65, v217
	v_add_u32_e32 v65, 0xffffffb0, v0
	s_nop 0
	v_cndmask_b32_e32 v119, v207, v119, vcc
	v_cmp_le_i32_e32 vcc, v65, v217
	v_add_u32_e32 v65, 0xffffff95, v0
	s_nop 0
	v_cndmask_b32_e32 v103, v207, v103, vcc
	v_cmp_le_i32_e32 vcc, v65, v217
	v_add_u32_e32 v65, 0xffffffb5, v0
	s_nop 0
	v_cndmask_b32_e32 v120, v207, v120, vcc
	v_cmp_le_i32_e32 vcc, v65, v217
	v_add_u32_e32 v65, 0xffffff96, v0
	s_nop 0
	v_cndmask_b32_e32 v104, v207, v104, vcc
	v_cmp_le_i32_e32 vcc, v65, v217
	v_add_u32_e32 v65, 0xffffffb6, v0
	s_nop 0
	v_cndmask_b32_e32 v121, v207, v121, vcc
	v_cmp_le_i32_e32 vcc, v65, v217
	v_add_u32_e32 v65, 0xffffff97, v0
	s_nop 0
	v_cndmask_b32_e32 v105, v207, v105, vcc
	v_cmp_le_i32_e32 vcc, v65, v217
	v_add_u32_e32 v65, 0xffffffb7, v0
	s_nop 0
	v_cndmask_b32_e32 v122, v207, v122, vcc
	v_cmp_le_i32_e32 vcc, v65, v217
	v_add_u32_e32 v65, 0xffffff98, v0
	s_nop 0
	v_cndmask_b32_e32 v106, v207, v106, vcc
	v_cmp_le_i32_e32 vcc, v65, v217
	v_add_u32_e32 v65, 0xffffffb8, v0
	s_nop 0
	v_cndmask_b32_e32 v123, v207, v123, vcc
	v_cmp_le_i32_e32 vcc, v65, v217
	v_add_u32_e32 v65, 0xffffff9d, v0
	s_nop 0
	v_cndmask_b32_e32 v107, v207, v107, vcc
	v_cmp_le_i32_e32 vcc, v65, v217
	v_add_u32_e32 v65, 0xffffffbd, v0
	s_nop 0
	v_cndmask_b32_e32 v124, v207, v124, vcc
	v_cmp_le_i32_e32 vcc, v65, v217
	v_add_u32_e32 v65, 0xffffff9e, v0
	s_nop 0
	v_cndmask_b32_e32 v108, v207, v108, vcc
	v_cmp_le_i32_e32 vcc, v65, v217
	v_add_u32_e32 v65, 0xffffffbe, v0
	s_nop 0
	v_cndmask_b32_e32 v125, v207, v125, vcc
	v_cmp_le_i32_e32 vcc, v65, v217
	v_add_u32_e32 v65, 0xffffff9f, v0
	s_nop 0
	v_cndmask_b32_e32 v109, v207, v109, vcc
	v_cmp_le_i32_e32 vcc, v65, v217
	v_add_u32_e32 v65, 0xffffffbf, v0
	s_nop 0
	v_cndmask_b32_e32 v126, v207, v126, vcc
	v_cmp_le_i32_e32 vcc, v65, v217
	v_add_u32_e32 v65, 0xffffffa0, v0
	s_nop 0
	v_cndmask_b32_e32 v110, v207, v110, vcc
	v_cmp_le_i32_e32 vcc, v65, v217
	v_subrev_u32_e32 v65, 64, v0
	s_nop 0
	v_cndmask_b32_e32 v127, v207, v127, vcc
	v_cmp_le_i32_e32 vcc, v65, v217
	s_nop 1
	v_cndmask_b32_e32 v111, v207, v111, vcc

.LBB0_259:
	s_waitcnt lgkmcnt(14)
	v_mfma_f32_32x32x16_bf16 v[32:47], v[156:159], v[196:199], v[32:47]
	v_exp_f32_e32 v112, v112
	v_exp_f32_e32 v113, v113
	v_exp_f32_e32 v114, v114
	v_exp_f32_e32 v115, v115
	s_waitcnt lgkmcnt(12)
	v_mfma_f32_32x32x16_bf16 v[16:31], v[156:159], v[188:191], v[16:31]
	v_exp_f32_e32 v116, v116
	v_exp_f32_e32 v117, v117
	v_exp_f32_e32 v118, v118
	v_exp_f32_e32 v119, v119
	v_add_u32_e32 v64, s65, v219
	ds_read_b128 v[188:191], v64
	ds_read_b128 v[184:187], v64 offset:512
	s_waitcnt lgkmcnt(12)
	v_mfma_f32_32x32x16_bf16 v[32:47], v[152:155], v[192:195], v[32:47]
	v_exp_f32_e32 v120, v120
	v_exp_f32_e32 v121, v121
	v_exp_f32_e32 v122, v122
	v_exp_f32_e32 v123, v123
	ds_read_b128 v[180:183], v64 offset:2048
	ds_read_b128 v[176:179], v64 offset:2560
	s_waitcnt lgkmcnt(12)
	v_mfma_f32_32x32x16_bf16 v[16:31], v[152:155], v[84:87], v[16:31]
	v_exp_f32_e32 v124, v124
	v_exp_f32_e32 v125, v125
	v_exp_f32_e32 v126, v126
	v_exp_f32_e32 v127, v127
	ds_read_b128 v[172:175], v64 offset:4096
	ds_read_b128 v[168:171], v64 offset:4608
	s_waitcnt lgkmcnt(12)
	v_mfma_f32_32x32x16_bf16 v[32:47], v[148:151], v[80:83], v[32:47]
	v_exp_f32_e32 v96, v96
	v_exp_f32_e32 v97, v97
	v_exp_f32_e32 v98, v98
	v_exp_f32_e32 v99, v99
	ds_read_b128 v[164:167], v64 offset:6144
	ds_read_b128 v[160:163], v64 offset:6656
	s_waitcnt lgkmcnt(12)
	v_mfma_f32_32x32x16_bf16 v[16:31], v[148:151], v[10:13], v[16:31]
	v_exp_f32_e32 v100, v100
	v_exp_f32_e32 v101, v101
	v_exp_f32_e32 v102, v102
	v_exp_f32_e32 v103, v103
	s_waitcnt lgkmcnt(10)
	v_mfma_f32_32x32x16_bf16 v[32:47], v[140:143], v[6:9], v[32:47]
	v_exp_f32_e32 v104, v104
	v_exp_f32_e32 v105, v105
	v_exp_f32_e32 v106, v106
	v_exp_f32_e32 v107, v107
	s_waitcnt lgkmcnt(8)
	v_mfma_f32_32x32x16_bf16 v[16:31], v[140:143], v[2:5], v[16:31]
	v_add_u32_e32 v84, s98, v220
	v_add_u32_e32 v84, 0xf000, v84
	ds_read_b64_tr_b16 v[2:3], v84 offset:24576
	ds_read_b64_tr_b16 v[4:5], v84 offset:25088
	ds_read_b64_tr_b16 v[6:7], v84 offset:28672
	ds_read_b64_tr_b16 v[8:9], v84 offset:29184
	ds_read_b64_tr_b16 v[10:11], v84 offset:25600
	ds_read_b64_tr_b16 v[12:13], v84 offset:26112
	ds_read_b64_tr_b16 v[64:65], v84 offset:29696
	ds_read_b64_tr_b16 v[66:67], v84 offset:30208
	ds_read_b64_tr_b16 v[68:69], v84 offset:26624
	ds_read_b64_tr_b16 v[70:71], v84 offset:27136
	ds_read_b64_tr_b16 v[72:73], v84 offset:30720
	ds_read_b64_tr_b16 v[74:75], v84 offset:31232
	ds_read_b64_tr_b16 v[76:77], v84 offset:27648
	ds_read_b64_tr_b16 v[78:79], v84 offset:28160
	ds_read_b64_tr_b16 v[80:81], v84 offset:31744
	ds_read_b64_tr_b16 v[82:83], v84 offset:32256
	s_waitcnt lgkmcnt(14)
	v_mfma_f32_32x32x16_bf16 v[224:239], v[156:159], v[2:5], v[224:239]
	s_waitcnt lgkmcnt(12)
	v_mfma_f32_32x32x16_bf16 v[240:255], v[156:159], v[6:9], v[240:255]
	s_waitcnt lgkmcnt(10)
	v_mfma_f32_32x32x16_bf16 v[224:239], v[152:155], v[10:13], v[224:239]
	s_waitcnt lgkmcnt(8)
	v_mfma_f32_32x32x16_bf16 v[240:255], v[152:155], v[64:67], v[240:255]
	s_waitcnt lgkmcnt(6)
	v_mfma_f32_32x32x16_bf16 v[224:239], v[148:151], v[68:71], v[224:239]
	s_waitcnt lgkmcnt(4)
	v_mfma_f32_32x32x16_bf16 v[240:255], v[148:151], v[72:75], v[240:255]
	s_waitcnt lgkmcnt(2)
	v_mfma_f32_32x32x16_bf16 v[224:239], v[140:143], v[76:79], v[224:239]
	s_waitcnt lgkmcnt(0)
	v_mfma_f32_32x32x16_bf16 v[240:255], v[140:143], v[80:83], v[240:255]
	v_exp_f32_e32 v108, v108
	v_exp_f32_e32 v109, v109
	v_exp_f32_e32 v110, v110
	v_exp_f32_e32 v111, v111
	s_mov_b64 s[44:45], -1
	s_and_b64 vcc, exec, s[2:3]
	s_cbranch_vccz .LBB0_292
	s_add_i32 s44, s46, -2
	s_cmp_ge_u32 s44, s66
	s_mov_b64 s[44:45], -1
	s_cbranch_scc0 .LBB0_262
	s_waitcnt vmcnt(0) lgkmcnt(0)
	s_barrier
	s_mov_b64 s[44:45], 0

.LBB0_266:
	s_waitcnt lgkmcnt(0)
	ds_read_b128 v[2:5], v223 offset:49248
	ds_read_b128 v[6:9], v223 offset:49216
	ds_read_b128 v[10:13], v223 offset:49184
	ds_read_b128 v[64:67], v223 offset:49152
	s_waitcnt lgkmcnt(3)
	v_pk_mul_f32 v[44:45], v[44:45], v[2:3]
	v_pk_mul_f32 v[236:237], v[236:237], v[2:3]
	s_waitcnt lgkmcnt(2)
	v_pk_mul_f32 v[40:41], v[40:41], v[6:7]
	v_pk_mul_f32 v[232:233], v[232:233], v[6:7]
	s_waitcnt lgkmcnt(1)
	v_pk_mul_f32 v[36:37], v[36:37], v[10:11]
	v_pk_mul_f32 v[228:229], v[228:229], v[10:11]
	v_pk_mul_f32 v[46:47], v[46:47], v[4:5]
	v_pk_mul_f32 v[238:239], v[238:239], v[4:5]
	v_pk_mul_f32 v[42:43], v[42:43], v[8:9]
	v_pk_mul_f32 v[234:235], v[234:235], v[8:9]
	v_pk_mul_f32 v[38:39], v[38:39], v[12:13]
	v_pk_mul_f32 v[230:231], v[230:231], v[12:13]
	s_waitcnt lgkmcnt(0)
	v_pk_mul_f32 v[34:35], v[34:35], v[66:67]
	v_pk_mul_f32 v[226:227], v[226:227], v[66:67]
	v_pk_mul_f32 v[32:33], v[32:33], v[64:65]
	v_pk_mul_f32 v[224:225], v[224:225], v[64:65]
	v_pk_mul_f32 v[28:29], v[28:29], v[2:3]
	v_pk_mul_f32 v[252:253], v[252:253], v[2:3]
	v_pk_mul_f32 v[24:25], v[24:25], v[6:7]
	v_pk_mul_f32 v[248:249], v[248:249], v[6:7]
	v_pk_mul_f32 v[20:21], v[20:21], v[10:11]
	v_pk_mul_f32 v[244:245], v[244:245], v[10:11]
	v_pk_mul_f32 v[30:31], v[30:31], v[4:5]
	v_pk_mul_f32 v[254:255], v[254:255], v[4:5]
	v_pk_mul_f32 v[26:27], v[26:27], v[8:9]
	v_pk_mul_f32 v[250:251], v[250:251], v[8:9]
	v_pk_mul_f32 v[22:23], v[22:23], v[12:13]
	v_pk_mul_f32 v[246:247], v[246:247], v[12:13]
	v_pk_mul_f32 v[18:19], v[18:19], v[66:67]
	v_pk_mul_f32 v[242:243], v[242:243], v[66:67]
	v_pk_mul_f32 v[16:17], v[16:17], v[64:65]
	v_pk_mul_f32 v[240:241], v[240:241], v[64:65]
.LBB0_267:
	v_add_u32_e32 v4, s64, v220
	s_mov_b32 s98, s64
	ds_read_b64_tr_b16 v[200:201], v4 offset:24576
	ds_read_b64_tr_b16 v[202:203], v4 offset:25088
	s_waitcnt lgkmcnt(9)
	v_mfma_f32_32x32x16_bf16 v[80:95], v[188:191], v[144:147], v[48:63]
	v_add_f32_e32 v2, v112, v113
	v_add_f32_e32 v2, v114, v2
	v_add_f32_e32 v2, v115, v2
	v_add_f32_e32 v2, v116, v2
	v_add_f32_e32 v2, v117, v2
	v_cvt_pk_bf16_f32 v156, v112, v113
	v_cvt_pk_bf16_f32 v157, v114, v115
	ds_read_b64_tr_b16 v[196:197], v4 offset:28672
	ds_read_b64_tr_b16 v[198:199], v4 offset:29184
	s_waitcnt lgkmcnt(10)
	v_mfma_f32_32x32x16_bf16 v[64:79], v[184:187], v[144:147], v[48:63]
	v_add_f32_e32 v2, v118, v2
	v_add_f32_e32 v2, v119, v2
	v_add_f32_e32 v2, v120, v2
	v_add_f32_e32 v2, v121, v2
	v_cvt_pk_bf16_f32 v158, v116, v117
	v_cvt_pk_bf16_f32 v159, v118, v119
	ds_read_b64_tr_b16 v[192:193], v4 offset:25600
	ds_read_b64_tr_b16 v[194:195], v4 offset:26112
	s_waitcnt lgkmcnt(11)
	v_mfma_f32_32x32x16_bf16 v[80:95], v[180:183], v[136:139], v[80:95]
	v_add_f32_e32 v2, v122, v2
	v_add_f32_e32 v2, v123, v2
	v_add_f32_e32 v2, v124, v2
	v_add_f32_e32 v2, v125, v2
	v_cvt_pk_bf16_f32 v152, v120, v121
	v_cvt_pk_bf16_f32 v153, v122, v123
	ds_read_b64_tr_b16 v[116:117], v4 offset:29696
	ds_read_b64_tr_b16 v[118:119], v4 offset:30208
	s_waitcnt lgkmcnt(12)
	v_mfma_f32_32x32x16_bf16 v[64:79], v[176:179], v[136:139], v[64:79]
	v_add_f32_e32 v2, v126, v2
	v_add_f32_e32 v2, v127, v2
	v_add_f32_e32 v2, v96, v2
	v_add_f32_e32 v2, v97, v2
	v_cvt_pk_bf16_f32 v154, v124, v125
	v_cvt_pk_bf16_f32 v155, v126, v127
	ds_read_b64_tr_b16 v[112:113], v4 offset:26624
	ds_read_b64_tr_b16 v[114:115], v4 offset:27136
	s_waitcnt lgkmcnt(13)
	v_mfma_f32_32x32x16_bf16 v[80:95], v[172:175], v[132:135], v[80:95]
	v_add_f32_e32 v2, v98, v2
	v_add_f32_e32 v2, v99, v2
	v_add_f32_e32 v2, v100, v2
	v_add_f32_e32 v2, v101, v2
	v_cvt_pk_bf16_f32 v148, v96, v97
	v_cvt_pk_bf16_f32 v149, v98, v99
	ds_read_b64_tr_b16 v[10:11], v4 offset:30720
	ds_read_b64_tr_b16 v[12:13], v4 offset:31232
	s_waitcnt lgkmcnt(14)
	v_mfma_f32_32x32x16_bf16 v[64:79], v[168:171], v[132:135], v[64:79]
	v_add_f32_e32 v2, v102, v2
	v_add_f32_e32 v2, v103, v2
	v_add_f32_e32 v2, v104, v2
	v_add_f32_e32 v2, v105, v2
	v_cvt_pk_bf16_f32 v150, v100, v101
	v_cvt_pk_bf16_f32 v151, v102, v103
	ds_read_b64_tr_b16 v[6:7], v4 offset:27648
	ds_read_b64_tr_b16 v[8:9], v4 offset:28160
	s_waitcnt lgkmcnt(14)
	v_mfma_f32_32x32x16_bf16 v[80:95], v[164:167], v[128:131], v[80:95]
	v_add_f32_e32 v2, v106, v2
	v_add_f32_e32 v2, v107, v2
	v_add_f32_e32 v2, v108, v2
	v_add_f32_e32 v96, v109, v2
	v_cvt_pk_bf16_f32 v140, v104, v105
	v_cvt_pk_bf16_f32 v141, v106, v107
	ds_read_b64_tr_b16 v[2:3], v4 offset:31744
	ds_read_b64_tr_b16 v[4:5], v4 offset:32256
	v_mfma_f32_32x32x16_bf16 v[64:79], v[160:163], v[128:131], v[64:79]
	v_add_f32_e32 v96, v110, v96
	v_add_f32_e32 v96, v111, v96
	v_add_f32_e32 v96, 0, v96
	v_cvt_pk_bf16_f32 v142, v108, v109
	v_cvt_pk_bf16_f32 v143, v110, v111
	s_add_i32 s68, s46, 2
	s_cmp_ge_u32 s68, s63
	s_cselect_b64 s[44:45], -1, 0
	s_and_b64 vcc, exec, s[44:45]
	s_cbranch_vccnz .LBB0_269
	s_add_i32 s6, s65, s61
	s_mov_b32 s7, m0
	s_mov_b32 m0, s6
	s_nop 0
	global_load_lds_dwordx4 v[204:205], off
	s_mov_b32 m0, s7
.LBB0_269:
	s_add_i32 s6, s65, 0x2000
	s_cmpk_lg_i32 s65, 0x4000
	s_cselect_b32 s64, s6, 0
	s_cmp_lt_u32 s46, s63
	s_cselect_b64 s[48:49], -1, 0
	s_cmp_ge_u32 s46, s63
	s_cbranch_scc1 .LBB0_271
	s_add_i32 s6, s64, s62
	s_add_i32 s100, s64, s99
	v_lshl_add_u64 v[98:99], v[14:15], 0, s[22:23]
	s_mov_b32 s7, m0
	s_mov_b32 m0, s6
	s_nop 0
	global_load_lds_dwordx4 v[98:99], off
	s_mov_b32 m0, s100
	v_lshl_add_u64 v[100:101], v[98:99], 0, 64
	v_lshl_add_u64 v[100:101], v[100:101], 0, 64
	global_load_lds_dwordx4 v[100:101], off
	s_mov_b32 m0, s7

.LBB0_282:
	s_waitcnt lgkmcnt(4)
	v_mfma_f32_32x32x16_bf16 v[16:31], v[148:151], v[10:13], v[16:31]
	v_exp_f32_e32 v68, v68
	v_exp_f32_e32 v69, v69
	v_exp_f32_e32 v70, v70
	v_exp_f32_e32 v71, v71
	s_waitcnt lgkmcnt(2)
	v_mfma_f32_32x32x16_bf16 v[32:47], v[140:143], v[6:9], v[32:47]
	v_exp_f32_e32 v72, v72
	v_exp_f32_e32 v73, v73
	v_exp_f32_e32 v74, v74
	v_exp_f32_e32 v75, v75
	s_waitcnt lgkmcnt(0)
	v_mfma_f32_32x32x16_bf16 v[16:31], v[140:143], v[2:5], v[16:31]
	v_add_u32_e32 v116, s98, v220
	v_add_u32_e32 v116, 0xf000, v116
	ds_read_b64_tr_b16 v[2:3], v116 offset:24576
	ds_read_b64_tr_b16 v[4:5], v116 offset:25088
	ds_read_b64_tr_b16 v[6:7], v116 offset:28672
	ds_read_b64_tr_b16 v[8:9], v116 offset:29184
	ds_read_b64_tr_b16 v[10:11], v116 offset:25600
	ds_read_b64_tr_b16 v[12:13], v116 offset:26112
	ds_read_b64_tr_b16 v[96:97], v116 offset:29696
	ds_read_b64_tr_b16 v[98:99], v116 offset:30208
	ds_read_b64_tr_b16 v[100:101], v116 offset:26624
	ds_read_b64_tr_b16 v[102:103], v116 offset:27136
	ds_read_b64_tr_b16 v[104:105], v116 offset:30720
	ds_read_b64_tr_b16 v[106:107], v116 offset:31232
	ds_read_b64_tr_b16 v[108:109], v116 offset:27648
	ds_read_b64_tr_b16 v[110:111], v116 offset:28160
	ds_read_b64_tr_b16 v[112:113], v116 offset:31744
	ds_read_b64_tr_b16 v[114:115], v116 offset:32256
	s_waitcnt lgkmcnt(14)
	v_mfma_f32_32x32x16_bf16 v[224:239], v[156:159], v[2:5], v[224:239]
	s_waitcnt lgkmcnt(12)
	v_mfma_f32_32x32x16_bf16 v[240:255], v[156:159], v[6:9], v[240:255]
	s_waitcnt lgkmcnt(10)
	v_mfma_f32_32x32x16_bf16 v[224:239], v[152:155], v[10:13], v[224:239]
	s_waitcnt lgkmcnt(8)
	v_mfma_f32_32x32x16_bf16 v[240:255], v[152:155], v[96:99], v[240:255]
	s_waitcnt lgkmcnt(6)
	v_mfma_f32_32x32x16_bf16 v[224:239], v[148:151], v[100:103], v[224:239]
	s_waitcnt lgkmcnt(4)
	v_mfma_f32_32x32x16_bf16 v[240:255], v[148:151], v[104:107], v[240:255]
	s_waitcnt lgkmcnt(2)
	v_mfma_f32_32x32x16_bf16 v[224:239], v[140:143], v[108:111], v[224:239]
	s_waitcnt lgkmcnt(0)
	v_mfma_f32_32x32x16_bf16 v[240:255], v[140:143], v[112:115], v[240:255]
	v_exp_f32_e32 v76, v76
	v_exp_f32_e32 v77, v77
	v_exp_f32_e32 v78, v78
	v_exp_f32_e32 v79, v79
	s_mov_b64 s[6:7], -1
	s_and_b64 vcc, exec, s[44:45]
	s_cbranch_vccz .LBB0_294
	s_and_b64 vcc, exec, s[2:3]
	s_cbranch_vccz .LBB0_285
	s_waitcnt vmcnt(0) lgkmcnt(0)
	s_barrier
	s_mov_b64 s[6:7], 0

.LBB0_289:
	s_waitcnt lgkmcnt(0)
	ds_read_b128 v[2:5], v223 offset:49248
	ds_read_b128 v[6:9], v223 offset:49216
	ds_read_b128 v[10:13], v223 offset:49184
	ds_read_b128 v[96:99], v223 offset:49152
	s_waitcnt lgkmcnt(3)
	v_pk_mul_f32 v[44:45], v[44:45], v[2:3]
	v_pk_mul_f32 v[236:237], v[236:237], v[2:3]
	s_waitcnt lgkmcnt(2)
	v_pk_mul_f32 v[40:41], v[40:41], v[6:7]
	v_pk_mul_f32 v[232:233], v[232:233], v[6:7]
	s_waitcnt lgkmcnt(1)
	v_pk_mul_f32 v[36:37], v[36:37], v[10:11]
	v_pk_mul_f32 v[228:229], v[228:229], v[10:11]
	v_pk_mul_f32 v[46:47], v[46:47], v[4:5]
	v_pk_mul_f32 v[238:239], v[238:239], v[4:5]
	v_pk_mul_f32 v[42:43], v[42:43], v[8:9]
	v_pk_mul_f32 v[234:235], v[234:235], v[8:9]
	v_pk_mul_f32 v[38:39], v[38:39], v[12:13]
	v_pk_mul_f32 v[230:231], v[230:231], v[12:13]
	s_waitcnt lgkmcnt(0)
	v_pk_mul_f32 v[34:35], v[34:35], v[98:99]
	v_pk_mul_f32 v[226:227], v[226:227], v[98:99]
	v_pk_mul_f32 v[32:33], v[32:33], v[96:97]
	v_pk_mul_f32 v[224:225], v[224:225], v[96:97]
	v_pk_mul_f32 v[28:29], v[28:29], v[2:3]
	v_pk_mul_f32 v[252:253], v[252:253], v[2:3]
	v_pk_mul_f32 v[24:25], v[24:25], v[6:7]
	v_pk_mul_f32 v[248:249], v[248:249], v[6:7]
	v_pk_mul_f32 v[20:21], v[20:21], v[10:11]
	v_pk_mul_f32 v[244:245], v[244:245], v[10:11]
	v_pk_mul_f32 v[30:31], v[30:31], v[4:5]
	v_pk_mul_f32 v[254:255], v[254:255], v[4:5]
	v_pk_mul_f32 v[26:27], v[26:27], v[8:9]
	v_pk_mul_f32 v[250:251], v[250:251], v[8:9]
	v_pk_mul_f32 v[22:23], v[22:23], v[12:13]
	v_pk_mul_f32 v[246:247], v[246:247], v[12:13]
	v_pk_mul_f32 v[18:19], v[18:19], v[98:99]
	v_pk_mul_f32 v[242:243], v[242:243], v[98:99]
	v_pk_mul_f32 v[16:17], v[16:17], v[96:97]
	v_pk_mul_f32 v[240:241], v[240:241], v[96:97]

.LBB0_303:
	v_add_u32_e32 v0, s65, v220
	s_mov_b32 s98, s65
	ds_read_b64_tr_b16 v[192:193], v0 offset:24576
	ds_read_b64_tr_b16 v[194:195], v0 offset:25088
	v_add_f32_e32 v2, v80, v81
	v_add_f32_e32 v2, v82, v2
	v_add_f32_e32 v2, v83, v2
	v_add_f32_e32 v2, v84, v2
	v_add_f32_e32 v2, v85, v2
	v_cvt_pk_bf16_f32 v156, v80, v81
	v_cvt_pk_bf16_f32 v157, v82, v83
	s_waitcnt lgkmcnt(9)
	v_mfma_f32_32x32x16_bf16 v[96:111], v[188:191], v[144:147], v[48:63]
	ds_read_b64_tr_b16 v[124:125], v0 offset:28672
	ds_read_b64_tr_b16 v[126:127], v0 offset:29184
	s_waitcnt lgkmcnt(10)
	v_mfma_f32_32x32x16_bf16 v[48:63], v[184:187], v[144:147], v[48:63]
	v_add_f32_e32 v2, v86, v2
	v_add_f32_e32 v2, v87, v2
	v_add_f32_e32 v2, v88, v2
	v_add_f32_e32 v2, v89, v2
	v_cvt_pk_bf16_f32 v158, v84, v85
	v_cvt_pk_bf16_f32 v159, v86, v87
	ds_read_b64_tr_b16 v[120:121], v0 offset:25600
	ds_read_b64_tr_b16 v[122:123], v0 offset:26112
	v_add_f32_e32 v2, v90, v2
	v_add_f32_e32 v2, v91, v2
	v_add_f32_e32 v2, v92, v2
	v_add_f32_e32 v2, v93, v2
	v_cvt_pk_bf16_f32 v152, v88, v89
	v_cvt_pk_bf16_f32 v153, v90, v91
	s_waitcnt lgkmcnt(11)
	v_mfma_f32_32x32x16_bf16 v[96:111], v[180:183], v[136:139], v[96:111]
	ds_read_b64_tr_b16 v[116:117], v0 offset:29696
	ds_read_b64_tr_b16 v[118:119], v0 offset:30208
	s_waitcnt lgkmcnt(12)
	v_mfma_f32_32x32x16_bf16 v[48:63], v[176:179], v[136:139], v[48:63]
	v_add_f32_e32 v2, v94, v2
	v_add_f32_e32 v2, v95, v2
	v_add_f32_e32 v2, v64, v2
	v_add_f32_e32 v2, v65, v2
	v_cvt_pk_bf16_f32 v154, v92, v93
	v_cvt_pk_bf16_f32 v155, v94, v95
	ds_read_b64_tr_b16 v[112:113], v0 offset:26624
	ds_read_b64_tr_b16 v[114:115], v0 offset:27136
	v_add_f32_e32 v2, v66, v2
	v_add_f32_e32 v2, v67, v2
	v_add_f32_e32 v2, v68, v2
	v_add_f32_e32 v2, v69, v2
	v_cvt_pk_bf16_f32 v148, v64, v65
	v_cvt_pk_bf16_f32 v149, v66, v67
	s_waitcnt lgkmcnt(13)
	v_mfma_f32_32x32x16_bf16 v[96:111], v[172:175], v[132:135], v[96:111]
	ds_read_b64_tr_b16 v[10:11], v0 offset:30720
	ds_read_b64_tr_b16 v[12:13], v0 offset:31232
	s_waitcnt lgkmcnt(14)
	v_mfma_f32_32x32x16_bf16 v[48:63], v[168:171], v[132:135], v[48:63]
	v_add_f32_e32 v2, v70, v2
	v_add_f32_e32 v2, v71, v2
	v_add_f32_e32 v2, v72, v2
	v_add_f32_e32 v2, v73, v2
	v_cvt_pk_bf16_f32 v150, v68, v69
	v_cvt_pk_bf16_f32 v151, v70, v71
	ds_read_b64_tr_b16 v[6:7], v0 offset:27648
	ds_read_b64_tr_b16 v[8:9], v0 offset:28160
	v_add_f32_e32 v2, v74, v2
	v_add_f32_e32 v2, v75, v2
	v_add_f32_e32 v2, v76, v2
	v_add_f32_e32 v14, v77, v2
	v_cvt_pk_bf16_f32 v140, v72, v73
	v_cvt_pk_bf16_f32 v141, v74, v75
	s_waitcnt lgkmcnt(14)
	v_mfma_f32_32x32x16_bf16 v[96:111], v[164:167], v[128:131], v[96:111]
	ds_read_b64_tr_b16 v[2:3], v0 offset:31744
	ds_read_b64_tr_b16 v[4:5], v0 offset:32256
	v_mfma_f32_32x32x16_bf16 v[48:63], v[160:163], v[128:131], v[48:63]
	v_add_f32_e32 v0, v78, v14
	v_add_f32_e32 v0, v79, v0
	v_add_f32_e32 v0, 0, v0
	v_cvt_pk_bf16_f32 v142, v76, v77
	v_cvt_pk_bf16_f32 v143, v78, v79
	v_or_b32_e32 v15, 0xe0, v214
	v_or_b32_e32 v14, 0xc0, v214
	v_cmp_le_i32_e32 vcc, v15, v217
	v_add_f32_e32 v0, v222, v0
	s_nop 2
	v_cndmask_b32_e32 v48, v207, v48, vcc
	v_cmp_lt_i32_e32 vcc, v14, v217
	s_nop 1
	v_cndmask_b32_e32 v65, v207, v97, vcc
	v_cmp_le_i32_e32 vcc, v14, v217
	v_or_b32_e32 v14, 0xe1, v214
	s_nop 0
	v_cndmask_b32_e32 v64, v207, v96, vcc
	v_cmp_le_i32_e32 vcc, v14, v217
	v_or_b32_e32 v14, 0xc2, v214
	v_max_f32_e32 v15, v64, v64
	v_cndmask_b32_e32 v49, v207, v49, vcc
	v_cmp_le_i32_e32 vcc, v14, v217
	v_or_b32_e32 v14, 0xe2, v214
	s_nop 0
	v_cndmask_b32_e32 v66, v207, v98, vcc
	v_cmp_le_i32_e32 vcc, v14, v217
	v_or_b32_e32 v14, 0xc3, v214
	s_nop 0
	v_cndmask_b32_e32 v50, v207, v50, vcc
	v_cmp_le_i32_e32 vcc, v14, v217
	v_or_b32_e32 v14, 0xe3, v214
	s_nop 0
	v_cndmask_b32_e32 v67, v207, v99, vcc
	v_cmp_le_i32_e32 vcc, v14, v217
	v_or_b32_e32 v14, 0xc8, v214
	s_nop 0
	v_cndmask_b32_e32 v51, v207, v51, vcc
	v_cmp_le_i32_e32 vcc, v14, v217
	v_or_b32_e32 v14, 0xe8, v214
	s_nop 0
	v_cndmask_b32_e32 v68, v207, v100, vcc
	v_cmp_le_i32_e32 vcc, v14, v217
	v_or_b32_e32 v14, 0xc9, v214
	s_nop 0
	v_cndmask_b32_e32 v52, v207, v52, vcc
	v_cmp_le_i32_e32 vcc, v14, v217
	v_or_b32_e32 v14, 0xe9, v214
	s_nop 0
	v_cndmask_b32_e32 v69, v207, v101, vcc
	v_cmp_le_i32_e32 vcc, v14, v217
	v_or_b32_e32 v14, 0xca, v214
	s_nop 0
	v_cndmask_b32_e32 v53, v207, v53, vcc
	v_cmp_le_i32_e32 vcc, v14, v217
	v_or_b32_e32 v14, 0xea, v214
	s_nop 0
	v_cndmask_b32_e32 v70, v207, v102, vcc
	v_cmp_le_i32_e32 vcc, v14, v217
	v_or_b32_e32 v14, 0xcb, v214
	s_nop 0
	v_cndmask_b32_e32 v54, v207, v54, vcc
	v_cmp_le_i32_e32 vcc, v14, v217
	v_or_b32_e32 v14, 0xeb, v214
	s_nop 0
	v_cndmask_b32_e32 v71, v207, v103, vcc
	v_cmp_le_i32_e32 vcc, v14, v217
	v_or_b32_e32 v14, 0xd0, v214
	s_nop 0
	v_cndmask_b32_e32 v55, v207, v55, vcc
	v_cmp_le_i32_e32 vcc, v14, v217
	v_or_b32_e32 v14, 0xf0, v214
	s_nop 0
	v_cndmask_b32_e32 v72, v207, v104, vcc
	v_cmp_le_i32_e32 vcc, v14, v217
	v_or_b32_e32 v14, 0xd1, v214
	s_nop 0
	v_cndmask_b32_e32 v56, v207, v56, vcc
	v_cmp_le_i32_e32 vcc, v14, v217
	v_or_b32_e32 v14, 0xf1, v214
	s_nop 0
	v_cndmask_b32_e32 v73, v207, v105, vcc
	v_cmp_le_i32_e32 vcc, v14, v217
	v_or_b32_e32 v14, 0xd2, v214
	s_nop 0
	v_cndmask_b32_e32 v57, v207, v57, vcc
	v_cmp_le_i32_e32 vcc, v14, v217
	v_or_b32_e32 v14, 0xf2, v214
	s_nop 0
	v_cndmask_b32_e32 v74, v207, v106, vcc
	v_cmp_le_i32_e32 vcc, v14, v217
	v_or_b32_e32 v14, 0xd3, v214
	s_nop 0
	v_cndmask_b32_e32 v58, v207, v58, vcc
	v_cmp_le_i32_e32 vcc, v14, v217
	v_or_b32_e32 v14, 0xf3, v214
	s_nop 0
	v_cndmask_b32_e32 v75, v207, v107, vcc
	v_cmp_le_i32_e32 vcc, v14, v217
	v_or_b32_e32 v14, 0xd8, v214
	s_nop 0
	v_cndmask_b32_e32 v59, v207, v59, vcc
	v_cmp_le_i32_e32 vcc, v14, v217
	v_or_b32_e32 v14, 0xf8, v214
	s_nop 0
	v_cndmask_b32_e32 v76, v207, v108, vcc
	v_cmp_le_i32_e32 vcc, v14, v217
	v_or_b32_e32 v14, 0xd9, v214
	s_nop 0
	v_cndmask_b32_e32 v60, v207, v60, vcc
	v_cmp_le_i32_e32 vcc, v14, v217
	v_or_b32_e32 v14, 0xf9, v214
	s_nop 0
	v_cndmask_b32_e32 v77, v207, v109, vcc
	v_cmp_le_i32_e32 vcc, v14, v217
	v_or_b32_e32 v14, 0xda, v214
	s_nop 0
	v_cndmask_b32_e32 v61, v207, v61, vcc
	v_cmp_le_i32_e32 vcc, v14, v217
	v_or_b32_e32 v14, 0xfa, v214
	s_nop 0
	v_cndmask_b32_e32 v78, v207, v110, vcc
	v_cmp_le_i32_e32 vcc, v14, v217
	v_or_b32_e32 v14, 0xdb, v214
	s_nop 0
	v_cndmask_b32_e32 v62, v207, v62, vcc
	v_cmp_le_i32_e32 vcc, v14, v217
	v_or_b32_e32 v14, 0xfb, v214
	s_nop 0
	v_cndmask_b32_e32 v79, v207, v111, vcc
	v_cmp_le_i32_e32 vcc, v14, v217
	v_max_f32_e32 v14, v65, v65
	v_max_f32_e32 v14, v15, v14
	v_max3_f32 v15, v66, v67, v49
	v_max3_f32 v14, v14, v48, v50
	v_max3_f32 v14, v14, v51, v68
	v_max3_f32 v15, v15, v70, v71
	v_max3_f32 v14, v14, v69, v52
	v_max3_f32 v15, v15, v54, v55
	v_max3_f32 v14, v14, v53, v72
	v_max3_f32 v15, v15, v74, v75
	v_max3_f32 v14, v14, v73, v56
	v_max3_f32 v15, v15, v58, v59
	v_cndmask_b32_e32 v63, v207, v63, vcc
	v_max3_f32 v14, v14, v57, v76
	v_max3_f32 v15, v15, v78, v79
	v_max3_f32 v14, v14, v77, v60
	v_max3_f32 v15, v15, v62, v63
	v_max3_f32 v14, v14, v61, v15
	v_mov_b32_e32 v15, v14
	s_nop 1
	v_permlane32_swap_b32_e32 v14, v15
	v_max_f32_e32 v15, v15, v15
	v_max_f32_e32 v14, v14, v14
	v_max_f32_e32 v14, v14, v15
	v_cmp_lt_f32_e32 vcc, s52, v14
	s_cmp_lg_u64 vcc, 0
	s_cselect_b64 s[2:3], -1, 0
	s_cbranch_vccnz .LBB0_308
.LBB0_304:
	s_waitcnt lgkmcnt(14)
	v_mfma_f32_32x32x16_bf16 v[32:47], v[156:159], v[192:195], v[32:47]
	v_exp_f32_e32 v64, v64
	v_exp_f32_e32 v65, v65
	v_exp_f32_e32 v66, v66
	v_exp_f32_e32 v67, v67
	s_waitcnt lgkmcnt(12)
	v_mfma_f32_32x32x16_bf16 v[16:31], v[156:159], v[124:127], v[16:31]
	v_exp_f32_e32 v68, v68
	v_exp_f32_e32 v69, v69
	v_exp_f32_e32 v70, v70
	v_exp_f32_e32 v71, v71
	s_waitcnt lgkmcnt(10)
	v_mfma_f32_32x32x16_bf16 v[32:47], v[152:155], v[120:123], v[32:47]
	v_exp_f32_e32 v72, v72
	v_exp_f32_e32 v73, v73
	v_exp_f32_e32 v74, v74
	v_exp_f32_e32 v75, v75
	s_waitcnt lgkmcnt(8)
	v_mfma_f32_32x32x16_bf16 v[16:31], v[152:155], v[116:119], v[16:31]
	v_exp_f32_e32 v76, v76
	v_exp_f32_e32 v77, v77
	v_exp_f32_e32 v78, v78
	v_exp_f32_e32 v79, v79
	s_waitcnt lgkmcnt(6)
	v_mfma_f32_32x32x16_bf16 v[32:47], v[148:151], v[112:115], v[32:47]
	v_exp_f32_e32 v48, v48
	v_exp_f32_e32 v49, v49
	v_exp_f32_e32 v50, v50
	v_exp_f32_e32 v51, v51
	s_waitcnt lgkmcnt(4)
	v_mfma_f32_32x32x16_bf16 v[16:31], v[148:151], v[10:13], v[16:31]
	v_exp_f32_e32 v52, v52
	v_exp_f32_e32 v53, v53
	v_exp_f32_e32 v54, v54
	v_exp_f32_e32 v55, v55
	s_waitcnt lgkmcnt(2)
	v_mfma_f32_32x32x16_bf16 v[32:47], v[140:143], v[6:9], v[32:47]
	v_exp_f32_e32 v56, v56
	v_exp_f32_e32 v57, v57
	v_exp_f32_e32 v58, v58
	v_exp_f32_e32 v59, v59
	s_waitcnt lgkmcnt(0)
	v_mfma_f32_32x32x16_bf16 v[16:31], v[140:143], v[2:5], v[16:31]
	v_add_u32_e32 v14, s98, v220
	v_add_u32_e32 v14, 0xf000, v14
	ds_read_b64_tr_b16 v[2:3], v14 offset:24576
	ds_read_b64_tr_b16 v[4:5], v14 offset:25088
	ds_read_b64_tr_b16 v[6:7], v14 offset:28672
	ds_read_b64_tr_b16 v[8:9], v14 offset:29184
	ds_read_b64_tr_b16 v[10:11], v14 offset:25600
	ds_read_b64_tr_b16 v[12:13], v14 offset:26112
	ds_read_b64_tr_b16 v[80:81], v14 offset:29696
	ds_read_b64_tr_b16 v[82:83], v14 offset:30208
	ds_read_b64_tr_b16 v[84:85], v14 offset:26624
	ds_read_b64_tr_b16 v[86:87], v14 offset:27136
	ds_read_b64_tr_b16 v[88:89], v14 offset:30720
	ds_read_b64_tr_b16 v[90:91], v14 offset:31232
	ds_read_b64_tr_b16 v[92:93], v14 offset:27648
	ds_read_b64_tr_b16 v[94:95], v14 offset:28160
	ds_read_b64_tr_b16 v[96:97], v14 offset:31744
	ds_read_b64_tr_b16 v[98:99], v14 offset:32256
	s_waitcnt lgkmcnt(14)
	v_mfma_f32_32x32x16_bf16 v[224:239], v[156:159], v[2:5], v[224:239]
	s_waitcnt lgkmcnt(12)
	v_mfma_f32_32x32x16_bf16 v[240:255], v[156:159], v[6:9], v[240:255]
	s_waitcnt lgkmcnt(10)
	v_mfma_f32_32x32x16_bf16 v[224:239], v[152:155], v[10:13], v[224:239]
	s_waitcnt lgkmcnt(8)
	v_mfma_f32_32x32x16_bf16 v[240:255], v[152:155], v[80:83], v[240:255]
	s_waitcnt lgkmcnt(6)
	v_mfma_f32_32x32x16_bf16 v[224:239], v[148:151], v[84:87], v[224:239]
	s_waitcnt lgkmcnt(4)
	v_mfma_f32_32x32x16_bf16 v[240:255], v[148:151], v[88:91], v[240:255]
	s_waitcnt lgkmcnt(2)
	v_mfma_f32_32x32x16_bf16 v[224:239], v[140:143], v[92:95], v[224:239]
	s_waitcnt lgkmcnt(0)
	v_mfma_f32_32x32x16_bf16 v[240:255], v[140:143], v[96:99], v[240:255]
	v_exp_f32_e32 v60, v60
	v_exp_f32_e32 v61, v61
	v_exp_f32_e32 v62, v62
	v_exp_f32_e32 v63, v63
	s_andn2_b64 vcc, exec, s[2:3]
	v_lshl_add_u32 v2, v214, 2, s60
	s_cbranch_vccnz .LBB0_306
	s_waitcnt lgkmcnt(0)
	ds_read_b128 v[4:7], v2 offset:49248
	ds_read_b128 v[8:11], v2 offset:49216
	ds_read_b128 v[12:15], v2 offset:49184
	ds_read_b128 v[80:83], v2 offset:49152
	s_waitcnt lgkmcnt(3)
	v_pk_mul_f32 v[46:47], v[46:47], v[6:7]
	v_pk_mul_f32 v[238:239], v[238:239], v[6:7]
	s_waitcnt lgkmcnt(2)
	v_pk_mul_f32 v[42:43], v[42:43], v[10:11]
	v_pk_mul_f32 v[234:235], v[234:235], v[10:11]
	s_waitcnt lgkmcnt(1)
	v_pk_mul_f32 v[38:39], v[38:39], v[14:15]
	v_pk_mul_f32 v[230:231], v[230:231], v[14:15]
	s_waitcnt lgkmcnt(0)
	v_pk_mul_f32 v[34:35], v[34:35], v[82:83]
	v_pk_mul_f32 v[226:227], v[226:227], v[82:83]
	v_pk_mul_f32 v[44:45], v[44:45], v[4:5]
	v_pk_mul_f32 v[236:237], v[236:237], v[4:5]
	v_pk_mul_f32 v[40:41], v[40:41], v[8:9]
	v_pk_mul_f32 v[232:233], v[232:233], v[8:9]
	v_pk_mul_f32 v[36:37], v[36:37], v[12:13]
	v_pk_mul_f32 v[228:229], v[228:229], v[12:13]
	v_pk_mul_f32 v[32:33], v[32:33], v[80:81]
	v_pk_mul_f32 v[224:225], v[224:225], v[80:81]
	v_pk_mul_f32 v[30:31], v[30:31], v[6:7]
	v_pk_mul_f32 v[254:255], v[254:255], v[6:7]
	v_pk_mul_f32 v[26:27], v[26:27], v[10:11]
	v_pk_mul_f32 v[250:251], v[250:251], v[10:11]
	v_pk_mul_f32 v[22:23], v[22:23], v[14:15]
	v_pk_mul_f32 v[246:247], v[246:247], v[14:15]
	v_pk_mul_f32 v[18:19], v[18:19], v[82:83]
	v_pk_mul_f32 v[242:243], v[242:243], v[82:83]
	v_pk_mul_f32 v[28:29], v[28:29], v[4:5]
	v_pk_mul_f32 v[252:253], v[252:253], v[4:5]
	v_pk_mul_f32 v[24:25], v[24:25], v[8:9]
	v_pk_mul_f32 v[248:249], v[248:249], v[8:9]
	v_pk_mul_f32 v[20:21], v[20:21], v[12:13]
	v_pk_mul_f32 v[244:245], v[244:245], v[12:13]
	v_pk_mul_f32 v[16:17], v[16:17], v[80:81]
	v_pk_mul_f32 v[240:241], v[240:241], v[80:81]
.LBB0_306:
	v_add_f32_e32 v4, v64, v65
	v_add_f32_e32 v4, v66, v4
	v_add_f32_e32 v4, v67, v4
	v_add_f32_e32 v4, v68, v4
	v_add_f32_e32 v4, v69, v4
	v_add_f32_e32 v4, v70, v4
	v_add_f32_e32 v4, v71, v4
	v_add_f32_e32 v4, v72, v4
	v_add_f32_e32 v4, v73, v4
	v_add_f32_e32 v4, v74, v4
	v_add_f32_e32 v4, v75, v4
	v_add_f32_e32 v4, v76, v4
	v_add_f32_e32 v4, v77, v4
	v_add_f32_e32 v4, v78, v4
	v_add_f32_e32 v4, v79, v4
	v_add_f32_e32 v4, v48, v4
	v_add_f32_e32 v4, v49, v4
	v_add_f32_e32 v4, v50, v4
	v_add_f32_e32 v4, v51, v4
	v_add_f32_e32 v4, v52, v4
	v_add_f32_e32 v4, v53, v4
	v_add_f32_e32 v4, v54, v4
	v_add_f32_e32 v4, v55, v4
	v_add_f32_e32 v4, v56, v4
	v_add_f32_e32 v4, v57, v4
	v_add_f32_e32 v4, v58, v4
	v_add_f32_e32 v4, v59, v4
	v_add_f32_e32 v4, v60, v4
	s_cmp_lg_u32 0, -1
	v_add_f32_e32 v4, v61, v4
	s_cselect_b32 s2, 0, 0
	v_add_f32_e32 v4, v62, v4
	s_addk_i32 s2, 0x6000
	v_add_f32_e32 v4, v63, v4
	v_add3_u32 v3, v215, s2, v212
	v_add_f32_e32 v0, v0, v4
	v_cvt_pk_bf16_f32 v4, v64, v65
	v_cvt_pk_bf16_f32 v5, v66, v67
	v_cvt_pk_bf16_f32 v6, v68, v69
	v_cvt_pk_bf16_f32 v7, v70, v71
	v_cvt_pk_bf16_f32 v8, v72, v73
	v_cvt_pk_bf16_f32 v9, v74, v75
	v_cvt_pk_bf16_f32 v10, v76, v77
	v_cvt_pk_bf16_f32 v11, v78, v79
	v_cvt_pk_bf16_f32 v12, v48, v49
	v_cvt_pk_bf16_f32 v13, v50, v51
	v_cvt_pk_bf16_f32 v14, v52, v53
	v_cvt_pk_bf16_f32 v15, v54, v55
	v_cvt_pk_bf16_f32 v48, v56, v57
	v_cvt_pk_bf16_f32 v49, v58, v59
	v_cvt_pk_bf16_f32 v50, v60, v61
	v_cvt_pk_bf16_f32 v51, v62, v63
	v_add3_u32 v3, v3, v213, s64
	v_add_u32_e32 v84, 0xf000, v3
	ds_read_b64_tr_b16 v[52:53],v3 offset:0
	ds_read_b64_tr_b16 v[54:55],v3 offset:512
	ds_read_b64_tr_b16 v[56:57],v3 offset:1024
	ds_read_b64_tr_b16 v[58:59],v3 offset:1536
	ds_read_b64_tr_b16 v[60:61],v3 offset:2048
	ds_read_b64_tr_b16 v[62:63],v3 offset:2560
	ds_read_b64_tr_b16 v[64:65],v3 offset:3072
	ds_read_b64_tr_b16 v[66:67],v3 offset:3584
	s_waitcnt lgkmcnt(0)
	s_nop 0
	v_mfma_f32_32x32x16_bf16 v[32:47], v[4:7], v[52:55], v[32:47]
	ds_read_b64_tr_b16 v[52:53],v3 offset:4096
	ds_read_b64_tr_b16 v[54:55],v3 offset:4608
	v_mfma_f32_32x32x16_bf16 v[32:47], v[8:11], v[56:59], v[32:47]
	ds_read_b64_tr_b16 v[56:57],v3 offset:5120
	ds_read_b64_tr_b16 v[58:59],v3 offset:5632
	v_mfma_f32_32x32x16_bf16 v[32:47], v[12:15], v[60:63], v[32:47]
	ds_read_b64_tr_b16 v[60:61],v3 offset:6144
	ds_read_b64_tr_b16 v[62:63],v3 offset:6656
	ds_read_b64_tr_b16 v[68:69],v3 offset:7168
	ds_read_b64_tr_b16 v[70:71],v3 offset:7680
	s_waitcnt lgkmcnt(0)
	v_mfma_f32_32x32x16_bf16 v[32:47], v[48:51], v[64:67], v[32:47]
	v_mfma_f32_32x32x16_bf16 v[16:31], v[4:7], v[52:55], v[16:31]
	v_mov_b32_e32 v3, v0
	s_nop 1
	v_permlane32_swap_b32_e32 v0, v3
	v_cmp_gt_u32_e32 vcc, 32, v208
	v_mfma_f32_32x32x16_bf16 v[16:31], v[8:11], v[56:59], v[16:31]
	v_mfma_f32_32x32x16_bf16 v[16:31], v[12:15], v[60:63], v[16:31]
	v_mfma_f32_32x32x16_bf16 v[16:31], v[48:51], v[68:71], v[16:31]
	ds_read_b64_tr_b16 v[52:53], v84 offset:0
	ds_read_b64_tr_b16 v[54:55], v84 offset:512
	ds_read_b64_tr_b16 v[56:57], v84 offset:1024
	ds_read_b64_tr_b16 v[58:59], v84 offset:1536
	ds_read_b64_tr_b16 v[60:61], v84 offset:2048
	ds_read_b64_tr_b16 v[62:63], v84 offset:2560
	ds_read_b64_tr_b16 v[64:65], v84 offset:3072
	ds_read_b64_tr_b16 v[66:67], v84 offset:3584
	ds_read_b64_tr_b16 v[68:69], v84 offset:4096
	ds_read_b64_tr_b16 v[70:71], v84 offset:4608
	ds_read_b64_tr_b16 v[72:73], v84 offset:5120
	ds_read_b64_tr_b16 v[74:75], v84 offset:5632
	ds_read_b64_tr_b16 v[76:77], v84 offset:6144
	ds_read_b64_tr_b16 v[78:79], v84 offset:6656
	ds_read_b64_tr_b16 v[80:81], v84 offset:7168
	ds_read_b64_tr_b16 v[82:83], v84 offset:7680
	s_waitcnt lgkmcnt(14)
	v_mfma_f32_32x32x16_bf16 v[224:239], v[4:7], v[52:55], v[224:239]
	s_waitcnt lgkmcnt(12)
	v_mfma_f32_32x32x16_bf16 v[224:239], v[8:11], v[56:59], v[224:239]
	s_waitcnt lgkmcnt(10)
	v_mfma_f32_32x32x16_bf16 v[224:239], v[12:15], v[60:63], v[224:239]
	s_waitcnt lgkmcnt(8)
	v_mfma_f32_32x32x16_bf16 v[224:239], v[48:51], v[64:67], v[224:239]
	s_waitcnt lgkmcnt(6)
	v_mfma_f32_32x32x16_bf16 v[240:255], v[4:7], v[68:71], v[240:255]
	s_waitcnt lgkmcnt(4)
	v_mfma_f32_32x32x16_bf16 v[240:255], v[8:11], v[72:75], v[240:255]
	s_waitcnt lgkmcnt(2)
	v_mfma_f32_32x32x16_bf16 v[240:255], v[12:15], v[76:79], v[240:255]
	s_waitcnt lgkmcnt(0)
	v_mfma_f32_32x32x16_bf16 v[240:255], v[48:51], v[80:83], v[240:255]
	s_and_saveexec_b64 s[2:3], vcc
	s_cbranch_execz .LBB0_232
	v_add_f32_e32 v0, v0, v3
	ds_write_b32 v216, v0 offset:49280
	s_branch .LBB0_232

.Lattn_rest_0:
	v_lshlrev_b32_e32 v225, 2, v206
	v_add_u32_e32 v225, 0x1b000, v225
	ds_read_b32 v254, v225
	s_waitcnt lgkmcnt(0)

.LBB0_1709:
	v_lshlrev_b32_e32 v225, 2, v206
	v_add_u32_e32 v225, 0x1b000, v225
	ds_write_b32 v225, v254
	s_mov_b32 s26, 0xffff0000
	s_mov_b32 s9, 0
	v_mov_b32_e32 v1, 0
	s_mov_b64 s[10:11], 0x12000000
	s_mov_b64 s[12:13], 0x14000000
	s_mov_b64 s[14:15], 0x12010000
	s_mov_b64 s[16:17], 0x10000000
	s_brev_b32 s51, 8
	s_mov_b64 s[18:19], 0x12020000
	s_mov_b64 s[20:21], 0x30000
	s_mov_b64 s[22:23], 0x10000
	s_mov_b64 s[24:25], 0x50000
	s_mov_b32 s27, -1
	s_mov_b32 s52, 0x41000000
	s_mov_b64 s[28:29], 0x20000
	s_mov_b64 s[30:31], 0x40000
	s_mov_b64 s[34:35], 0x1c000000
	v_mov_b32_e32 v208, 0xff800000
	s_branch .LBB0_1711

.Lattn_ep_1:
	ds_read_b128 v[4:7], v2 offset:49280
	ds_read_b128 v[8:11], v2 offset:49312
	s_add_u32 s4, s42, s57
	s_addc_u32 s5, s43, 0
	s_lshl_b32 s6, s59, 12
	s_waitcnt lgkmcnt(1)
	v_rcp_f32_e32 v0, v4
	v_rcp_f32_e32 v3, v5
	v_rcp_f32_e32 v12, v6
	v_rcp_f32_e32 v13, v7
	s_waitcnt lgkmcnt(0)
	v_rcp_f32_e32 v14, v8
	ds_read_b128 v[4:7], v2 offset:49344
	v_rcp_f32_e32 v15, v9
	v_rcp_f32_e32 v48, v10
	v_rcp_f32_e32 v49, v11
	ds_read_b128 v[8:11], v2 offset:49376
	s_waitcnt lgkmcnt(1)
	v_rcp_f32_e32 v2, v4
	v_rcp_f32_e32 v4, v5
	v_rcp_f32_e32 v5, v6
	v_rcp_f32_e32 v6, v7
	s_waitcnt lgkmcnt(0)
	v_rcp_f32_e32 v7, v8
	v_rcp_f32_e32 v8, v9
	v_rcp_f32_e32 v9, v10
	v_rcp_f32_e32 v10, v11
	s_add_i32 s6, s6, 0
	v_lshlrev_b32_e32 v11, 1, v211
	v_lshlrev_b32_e32 v50, 9, v212
	v_mul_f32_e32 v32, v32, v0
	v_mul_f32_e32 v0, v16, v0
	v_add3_u32 v11, s6, v11, v50
	v_cvt_pk_bf16_f32 v0, v0, s0
	ds_write_b16 v11, v0 offset:51264
	v_mul_f32_e32 v0, v33, v3
	v_cvt_pk_bf16_f32 v0, v0, s0
	ds_write_b16 v11, v0 offset:51328
	v_mul_f32_e32 v0, v17, v3
	v_cvt_pk_bf16_f32 v0, v0, s0
	ds_write_b16 v11, v0 offset:51392
	v_mul_f32_e32 v0, v34, v12
	v_cvt_pk_bf16_f32 v0, v0, s0
	ds_write_b16 v11, v0 offset:51456
	v_mul_f32_e32 v0, v18, v12
	v_cvt_pk_bf16_f32 v0, v0, s0
	ds_write_b16 v11, v0 offset:51520
	v_mul_f32_e32 v0, v35, v13
	v_cvt_pk_bf16_f32 v0, v0, s0
	ds_write_b16 v11, v0 offset:51584
	v_mul_f32_e32 v0, v19, v13
	v_cvt_pk_bf16_f32 v0, v0, s0
	ds_write_b16 v11, v0 offset:51648
	v_mul_f32_e32 v0, v36, v14
	v_cvt_pk_bf16_f32 v0, v0, s0
	ds_write_b16 v11, v0 offset:52224
	v_mul_f32_e32 v0, v20, v14
	v_cvt_pk_bf16_f32 v0, v0, s0
	ds_write_b16 v11, v0 offset:52288
	v_mul_f32_e32 v0, v37, v15
	v_cvt_pk_bf16_f32 v0, v0, s0
	ds_write_b16 v11, v0 offset:52352
	v_mul_f32_e32 v0, v21, v15
	v_cvt_pk_bf16_f32 v0, v0, s0
	ds_write_b16 v11, v0 offset:52416
	v_mul_f32_e32 v0, v38, v48
	v_cvt_pk_bf16_f32 v0, v0, s0
	ds_write_b16 v11, v0 offset:52480
	v_mul_f32_e32 v0, v22, v48
	v_cvt_pk_bf16_f32 v0, v0, s0
	ds_write_b16 v11, v0 offset:52544
	v_mul_f32_e32 v0, v39, v49
	v_cvt_pk_bf16_f32 v0, v0, s0
	ds_write_b16 v11, v0 offset:52608
	v_mul_f32_e32 v0, v23, v49
	v_cvt_pk_bf16_f32 v0, v0, s0
	ds_write_b16 v11, v0 offset:52672
	v_mul_f32_e32 v0, v40, v2
	v_cvt_pk_bf16_f32 v0, v0, s0
	ds_write_b16 v11, v0 offset:53248
	v_mul_f32_e32 v0, v24, v2
	v_cvt_pk_bf16_f32 v0, v0, s0
	ds_write_b16 v11, v0 offset:53312
	v_mul_f32_e32 v0, v41, v4
	v_cvt_pk_bf16_f32 v0, v0, s0
	ds_write_b16 v11, v0 offset:53376
	v_mul_f32_e32 v0, v25, v4
	v_cvt_pk_bf16_f32 v0, v0, s0
	ds_write_b16 v11, v0 offset:53440
	v_mul_f32_e32 v0, v42, v5
	v_cvt_pk_bf16_f32 v0, v0, s0
	ds_write_b16 v11, v0 offset:53504
	v_mul_f32_e32 v0, v26, v5
	v_cvt_pk_bf16_f32 v0, v0, s0
	ds_write_b16 v11, v0 offset:53568
	v_mul_f32_e32 v0, v43, v6
	v_cvt_pk_bf16_f32 v0, v0, s0
	ds_write_b16 v11, v0 offset:53632
	v_mul_f32_e32 v0, v27, v6
	v_cvt_pk_bf16_f32 v0, v0, s0
	ds_write_b16 v11, v0 offset:53696
	v_mul_f32_e32 v0, v44, v7
	v_cvt_pk_bf16_f32 v0, v0, s0
	ds_write_b16 v11, v0 offset:54272
	v_mul_f32_e32 v0, v28, v7
	v_cvt_pk_bf16_f32 v0, v0, s0
	ds_write_b16 v11, v0 offset:54336
	v_mul_f32_e32 v0, v45, v8
	v_cvt_pk_bf16_f32 v0, v0, s0
	ds_write_b16 v11, v0 offset:54400
	v_mul_f32_e32 v0, v29, v8
	v_cvt_pk_bf16_f32 v0, v0, s0
	ds_write_b16 v11, v0 offset:54464
	v_mul_f32_e32 v0, v46, v9
	v_cvt_pk_bf16_f32 v0, v0, s0
	ds_write_b16 v11, v0 offset:54528
	v_mul_f32_e32 v0, v30, v9
	v_cvt_pk_bf16_f32 v0, v0, s0
	ds_write_b16 v11, v0 offset:54592
	v_mul_f32_e32 v0, v47, v10
	v_cvt_pk_bf16_f32 v0, v0, s0
	ds_write_b16 v11, v0 offset:54656
	v_mul_f32_e32 v0, v31, v10
	v_cvt_pk_bf16_f32 v0, v0, s0
	s_lshl_b64 s[2:3], s[40:41], 11
	ds_write_b16 v11, v0 offset:54720
	v_lshlrev_b32_e32 v0, 1, v210
	v_cvt_pk_bf16_f32 v32, v32, s0
	s_add_u32 s2, s4, s2
	v_and_b32_e32 v0, 0x70, v0
	ds_write_b16 v11, v32 offset:51200
	s_addc_u32 s3, s5, s3
	v_lshrrev_b32_e32 v14, 3, v209
	v_add_u32_e32 v15, s6, v0
	s_waitcnt lgkmcnt(0)
	v_lshl_add_u64 v[2:3], s[2:3], 0, v[0:1]
	v_lshl_add_u32 v0, v14, 7, v15
	v_or_b32_e32 v16, 8, v14
	v_lshl_add_u64 v[10:11], v[2:3], 0, s[34:35]
	ds_read_b128 v[2:5], v0 offset:51200
	v_lshl_add_u32 v6, v16, 7, v15
	ds_read_b128 v[6:9], v6 offset:51200
	v_lshlrev_b32_e32 v0, 11, v14
	v_lshl_add_u64 v[12:13], v[10:11], 0, v[0:1]
	v_lshlrev_b32_e32 v0, 11, v16
	s_waitcnt lgkmcnt(1)
	global_store_dwordx4 v[12:13], v[2:5], off
	s_add_i32 s58, s58, 1
	s_cmp_eq_u32 s58, 4
	v_lshl_add_u64 v[2:3], v[10:11], 0, v[0:1]
	v_or_b32_e32 v0, 16, v14
	s_waitcnt lgkmcnt(0)
	global_store_dwordx4 v[2:3], v[6:9], off
	v_lshl_add_u32 v2, v0, 7, v15
	v_or_b32_e32 v14, 24, v14
	ds_read_b128 v[2:5], v2 offset:51200
	v_lshl_add_u32 v6, v14, 7, v15
	ds_read_b128 v[6:9], v6 offset:51200
	v_lshlrev_b32_e32 v0, 11, v0
	v_lshl_add_u64 v[12:13], v[10:11], 0, v[0:1]
	v_lshlrev_b32_e32 v0, 11, v14
	s_waitcnt lgkmcnt(1)
	global_store_dwordx4 v[12:13], v[2:5], off
	s_nop 1
	v_lshl_add_u64 v[2:3], v[10:11], 0, v[0:1]
	s_waitcnt lgkmcnt(0)
	global_store_dwordx4 v[2:3], v[6:9], off
	s_nop 1
	s_cmp_lg_u32 s101, 0
	s_cbranch_scc1 .Lattn_ep_done_1
	s_mov_b32 s101, 1
	v_mov_b32_e32 v16, v240
	v_mov_b32_e32 v17, v241
	v_mov_b32_e32 v18, v242
	v_mov_b32_e32 v19, v243
	v_mov_b32_e32 v20, v244
	v_mov_b32_e32 v21, v245
	v_mov_b32_e32 v22, v246
	v_mov_b32_e32 v23, v247
	v_mov_b32_e32 v24, v248
	v_mov_b32_e32 v25, v249
	v_mov_b32_e32 v26, v250
	v_mov_b32_e32 v27, v251
	v_mov_b32_e32 v28, v252
	v_mov_b32_e32 v29, v253
	v_mov_b32_e32 v30, v254
	v_mov_b32_e32 v31, v255
	v_mov_b32_e32 v32, v224
	v_mov_b32_e32 v33, v225
	v_mov_b32_e32 v34, v226
	v_mov_b32_e32 v35, v227
	v_mov_b32_e32 v36, v228
	v_mov_b32_e32 v37, v229
	v_mov_b32_e32 v38, v230
	v_mov_b32_e32 v39, v231
	v_mov_b32_e32 v40, v232
	v_mov_b32_e32 v41, v233
	v_mov_b32_e32 v42, v234
	v_mov_b32_e32 v43, v235
	v_mov_b32_e32 v44, v236
	v_mov_b32_e32 v45, v237
	v_mov_b32_e32 v46, v238
	v_mov_b32_e32 v47, v239
	v_mov_b32_e32 v2, v51
	s_add_u32 s57, s57, 0x80
	s_sub_u32 s58, s58, 1
	s_branch .Lattn_ep_1

.LBB0_1713:
	v_mov_b64_e32 v[224:225], 0
	v_mov_b64_e32 v[226:227], 0
	v_mov_b64_e32 v[228:229], 0
	v_mov_b64_e32 v[230:231], 0
	v_mov_b64_e32 v[232:233], 0
	v_mov_b64_e32 v[234:235], 0
	v_mov_b64_e32 v[236:237], 0
	v_mov_b64_e32 v[238:239], 0
	v_mov_b64_e32 v[240:241], 0
	v_mov_b64_e32 v[242:243], 0
	v_mov_b64_e32 v[244:245], 0
	v_mov_b64_e32 v[246:247], 0
	v_mov_b64_e32 v[248:249], 0
	v_mov_b64_e32 v[250:251], 0
	v_mov_b64_e32 v[252:253], 0
	v_mov_b64_e32 v[254:255], 0
	s_mov_b64 s[2:3], s[0:1]
	s_load_dwordx2 s[2:3], s[2:3], 0xf0
	s_and_b32 s4, s58, 2
	s_lshl_b32 s4, s4, 1
	s_and_b32 s8, s58, 1
	s_or_b32 s4, s4, s53
	s_mov_b64 s[6:7], s[0:1]
	s_waitcnt lgkmcnt(0)
	s_add_u32 s2, s2, s54
	s_addc_u32 s3, s3, 0
	s_add_u32 s45, s2, s55
	s_addc_u32 s46, s3, 0
	s_add_u32 s47, s2, s56
	v_mov_b32_e32 v36, v206
	s_addc_u32 s48, s3, 0
	s_lshl_b32 s2, s4, 8
	v_readfirstlane_b32 s5, v36
	s_ashr_i32 s59, s5, 6
	s_xor_b32 s3, s2, 0xf00
	s_cmp_eq_u32 s8, 0
	s_cselect_b32 s44, s2, s3
	s_lshl_b32 s8, s59, 5
	s_or_b32 s2, s36, s44
	s_ashr_i32 s3, s8, 31
	s_add_u32 s40, s2, s8
	s_addc_u32 s41, s37, s3
	s_lshl_b64 s[2:3], s[40:41], 10
	s_add_u32 s2, s45, s2
	s_addc_u32 s3, s46, s3
	s_load_dwordx2 s[42:43], s[6:7], 0xf0
	s_add_u32 s6, s45, s38
	v_and_b32_e32 v209, 63, v36
	s_addc_u32 s7, s46, s39
	s_add_u32 s46, s47, s38
	v_lshlrev_b32_e32 v0, 10, v209
	s_addc_u32 s47, s48, s39
	v_lshl_add_u64 v[2:3], s[6:7], 0, v[0:1]
	s_lshl_b32 s6, s59, 3
	s_lshl_b32 s4, s59, 4
	v_bfe_u32 v0, v36, 2, 4
	s_ashr_i32 s7, s6, 31
	v_and_or_b32 v0, s4, 48, v0
	s_ashr_i32 s4, s5, 3
	v_lshl_add_u64 v[4:5], s[6:7], 1, v[2:3]
	s_and_b32 s6, s4, 0xffffffe0
	v_lshlrev_b32_e32 v0, 10, v0
	s_ashr_i32 s7, s6, 31
	v_lshlrev_b32_e32 v210, 3, v36
	s_lshl_b32 s4, s59, 10
	v_lshl_add_u64 v[2:3], s[46:47], 0, v[0:1]
	v_and_b32_e32 v213, 24, v210
	s_cmp_lg_u32 0, -1
	v_and_b32_e32 v211, 31, v36
	v_lshl_add_u64 v[2:3], s[6:7], 1, v[2:3]
	v_lshlrev_b32_e32 v0, 1, v213
	s_cselect_b32 s6, 0, 0
	v_bfe_u32 v212, v36, 5, 1
	v_lshl_add_u64 v[196:197], v[4:5], 0, s[10:11]
	v_lshl_add_u64 v[2:3], v[2:3], 0, v[0:1]
	s_add_i32 s61, s4, s6
	s_mov_b32 s6, m0
	s_mov_b32 m0, s61
	s_nop 0
	global_load_lds_dwordx4 v[196:197], off
	s_mov_b32 m0, s6
	v_lshlrev_b32_e32 v0, 10, v211
	v_lshl_add_u64 v[34:35], v[2:3], 0, s[12:13]
	s_add_i32 s62, s61, 0x6000
	s_add_i32 s99, s62, 0xf000
	s_mov_b32 s6, m0
	s_mov_b32 m0, s62
	s_nop 0
	global_load_lds_dwordx4 v[34:35], off
	s_mov_b32 m0, s99
	v_lshl_add_u64 v[2:3], v[34:35], 0, 64
	v_lshl_add_u64 v[2:3], v[2:3], 0, 64
	global_load_lds_dwordx4 v[2:3], off
	s_mov_b32 m0, s6
	v_lshl_add_u64 v[2:3], v[4:5], 0, s[14:15]
	v_lshl_or_b32 v0, v212, 4, v0
	s_add_i32 s6, s61, 0x2000
	s_mov_b32 s7, m0
	s_mov_b32 m0, s6
	s_nop 0
	global_load_lds_dwordx4 v[2:3], off
	s_mov_b32 m0, s7
	v_lshl_add_u64 v[2:3], s[2:3], 0, v[0:1]
	v_add_co_u32_e32 v6, vcc, s51, v2
	v_lshlrev_b32_e32 v0, 10, v212
	s_nop 0
	v_addc_co_u32_e32 v7, vcc, 0, v3, vcc
	global_load_dwordx4 v[144:147], v[6:7], off
	v_lshl_add_u64 v[6:7], v[2:3], 0, s[16:17]
	global_load_dwordx4 v[136:139], v[6:7], off offset:32
	global_load_dwordx4 v[132:135], v[6:7], off offset:64
	global_load_dwordx4 v[128:131], v[6:7], off offset:96
	v_mov_b32_e32 v2, v1
	v_lshlrev_b32_e32 v3, 4, v211
	v_lshl_add_u64 v[4:5], v[4:5], 0, s[18:19]
	s_add_i32 s2, s61, 0x4000
	s_mov_b32 s3, m0
	s_mov_b32 m0, s2
	s_nop 0
	global_load_lds_dwordx4 v[4:5], off
	s_mov_b32 m0, s3
	v_add3_u32 v220, 0, v0, v3
	s_waitcnt vmcnt(3) lgkmcnt(0)
	s_barrier
	ds_read_b128 v[38:41], v220
	v_mov_b32_e32 v3, v2
	v_mov_b32_e32 v4, v2
	v_mov_b32_e32 v5, v2
	v_mov_b32_e32 v6, v2
	v_mov_b32_e32 v7, v2
	v_mov_b32_e32 v8, v2
	v_mov_b32_e32 v9, v2
	v_mov_b32_e32 v10, v2
	v_mov_b32_e32 v11, v2
	v_mov_b32_e32 v12, v2
	v_mov_b32_e32 v13, v2
	v_mov_b32_e32 v14, v2
	v_mov_b32_e32 v15, v2
	v_mov_b32_e32 v16, v2
	v_mov_b32_e32 v17, v2
	s_cmp_lg_u32 s44, 0
	s_cselect_b64 s[2:3], -1, 0
	v_lshlrev_b32_e32 v215, 2, v212
	v_or_b32_e32 v218, s8, v211
	s_and_b64 vcc, exec, s[2:3]
	s_waitcnt vmcnt(3) lgkmcnt(0)
	v_mfma_f32_32x32x16_bf16 v[18:33], v[38:41], v[144:147], v[2:17]
	ds_read_b128 v[38:41], v220 offset:512
	s_waitcnt lgkmcnt(0)
	v_mfma_f32_32x32x16_bf16 v[2:17], v[38:41], v[144:147], v[2:17]
	ds_read_b128 v[38:41], v220 offset:2048
	s_waitcnt vmcnt(2) lgkmcnt(0)
	v_mfma_f32_32x32x16_bf16 v[18:33], v[38:41], v[136:139], v[18:33]
	ds_read_b128 v[38:41], v220 offset:2560
	s_waitcnt lgkmcnt(0)
	v_mfma_f32_32x32x16_bf16 v[2:17], v[38:41], v[136:139], v[2:17]
	ds_read_b128 v[38:41], v220 offset:4096
	s_waitcnt vmcnt(1) lgkmcnt(0)
	v_mfma_f32_32x32x16_bf16 v[18:33], v[38:41], v[132:135], v[18:33]
	ds_read_b128 v[38:41], v220 offset:4608
	s_waitcnt lgkmcnt(0)
	v_mfma_f32_32x32x16_bf16 v[2:17], v[38:41], v[132:135], v[2:17]
	ds_read_b128 v[38:41], v220 offset:6144
	s_waitcnt vmcnt(0) lgkmcnt(0)
	v_mfma_f32_32x32x16_bf16 v[18:33], v[38:41], v[128:131], v[18:33]
	ds_read_b128 v[38:41], v220 offset:6656
	s_waitcnt lgkmcnt(0)
	v_mfma_f32_32x32x16_bf16 v[2:17], v[38:41], v[128:131], v[2:17]
	s_nop 15
	s_nop 7
	s_cbranch_vccnz .LBB0_1715
	v_or_b32_e32 v0, 32, v215
	v_cmp_le_i32_e32 vcc, v0, v218
	v_or_b32_e32 v0, 33, v215
	s_nop 7
	v_cndmask_b32_e32 v2, v208, v2, vcc
	v_cmp_lt_i32_e32 vcc, v215, v218
	s_nop 1
	v_cndmask_b32_e32 v19, v208, v19, vcc
	v_cmp_le_i32_e32 vcc, v215, v218
	s_nop 1
	v_cndmask_b32_e32 v18, v208, v18, vcc
	v_cmp_le_i32_e32 vcc, v0, v218
	v_or_b32_e32 v0, 2, v215
	s_nop 0
	v_cndmask_b32_e32 v3, v208, v3, vcc
	v_cmp_le_i32_e32 vcc, v0, v218
	v_or_b32_e32 v0, 34, v215
	s_nop 0
	v_cndmask_b32_e32 v20, v208, v20, vcc
	v_cmp_le_i32_e32 vcc, v0, v218
	v_or_b32_e32 v0, 3, v215
	s_nop 0
	v_cndmask_b32_e32 v4, v208, v4, vcc
	v_cmp_le_i32_e32 vcc, v0, v218
	v_or_b32_e32 v0, 35, v215
	s_nop 0
	v_cndmask_b32_e32 v21, v208, v21, vcc
	v_cmp_le_i32_e32 vcc, v0, v218
	v_or_b32_e32 v0, 8, v215
	s_nop 0
	v_cndmask_b32_e32 v5, v208, v5, vcc
	v_cmp_le_i32_e32 vcc, v0, v218
	v_or_b32_e32 v0, 40, v215
	s_nop 0
	v_cndmask_b32_e32 v22, v208, v22, vcc
	v_cmp_le_i32_e32 vcc, v0, v218
	v_or_b32_e32 v0, 9, v215
	s_nop 0
	v_cndmask_b32_e32 v6, v208, v6, vcc
	v_cmp_le_i32_e32 vcc, v0, v218
	v_or_b32_e32 v0, 41, v215
	s_nop 0
	v_cndmask_b32_e32 v23, v208, v23, vcc
	v_cmp_le_i32_e32 vcc, v0, v218
	v_or_b32_e32 v0, 10, v215
	s_nop 0
	v_cndmask_b32_e32 v7, v208, v7, vcc
	v_cmp_le_i32_e32 vcc, v0, v218
	v_or_b32_e32 v0, 42, v215
	s_nop 0
	v_cndmask_b32_e32 v24, v208, v24, vcc
	v_cmp_le_i32_e32 vcc, v0, v218
	v_or_b32_e32 v0, 11, v215
	s_nop 0
	v_cndmask_b32_e32 v8, v208, v8, vcc
	v_cmp_le_i32_e32 vcc, v0, v218
	v_or_b32_e32 v0, 43, v215
	s_nop 0
	v_cndmask_b32_e32 v25, v208, v25, vcc
	v_cmp_le_i32_e32 vcc, v0, v218
	v_or_b32_e32 v0, 16, v215
	s_nop 0
	v_cndmask_b32_e32 v9, v208, v9, vcc
	v_cmp_le_i32_e32 vcc, v0, v218
	v_or_b32_e32 v0, 48, v215
	s_nop 0
	v_cndmask_b32_e32 v26, v208, v26, vcc
	v_cmp_le_i32_e32 vcc, v0, v218
	v_or_b32_e32 v0, 17, v215
	s_nop 0
	v_cndmask_b32_e32 v10, v208, v10, vcc
	v_cmp_le_i32_e32 vcc, v0, v218
	v_or_b32_e32 v0, 49, v215
	s_nop 0
	v_cndmask_b32_e32 v27, v208, v27, vcc
	v_cmp_le_i32_e32 vcc, v0, v218
	v_or_b32_e32 v0, 18, v215
	s_nop 0
	v_cndmask_b32_e32 v11, v208, v11, vcc
	v_cmp_le_i32_e32 vcc, v0, v218
	v_or_b32_e32 v0, 50, v215
	s_nop 0
	v_cndmask_b32_e32 v28, v208, v28, vcc
	v_cmp_le_i32_e32 vcc, v0, v218
	v_or_b32_e32 v0, 19, v215
	s_nop 0
	v_cndmask_b32_e32 v12, v208, v12, vcc
	v_cmp_le_i32_e32 vcc, v0, v218
	v_or_b32_e32 v0, 51, v215
	s_nop 0
	v_cndmask_b32_e32 v29, v208, v29, vcc
	v_cmp_le_i32_e32 vcc, v0, v218
	v_or_b32_e32 v0, 24, v215
	s_nop 0
	v_cndmask_b32_e32 v13, v208, v13, vcc
	v_cmp_le_i32_e32 vcc, v0, v218
	v_or_b32_e32 v0, 56, v215
	s_nop 0
	v_cndmask_b32_e32 v30, v208, v30, vcc
	v_cmp_le_i32_e32 vcc, v0, v218
	v_or_b32_e32 v0, 25, v215
	s_nop 0
	v_cndmask_b32_e32 v14, v208, v14, vcc
	v_cmp_le_i32_e32 vcc, v0, v218
	v_or_b32_e32 v0, 57, v215
	s_nop 0
	v_cndmask_b32_e32 v31, v208, v31, vcc
	v_cmp_le_i32_e32 vcc, v0, v218
	v_or_b32_e32 v0, 26, v215
	s_nop 0
	v_cndmask_b32_e32 v15, v208, v15, vcc
	v_cmp_le_i32_e32 vcc, v0, v218
	v_or_b32_e32 v0, 58, v215
	s_nop 0
	v_cndmask_b32_e32 v32, v208, v32, vcc
	v_cmp_le_i32_e32 vcc, v0, v218
	v_or_b32_e32 v0, 27, v215
	s_nop 0
	v_cndmask_b32_e32 v16, v208, v16, vcc
	v_cmp_le_i32_e32 vcc, v0, v218
	v_or_b32_e32 v0, 59, v215
	s_nop 0
	v_cndmask_b32_e32 v33, v208, v33, vcc
	v_cmp_le_i32_e32 vcc, v0, v218
	s_nop 1
	v_cndmask_b32_e32 v17, v208, v17, vcc
.LBB0_1715:
	v_lshlrev_b32_e32 v0, 1, v36
	v_and_b32_e32 v216, 32, v0
	v_lshlrev_b32_e32 v0, 4, v36
	v_and_b32_e32 v0, 0xc0, v0
	v_lshl_or_b32 v214, v212, 8, v0
	v_add_u32_e32 v0, 0, v216
	v_add3_u32 v221, v0, v213, v214
	v_max3_f32 v0, v18, v19, v2
	v_max3_f32 v36, v20, v21, v3
	s_and_b32 s5, s5, 0x3fffffc0
	v_max3_f32 v0, v0, v4, v5
	v_max3_f32 v36, v36, v24, v25
	s_add_i32 s6, s44, 0x100
	v_max3_f32 v0, v0, v22, v23
	v_max3_f32 v36, v36, v8, v9
	s_lshl_b32 s5, s5, 2
	v_max3_f32 v0, v0, v6, v7
	v_max3_f32 v36, v36, v28, v29
	s_add_i32 s60, s5, 0
	v_max3_f32 v0, v0, v26, v27
	v_max3_f32 v36, v36, v12, v13
	s_lshr_b32 s63, s6, 6
	v_max3_f32 v0, v0, v10, v11
	v_max3_f32 v36, v36, v32, v33
	s_cmp_lg_u32 0, -1
	v_max3_f32 v0, v0, v30, v31
	v_max3_f32 v36, v36, v16, v17
	v_lshl_add_u64 v[198:199], v[34:35], 0, s[22:23]
	v_max3_f32 v0, v0, v14, v15
	s_mov_b32 s8, 1
	v_max_f32_e32 v0, v0, v36
	s_mov_b32 s45, 0
	v_mov_b32_e32 v36, v0
	s_nop 1
	v_permlane32_swap_b32_e32 v0, v36
	v_max_f32_e32 v0, v0, v36
	v_lshlrev_b32_e32 v222, 4, v212
	v_add_f32_e32 v219, v1, v0
	v_sub_f32_e32 v2, v2, v0
	v_sub_f32_e32 v3, v3, v0
	v_sub_f32_e32 v18, v18, v0
	v_sub_f32_e32 v19, v19, v0
	v_sub_f32_e32 v20, v20, v0
	s_nop 0
	v_xor_b32_e32 v48, 0x80000000, v219
	v_mov_b32_e32 v49, v48
	v_mov_b32_e32 v50, v48
	v_mov_b32_e32 v51, v48
	v_mov_b32_e32 v52, v48
	v_mov_b32_e32 v53, v48
	v_mov_b32_e32 v54, v48
	v_mov_b32_e32 v55, v48
	v_mov_b32_e32 v56, v48
	v_mov_b32_e32 v57, v48
	v_mov_b32_e32 v58, v48
	v_mov_b32_e32 v59, v48
	v_mov_b32_e32 v60, v48
	v_mov_b32_e32 v61, v48
	v_mov_b32_e32 v62, v48
	v_mov_b32_e32 v63, v48
	s_waitcnt vmcnt(0) lgkmcnt(0)
	s_barrier
	v_exp_f32_e32 v64, v2
	v_exp_f32_e32 v65, v3
	v_lshl_add_u64 v[2:3], v[196:197], 0, s[20:21]
	s_mov_b32 s5, m0
	s_mov_b32 m0, s61
	s_nop 0
	global_load_lds_dwordx4 v[2:3], off
	s_mov_b32 m0, s5
	s_cselect_b32 s5, 0, 0
	s_add_i32 s4, s5, s4
	s_add_i32 s4, s4, 0x8000
	s_add_i32 s100, s4, 0xf000
	s_mov_b32 s5, m0
	s_mov_b32 m0, s4
	s_nop 0
	global_load_lds_dwordx4 v[198:199], off
	s_mov_b32 m0, s100
	v_lshl_add_u64 v[2:3], v[198:199], 0, 64
	v_lshl_add_u64 v[2:3], v[2:3], 0, 64
	global_load_lds_dwordx4 v[2:3], off
	s_mov_b32 m0, s5
	ds_read_b128 v[188:191], v220 offset:8192
	ds_read_b128 v[184:187], v220 offset:8704
	ds_read_b128 v[180:183], v220 offset:10240
	ds_read_b128 v[176:179], v220 offset:10752
	ds_read_b128 v[172:175], v220 offset:12288
	ds_read_b128 v[168:171], v220 offset:12800
	ds_read_b128 v[164:167], v220 offset:14336
	ds_read_b128 v[160:163], v220 offset:14848
	v_sub_f32_e32 v4, v4, v0
	v_sub_f32_e32 v21, v21, v0
	v_sub_f32_e32 v5, v5, v0
	v_sub_f32_e32 v22, v22, v0
	v_sub_f32_e32 v6, v6, v0
	v_sub_f32_e32 v23, v23, v0
	v_sub_f32_e32 v7, v7, v0
	v_sub_f32_e32 v24, v24, v0
	v_sub_f32_e32 v8, v8, v0
	v_sub_f32_e32 v25, v25, v0
	v_sub_f32_e32 v9, v9, v0
	v_sub_f32_e32 v26, v26, v0
	v_sub_f32_e32 v10, v10, v0
	v_sub_f32_e32 v27, v27, v0
	v_sub_f32_e32 v11, v11, v0
	v_sub_f32_e32 v28, v28, v0
	v_sub_f32_e32 v12, v12, v0
	v_sub_f32_e32 v29, v29, v0
	v_sub_f32_e32 v13, v13, v0
	v_sub_f32_e32 v30, v30, v0
	v_sub_f32_e32 v14, v14, v0
	v_sub_f32_e32 v31, v31, v0
	v_sub_f32_e32 v15, v15, v0
	v_sub_f32_e32 v32, v32, v0
	v_sub_f32_e32 v16, v16, v0
	v_sub_f32_e32 v33, v33, v0
	v_sub_f32_e32 v0, v17, v0
	v_exp_f32_e32 v80, v18
	v_exp_f32_e32 v81, v19
	v_exp_f32_e32 v82, v20
	v_exp_f32_e32 v83, v21
	v_exp_f32_e32 v84, v22
	v_exp_f32_e32 v85, v23
	v_exp_f32_e32 v86, v24
	v_exp_f32_e32 v87, v25
	v_exp_f32_e32 v88, v26
	v_exp_f32_e32 v89, v27
	v_exp_f32_e32 v90, v28
	v_exp_f32_e32 v91, v29
	v_exp_f32_e32 v92, v30
	v_exp_f32_e32 v93, v31
	v_exp_f32_e32 v94, v32
	v_exp_f32_e32 v95, v33
	v_exp_f32_e32 v66, v4
	v_exp_f32_e32 v67, v5
	v_exp_f32_e32 v68, v6
	v_exp_f32_e32 v69, v7
	v_exp_f32_e32 v70, v8
	v_exp_f32_e32 v71, v9
	v_exp_f32_e32 v72, v10
	v_exp_f32_e32 v73, v11
	v_exp_f32_e32 v74, v12
	v_exp_f32_e32 v75, v13
	v_exp_f32_e32 v76, v14
	v_exp_f32_e32 v77, v15
	v_exp_f32_e32 v78, v16
	v_exp_f32_e32 v79, v0
	s_waitcnt vmcnt(2) lgkmcnt(0)
	s_barrier
	s_andn2_b64 vcc, exec, s[2:3]
	v_cmp_gt_u32_e64 s[4:5], 32, v209
	v_lshl_add_u32 v217, v211, 2, s60
	s_cbranch_vccnz .LBB0_1731
	v_mov_b32_e32 v14, v1
	v_mov_b32_e32 v15, v1
	v_lshl_add_u64 v[200:201], v[34:35], 0, s[20:21]
	v_mov_b32_e32 v0, v1
	v_mov_b32_e32 v2, v1
	v_mov_b32_e32 v3, v1
	v_mov_b32_e32 v4, v1
	v_mov_b32_e32 v5, v1
	v_mov_b32_e32 v6, v1
	v_mov_b32_e32 v7, v1
	v_mov_b32_e32 v8, v1
	v_mov_b32_e32 v9, v1
	v_mov_b32_e32 v10, v1
	v_mov_b32_e32 v11, v1
	v_mov_b32_e32 v12, v1
	v_mov_b32_e32 v13, v1
	v_mov_b64_e32 v[46:47], v[14:15]
	v_mov_b64_e32 v[30:31], v[14:15]
	s_add_i32 s46, s63, -5
	v_lshl_add_u64 v[202:203], v[196:197], 0, s[24:25]
	s_mov_b32 s2, 0
	s_movk_i32 s45, 0x4000
	s_movk_i32 s47, 0x2000
	v_mov_b32_e32 v223, 0
	v_mov_b64_e32 v[44:45], v[12:13]
	v_mov_b64_e32 v[42:43], v[10:11]
	v_mov_b64_e32 v[40:41], v[8:9]
	v_mov_b64_e32 v[38:39], v[6:7]
	v_mov_b64_e32 v[36:37], v[4:5]
	v_mov_b64_e32 v[34:35], v[2:3]
	v_mov_b64_e32 v[32:33], v[0:1]
	v_mov_b64_e32 v[28:29], v[12:13]
	v_mov_b64_e32 v[26:27], v[10:11]
	v_mov_b64_e32 v[24:25], v[8:9]
	v_mov_b64_e32 v[22:23], v[6:7]
	v_mov_b64_e32 v[20:21], v[4:5]
	v_mov_b64_e32 v[18:19], v[2:3]
	v_mov_b64_e32 v[16:17], v[0:1]
.LBB0_1717:
	v_add_u32_e32 v0, s2, v221
	s_mov_b32 s98, s2
	ds_read_b64_tr_b16 v[192:193], v0 offset:24576
	ds_read_b64_tr_b16 v[194:195], v0 offset:25088
	s_waitcnt lgkmcnt(9)
	v_mfma_f32_32x32x16_bf16 v[112:127], v[188:191], v[144:147], v[48:63]
	v_add_f32_e32 v2, v80, v81
	v_add_f32_e32 v2, v82, v2
	v_add_f32_e32 v2, v83, v2
	v_add_f32_e32 v2, v84, v2
	v_add_f32_e32 v2, v85, v2
	v_cvt_pk_bf16_f32 v156, v80, v81
	v_cvt_pk_bf16_f32 v157, v82, v83
	ds_read_b64_tr_b16 v[188:189], v0 offset:28672
	ds_read_b64_tr_b16 v[190:191], v0 offset:29184
	s_waitcnt lgkmcnt(10)
	v_mfma_f32_32x32x16_bf16 v[96:111], v[184:187], v[144:147], v[48:63]
	v_add_f32_e32 v2, v86, v2
	v_add_f32_e32 v2, v87, v2
	v_add_f32_e32 v2, v88, v2
	v_add_f32_e32 v2, v89, v2
	v_cvt_pk_bf16_f32 v158, v84, v85
	v_cvt_pk_bf16_f32 v159, v86, v87
	ds_read_b64_tr_b16 v[184:185], v0 offset:25600
	ds_read_b64_tr_b16 v[186:187], v0 offset:26112
	s_waitcnt lgkmcnt(11)
	v_mfma_f32_32x32x16_bf16 v[112:127], v[180:183], v[136:139], v[112:127]
	v_add_f32_e32 v2, v90, v2
	v_add_f32_e32 v2, v91, v2
	v_add_f32_e32 v2, v92, v2
	v_add_f32_e32 v2, v93, v2
	v_cvt_pk_bf16_f32 v152, v88, v89
	v_cvt_pk_bf16_f32 v153, v90, v91
	ds_read_b64_tr_b16 v[84:85], v0 offset:29696
	ds_read_b64_tr_b16 v[86:87], v0 offset:30208
	s_waitcnt lgkmcnt(12)
	v_mfma_f32_32x32x16_bf16 v[96:111], v[176:179], v[136:139], v[96:111]
	v_add_f32_e32 v2, v94, v2
	v_add_f32_e32 v2, v95, v2
	v_add_f32_e32 v2, v64, v2
	v_add_f32_e32 v2, v65, v2
	v_cvt_pk_bf16_f32 v154, v92, v93
	v_cvt_pk_bf16_f32 v155, v94, v95
	ds_read_b64_tr_b16 v[80:81], v0 offset:26624
	ds_read_b64_tr_b16 v[82:83], v0 offset:27136
	s_waitcnt lgkmcnt(13)
	v_mfma_f32_32x32x16_bf16 v[112:127], v[172:175], v[132:135], v[112:127]
	v_add_f32_e32 v2, v66, v2
	v_add_f32_e32 v2, v67, v2
	v_add_f32_e32 v2, v68, v2
	v_add_f32_e32 v2, v69, v2
	v_cvt_pk_bf16_f32 v148, v64, v65
	v_cvt_pk_bf16_f32 v149, v66, v67
	ds_read_b64_tr_b16 v[10:11], v0 offset:30720
	ds_read_b64_tr_b16 v[12:13], v0 offset:31232
	s_waitcnt lgkmcnt(14)
	v_mfma_f32_32x32x16_bf16 v[96:111], v[168:171], v[132:135], v[96:111]
	v_add_f32_e32 v2, v70, v2
	v_add_f32_e32 v2, v71, v2
	v_add_f32_e32 v2, v72, v2
	v_add_f32_e32 v2, v73, v2
	v_cvt_pk_bf16_f32 v150, v68, v69
	v_cvt_pk_bf16_f32 v151, v70, v71
	ds_read_b64_tr_b16 v[6:7], v0 offset:27648
	ds_read_b64_tr_b16 v[8:9], v0 offset:28160
	s_waitcnt lgkmcnt(14)
	v_mfma_f32_32x32x16_bf16 v[112:127], v[164:167], v[128:131], v[112:127]
	v_add_f32_e32 v2, v74, v2
	v_add_f32_e32 v2, v75, v2
	v_add_f32_e32 v2, v76, v2
	v_add_f32_e32 v14, v77, v2
	v_cvt_pk_bf16_f32 v140, v72, v73
	v_cvt_pk_bf16_f32 v141, v74, v75
	ds_read_b64_tr_b16 v[2:3], v0 offset:31744
	ds_read_b64_tr_b16 v[4:5], v0 offset:32256
	v_mfma_f32_32x32x16_bf16 v[96:111], v[160:163], v[128:131], v[96:111]
	v_add_f32_e32 v0, v78, v14
	v_add_f32_e32 v0, v79, v0
	v_add_f32_e32 v0, 0, v0
	v_cvt_pk_bf16_f32 v142, v76, v77
	v_cvt_pk_bf16_f32 v143, v78, v79
	v_lshl_add_u64 v[14:15], v[202:203], 0, s[26:27]
	s_add_i32 s2, s47, s61
	s_mov_b32 s3, m0
	s_mov_b32 m0, s2
	s_nop 0
	global_load_lds_dwordx4 v[14:15], off
	s_mov_b32 m0, s3
	v_lshl_add_u64 v[14:15], v[200:201], 0, s[26:27]
	s_add_i32 s2, s45, s62
	s_add_i32 s100, s45, s99
	s_mov_b32 s3, m0
	s_mov_b32 m0, s2
	s_nop 0
	global_load_lds_dwordx4 v[14:15], off
	s_mov_b32 m0, s100
	v_lshl_add_u64 v[64:65], v[14:15], 0, 64
	v_lshl_add_u64 v[64:65], v[64:65], 0, 64
	global_load_lds_dwordx4 v[64:65], off
	s_mov_b32 m0, s3
	v_max_f32_e32 v14, v113, v113
	v_max_f32_e32 v15, v112, v112
	v_max_f32_e32 v14, v15, v14
	v_max3_f32 v15, v114, v115, v97
	v_max3_f32 v14, v14, v96, v98
	v_max3_f32 v14, v14, v99, v116
	v_max3_f32 v15, v15, v118, v119
	v_max3_f32 v14, v14, v117, v100
	v_max3_f32 v15, v15, v102, v103
	v_max3_f32 v14, v14, v101, v120
	v_max3_f32 v15, v15, v122, v123
	v_max3_f32 v14, v14, v121, v104
	v_max3_f32 v15, v15, v106, v107
	v_max3_f32 v14, v14, v105, v124
	v_max3_f32 v15, v15, v126, v127
	v_max3_f32 v64, v14, v125, v108
	v_max3_f32 v15, v15, v110, v111
	v_add_f32_e32 v14, v223, v0
	v_max3_f32 v0, v64, v109, v15
	v_mov_b32_e32 v15, v0
	s_nop 1
	v_permlane32_swap_b32_e32 v0, v15
	v_max_f32_e32 v15, v15, v15
	v_max_f32_e32 v0, v0, v0
	v_max_f32_e32 v0, v0, v15
	v_cmp_lt_f32_e32 vcc, s52, v0
	s_cmp_lg_u64 vcc, 0
	s_cselect_b64 s[2:3], -1, 0
	s_cbranch_vccnz .LBB0_1725
.LBB0_1718:
	s_waitcnt lgkmcnt(14)
	v_mfma_f32_32x32x16_bf16 v[32:47], v[156:159], v[192:195], v[32:47]
	v_exp_f32_e32 v112, v112
	v_exp_f32_e32 v113, v113
	v_exp_f32_e32 v114, v114
	v_exp_f32_e32 v115, v115
	s_waitcnt lgkmcnt(12)
	v_mfma_f32_32x32x16_bf16 v[16:31], v[156:159], v[188:191], v[16:31]
	v_exp_f32_e32 v116, v116
	v_exp_f32_e32 v117, v117
	v_exp_f32_e32 v118, v118
	v_exp_f32_e32 v119, v119
	v_add_u32_e32 v0, s45, v220
	ds_read_b128 v[64:67], v0
	ds_read_b128 v[160:163], v0 offset:512
	s_waitcnt lgkmcnt(12)
	v_mfma_f32_32x32x16_bf16 v[32:47], v[152:155], v[184:187], v[32:47]
	v_exp_f32_e32 v120, v120
	v_exp_f32_e32 v121, v121
	v_exp_f32_e32 v122, v122
	v_exp_f32_e32 v123, v123
	ds_read_b128 v[192:195], v0 offset:2048
	ds_read_b128 v[184:187], v0 offset:2560
	s_waitcnt lgkmcnt(12)
	v_mfma_f32_32x32x16_bf16 v[16:31], v[152:155], v[84:87], v[16:31]
	v_exp_f32_e32 v124, v124
	v_exp_f32_e32 v125, v125
	v_exp_f32_e32 v126, v126
	v_exp_f32_e32 v127, v127
	ds_read_b128 v[188:191], v0 offset:4096
	ds_read_b128 v[176:179], v0 offset:4608
	s_waitcnt lgkmcnt(12)
	v_mfma_f32_32x32x16_bf16 v[32:47], v[148:151], v[80:83], v[32:47]
	v_exp_f32_e32 v96, v96
	v_exp_f32_e32 v97, v97
	v_exp_f32_e32 v98, v98
	v_exp_f32_e32 v99, v99
	ds_read_b128 v[180:183], v0 offset:6144
	ds_read_b128 v[172:175], v0 offset:6656
	s_waitcnt lgkmcnt(12)
	v_mfma_f32_32x32x16_bf16 v[16:31], v[148:151], v[10:13], v[16:31]
	v_exp_f32_e32 v100, v100
	v_exp_f32_e32 v101, v101
	v_exp_f32_e32 v102, v102
	v_exp_f32_e32 v103, v103
	s_waitcnt lgkmcnt(10)
	v_mfma_f32_32x32x16_bf16 v[32:47], v[140:143], v[6:9], v[32:47]
	v_exp_f32_e32 v104, v104
	v_exp_f32_e32 v105, v105
	v_exp_f32_e32 v106, v106
	v_exp_f32_e32 v107, v107
	s_waitcnt lgkmcnt(8)
	v_mfma_f32_32x32x16_bf16 v[16:31], v[140:143], v[2:5], v[16:31]
	v_add_u32_e32 v0, s98, v221
	v_add_u32_e32 v0, 0xf000, v0
	ds_read_b64_tr_b16 v[2:3], v0 offset:24576
	ds_read_b64_tr_b16 v[4:5], v0 offset:25088
	ds_read_b64_tr_b16 v[6:7], v0 offset:28672
	ds_read_b64_tr_b16 v[8:9], v0 offset:29184
	ds_read_b64_tr_b16 v[10:11], v0 offset:25600
	ds_read_b64_tr_b16 v[12:13], v0 offset:26112
	ds_read_b64_tr_b16 v[68:69], v0 offset:29696
	ds_read_b64_tr_b16 v[70:71], v0 offset:30208
	ds_read_b64_tr_b16 v[72:73], v0 offset:26624
	ds_read_b64_tr_b16 v[74:75], v0 offset:27136
	ds_read_b64_tr_b16 v[76:77], v0 offset:30720
	ds_read_b64_tr_b16 v[78:79], v0 offset:31232
	ds_read_b64_tr_b16 v[80:81], v0 offset:27648
	ds_read_b64_tr_b16 v[82:83], v0 offset:28160
	ds_read_b64_tr_b16 v[84:85], v0 offset:31744
	ds_read_b64_tr_b16 v[86:87], v0 offset:32256
	s_waitcnt lgkmcnt(14)
	v_mfma_f32_32x32x16_bf16 v[224:239], v[156:159], v[2:5], v[224:239]
	s_waitcnt lgkmcnt(12)
	v_mfma_f32_32x32x16_bf16 v[240:255], v[156:159], v[6:9], v[240:255]
	s_waitcnt lgkmcnt(10)
	v_mfma_f32_32x32x16_bf16 v[224:239], v[152:155], v[10:13], v[224:239]
	s_waitcnt lgkmcnt(8)
	v_mfma_f32_32x32x16_bf16 v[240:255], v[152:155], v[68:71], v[240:255]
	s_waitcnt lgkmcnt(6)
	v_mfma_f32_32x32x16_bf16 v[224:239], v[148:151], v[72:75], v[224:239]
	s_waitcnt lgkmcnt(4)
	v_mfma_f32_32x32x16_bf16 v[240:255], v[148:151], v[76:79], v[240:255]
	s_waitcnt lgkmcnt(2)
	v_mfma_f32_32x32x16_bf16 v[224:239], v[140:143], v[80:83], v[224:239]
	s_waitcnt lgkmcnt(0)
	v_mfma_f32_32x32x16_bf16 v[240:255], v[140:143], v[84:87], v[240:255]
	v_exp_f32_e32 v108, v108
	v_exp_f32_e32 v109, v109
	v_exp_f32_e32 v110, v110
	v_exp_f32_e32 v111, v111
	s_waitcnt vmcnt(2) lgkmcnt(0)
	s_barrier
	s_andn2_b64 vcc, exec, s[2:3]
	v_add_u32_e32 v0, s60, v222
	s_cbranch_vccnz .LBB0_1720
	s_waitcnt lgkmcnt(0)
	ds_read_b128 v[2:5], v0 offset:49248
	ds_read_b128 v[6:9], v0 offset:49216
	ds_read_b128 v[10:13], v0 offset:49184
	ds_read_b128 v[68:71], v0 offset:49152
	s_waitcnt lgkmcnt(3)
	v_pk_mul_f32 v[44:45], v[44:45], v[2:3]
	v_pk_mul_f32 v[236:237], v[236:237], v[2:3]
	s_waitcnt lgkmcnt(2)
	v_pk_mul_f32 v[40:41], v[40:41], v[6:7]
	v_pk_mul_f32 v[232:233], v[232:233], v[6:7]
	s_waitcnt lgkmcnt(1)
	v_pk_mul_f32 v[36:37], v[36:37], v[10:11]
	v_pk_mul_f32 v[228:229], v[228:229], v[10:11]
	v_pk_mul_f32 v[46:47], v[46:47], v[4:5]
	v_pk_mul_f32 v[238:239], v[238:239], v[4:5]
	v_pk_mul_f32 v[42:43], v[42:43], v[8:9]
	v_pk_mul_f32 v[234:235], v[234:235], v[8:9]
	v_pk_mul_f32 v[38:39], v[38:39], v[12:13]
	v_pk_mul_f32 v[230:231], v[230:231], v[12:13]
	s_waitcnt lgkmcnt(0)
	v_pk_mul_f32 v[34:35], v[34:35], v[70:71]
	v_pk_mul_f32 v[226:227], v[226:227], v[70:71]
	v_pk_mul_f32 v[32:33], v[32:33], v[68:69]
	v_pk_mul_f32 v[224:225], v[224:225], v[68:69]
	v_pk_mul_f32 v[28:29], v[28:29], v[2:3]
	v_pk_mul_f32 v[252:253], v[252:253], v[2:3]
	v_pk_mul_f32 v[24:25], v[24:25], v[6:7]
	v_pk_mul_f32 v[248:249], v[248:249], v[6:7]
	v_pk_mul_f32 v[20:21], v[20:21], v[10:11]
	v_pk_mul_f32 v[244:245], v[244:245], v[10:11]
	v_pk_mul_f32 v[30:31], v[30:31], v[4:5]
	v_pk_mul_f32 v[254:255], v[254:255], v[4:5]
	v_pk_mul_f32 v[26:27], v[26:27], v[8:9]
	v_pk_mul_f32 v[250:251], v[250:251], v[8:9]
	v_pk_mul_f32 v[22:23], v[22:23], v[12:13]
	v_pk_mul_f32 v[246:247], v[246:247], v[12:13]
	v_pk_mul_f32 v[18:19], v[18:19], v[70:71]
	v_pk_mul_f32 v[242:243], v[242:243], v[70:71]
	v_pk_mul_f32 v[16:17], v[16:17], v[68:69]
	v_pk_mul_f32 v[240:241], v[240:241], v[68:69]
.LBB0_1720:
	s_add_i32 s2, s45, 0x2000
	s_cmpk_lg_i32 s45, 0x4000
	s_cselect_b32 s64, s2, 0
	v_add_u32_e32 v4, s47, v221
	s_mov_b32 s98, s47
	ds_read_b64_tr_b16 v[168:169], v4 offset:24576
	ds_read_b64_tr_b16 v[170:171], v4 offset:25088
	s_waitcnt lgkmcnt(9)
	v_mfma_f32_32x32x16_bf16 v[80:95], v[64:67], v[144:147], v[48:63]
	v_add_f32_e32 v2, v112, v113
	v_add_f32_e32 v2, v114, v2
	v_add_f32_e32 v2, v115, v2
	v_add_f32_e32 v2, v116, v2
	v_add_f32_e32 v2, v117, v2
	v_cvt_pk_bf16_f32 v156, v112, v113
	v_cvt_pk_bf16_f32 v157, v114, v115
	ds_read_b64_tr_b16 v[164:165], v4 offset:28672
	ds_read_b64_tr_b16 v[166:167], v4 offset:29184
	s_waitcnt lgkmcnt(10)
	v_mfma_f32_32x32x16_bf16 v[64:79], v[160:163], v[144:147], v[48:63]
	v_add_f32_e32 v2, v118, v2
	v_add_f32_e32 v2, v119, v2
	v_add_f32_e32 v2, v120, v2
	v_add_f32_e32 v2, v121, v2
	v_cvt_pk_bf16_f32 v158, v116, v117
	v_cvt_pk_bf16_f32 v159, v118, v119
	ds_read_b64_tr_b16 v[160:161], v4 offset:25600
	ds_read_b64_tr_b16 v[162:163], v4 offset:26112
	s_waitcnt lgkmcnt(11)
	v_mfma_f32_32x32x16_bf16 v[80:95], v[192:195], v[136:139], v[80:95]
	v_add_f32_e32 v2, v122, v2
	v_add_f32_e32 v2, v123, v2
	v_add_f32_e32 v2, v124, v2
	v_add_f32_e32 v2, v125, v2
	v_cvt_pk_bf16_f32 v152, v120, v121
	v_cvt_pk_bf16_f32 v153, v122, v123
	ds_read_b64_tr_b16 v[116:117], v4 offset:29696
	ds_read_b64_tr_b16 v[118:119], v4 offset:30208
	s_waitcnt lgkmcnt(12)
	v_mfma_f32_32x32x16_bf16 v[64:79], v[184:187], v[136:139], v[64:79]
	v_add_f32_e32 v2, v126, v2
	v_add_f32_e32 v2, v127, v2
	v_add_f32_e32 v2, v96, v2
	v_add_f32_e32 v2, v97, v2
	v_cvt_pk_bf16_f32 v154, v124, v125
	v_cvt_pk_bf16_f32 v155, v126, v127
	ds_read_b64_tr_b16 v[112:113], v4 offset:26624
	ds_read_b64_tr_b16 v[114:115], v4 offset:27136
	s_waitcnt lgkmcnt(13)
	v_mfma_f32_32x32x16_bf16 v[80:95], v[188:191], v[132:135], v[80:95]
	v_add_f32_e32 v2, v98, v2
	v_add_f32_e32 v2, v99, v2
	v_add_f32_e32 v2, v100, v2
	v_add_f32_e32 v2, v101, v2
	v_cvt_pk_bf16_f32 v148, v96, v97
	v_cvt_pk_bf16_f32 v149, v98, v99
	ds_read_b64_tr_b16 v[10:11], v4 offset:30720
	ds_read_b64_tr_b16 v[12:13], v4 offset:31232
	s_waitcnt lgkmcnt(14)
	v_mfma_f32_32x32x16_bf16 v[64:79], v[176:179], v[132:135], v[64:79]
	v_add_f32_e32 v2, v102, v2
	v_add_f32_e32 v2, v103, v2
	v_add_f32_e32 v2, v104, v2
	v_add_f32_e32 v2, v105, v2
	v_cvt_pk_bf16_f32 v150, v100, v101
	v_cvt_pk_bf16_f32 v151, v102, v103
	ds_read_b64_tr_b16 v[6:7], v4 offset:27648
	ds_read_b64_tr_b16 v[8:9], v4 offset:28160
	s_waitcnt lgkmcnt(14)
	v_mfma_f32_32x32x16_bf16 v[80:95], v[180:183], v[128:131], v[80:95]
	v_add_f32_e32 v2, v106, v2
	v_add_f32_e32 v2, v107, v2
	v_add_f32_e32 v2, v108, v2
	v_add_f32_e32 v15, v109, v2
	v_cvt_pk_bf16_f32 v140, v104, v105
	v_cvt_pk_bf16_f32 v141, v106, v107
	ds_read_b64_tr_b16 v[2:3], v4 offset:31744
	ds_read_b64_tr_b16 v[4:5], v4 offset:32256
	v_mfma_f32_32x32x16_bf16 v[64:79], v[172:175], v[128:131], v[64:79]
	v_add_f32_e32 v15, v110, v15
	v_add_f32_e32 v15, v111, v15
	v_add_f32_e32 v15, 0, v15
	v_cvt_pk_bf16_f32 v142, v108, v109
	v_cvt_pk_bf16_f32 v143, v110, v111
	v_max_f32_e32 v96, v81, v81
	v_max_f32_e32 v97, v80, v80
	v_max_f32_e32 v96, v97, v96
	s_nop 3
	v_max3_f32 v97, v82, v83, v65
	v_max3_f32 v96, v96, v64, v66
	v_max3_f32 v96, v96, v67, v84
	v_max3_f32 v97, v97, v86, v87
	v_max3_f32 v96, v96, v85, v68
	v_max3_f32 v97, v97, v70, v71
	v_max3_f32 v96, v96, v69, v88
	v_max3_f32 v97, v97, v90, v91
	v_max3_f32 v96, v96, v89, v72
	v_max3_f32 v97, v97, v74, v75
	v_max3_f32 v96, v96, v73, v92
	v_max3_f32 v97, v97, v94, v95
	v_max3_f32 v96, v96, v93, v76
	v_max3_f32 v97, v97, v78, v79
	v_add_f32_e32 v223, v14, v15
	v_max3_f32 v14, v96, v77, v97
	v_mov_b32_e32 v15, v14
	s_nop 1
	v_permlane32_swap_b32_e32 v14, v15
	v_max_f32_e32 v15, v15, v15
	v_max_f32_e32 v14, v14, v14
	s_add_i32 s2, s45, s61
	s_mov_b32 s3, m0
	s_mov_b32 m0, s2
	s_nop 0
	global_load_lds_dwordx4 v[202:203], off
	s_mov_b32 m0, s3
	v_max_f32_e32 v14, v14, v15
	s_add_i32 s2, s64, s62
	s_add_i32 s100, s64, s99
	s_mov_b32 s3, m0
	s_mov_b32 m0, s2
	s_nop 0
	global_load_lds_dwordx4 v[200:201], off
	s_mov_b32 m0, s100
	v_lshl_add_u64 v[96:97], v[200:201], 0, 64
	v_lshl_add_u64 v[96:97], v[96:97], 0, 64
	global_load_lds_dwordx4 v[96:97], off
	s_mov_b32 m0, s3
	v_cmp_lt_f32_e32 vcc, s52, v14
	s_cmp_lg_u64 vcc, 0
	s_cselect_b64 s[2:3], -1, 0
	s_cbranch_vccnz .LBB0_1728
.LBB0_1721:
	s_waitcnt lgkmcnt(14)
	v_mfma_f32_32x32x16_bf16 v[32:47], v[156:159], v[168:171], v[32:47]
	v_exp_f32_e32 v80, v80
	v_exp_f32_e32 v81, v81
	v_exp_f32_e32 v82, v82
	v_exp_f32_e32 v83, v83
	s_waitcnt lgkmcnt(12)
	v_mfma_f32_32x32x16_bf16 v[16:31], v[156:159], v[164:167], v[16:31]
	v_exp_f32_e32 v84, v84
	v_exp_f32_e32 v85, v85
	v_exp_f32_e32 v86, v86
	v_exp_f32_e32 v87, v87
	v_add_u32_e32 v14, s64, v220
	ds_read_b128 v[188:191], v14
	ds_read_b128 v[184:187], v14 offset:512
	s_waitcnt lgkmcnt(12)
	v_mfma_f32_32x32x16_bf16 v[32:47], v[152:155], v[160:163], v[32:47]
	v_exp_f32_e32 v88, v88
	v_exp_f32_e32 v89, v89
	v_exp_f32_e32 v90, v90
	v_exp_f32_e32 v91, v91
	ds_read_b128 v[180:183], v14 offset:2048
	ds_read_b128 v[176:179], v14 offset:2560
	s_waitcnt lgkmcnt(12)
	v_mfma_f32_32x32x16_bf16 v[16:31], v[152:155], v[116:119], v[16:31]
	v_exp_f32_e32 v92, v92
	v_exp_f32_e32 v93, v93
	v_exp_f32_e32 v94, v94
	v_exp_f32_e32 v95, v95
	ds_read_b128 v[172:175], v14 offset:4096
	ds_read_b128 v[168:171], v14 offset:4608
	s_waitcnt lgkmcnt(12)
	v_mfma_f32_32x32x16_bf16 v[32:47], v[148:151], v[112:115], v[32:47]
	v_exp_f32_e32 v64, v64
	v_exp_f32_e32 v65, v65
	v_exp_f32_e32 v66, v66
	v_exp_f32_e32 v67, v67
	ds_read_b128 v[164:167], v14 offset:6144
	ds_read_b128 v[160:163], v14 offset:6656
	s_waitcnt lgkmcnt(12)
	v_mfma_f32_32x32x16_bf16 v[16:31], v[148:151], v[10:13], v[16:31]
	v_exp_f32_e32 v68, v68
	v_exp_f32_e32 v69, v69
	v_exp_f32_e32 v70, v70
	v_exp_f32_e32 v71, v71
	s_waitcnt lgkmcnt(10)
	v_mfma_f32_32x32x16_bf16 v[32:47], v[140:143], v[6:9], v[32:47]
	v_exp_f32_e32 v72, v72
	v_exp_f32_e32 v73, v73
	v_exp_f32_e32 v74, v74
	v_exp_f32_e32 v75, v75
	s_waitcnt lgkmcnt(8)
	v_mfma_f32_32x32x16_bf16 v[16:31], v[140:143], v[2:5], v[16:31]
	v_add_u32_e32 v14, s98, v221
	v_add_u32_e32 v14, 0xf000, v14
	ds_read_b64_tr_b16 v[2:3], v14 offset:24576
	ds_read_b64_tr_b16 v[4:5], v14 offset:25088
	ds_read_b64_tr_b16 v[6:7], v14 offset:28672
	ds_read_b64_tr_b16 v[8:9], v14 offset:29184
	ds_read_b64_tr_b16 v[10:11], v14 offset:25600
	ds_read_b64_tr_b16 v[12:13], v14 offset:26112
	ds_read_b64_tr_b16 v[96:97], v14 offset:29696
	ds_read_b64_tr_b16 v[98:99], v14 offset:30208
	ds_read_b64_tr_b16 v[100:101], v14 offset:26624
	ds_read_b64_tr_b16 v[102:103], v14 offset:27136
	ds_read_b64_tr_b16 v[104:105], v14 offset:30720
	ds_read_b64_tr_b16 v[106:107], v14 offset:31232
	ds_read_b64_tr_b16 v[108:109], v14 offset:27648
	ds_read_b64_tr_b16 v[110:111], v14 offset:28160
	ds_read_b64_tr_b16 v[112:113], v14 offset:31744
	ds_read_b64_tr_b16 v[114:115], v14 offset:32256
	s_waitcnt lgkmcnt(14)
	v_mfma_f32_32x32x16_bf16 v[224:239], v[156:159], v[2:5], v[224:239]
	s_waitcnt lgkmcnt(12)
	v_mfma_f32_32x32x16_bf16 v[240:255], v[156:159], v[6:9], v[240:255]
	s_waitcnt lgkmcnt(10)
	v_mfma_f32_32x32x16_bf16 v[224:239], v[152:155], v[10:13], v[224:239]
	s_waitcnt lgkmcnt(8)
	v_mfma_f32_32x32x16_bf16 v[240:255], v[152:155], v[96:99], v[240:255]
	s_waitcnt lgkmcnt(6)
	v_mfma_f32_32x32x16_bf16 v[224:239], v[148:151], v[100:103], v[224:239]
	s_waitcnt lgkmcnt(4)
	v_mfma_f32_32x32x16_bf16 v[240:255], v[148:151], v[104:107], v[240:255]
	s_waitcnt lgkmcnt(2)
	v_mfma_f32_32x32x16_bf16 v[224:239], v[140:143], v[108:111], v[224:239]
	s_waitcnt lgkmcnt(0)
	v_mfma_f32_32x32x16_bf16 v[240:255], v[140:143], v[112:115], v[240:255]
	v_exp_f32_e32 v76, v76
	v_exp_f32_e32 v77, v77
	v_exp_f32_e32 v78, v78
	v_exp_f32_e32 v79, v79
	s_waitcnt vmcnt(2) lgkmcnt(0)
	s_barrier
	s_andn2_b64 vcc, exec, s[2:3]
	s_cbranch_vccnz .LBB0_1723
	s_waitcnt lgkmcnt(0)
	ds_read_b128 v[2:5], v0 offset:49248
	ds_read_b128 v[6:9], v0 offset:49216
	ds_read_b128 v[10:13], v0 offset:49184
	ds_read_b128 v[96:99], v0 offset:49152
	s_waitcnt lgkmcnt(3)
	v_pk_mul_f32 v[44:45], v[44:45], v[2:3]
	v_pk_mul_f32 v[236:237], v[236:237], v[2:3]
	s_waitcnt lgkmcnt(2)
	v_pk_mul_f32 v[40:41], v[40:41], v[6:7]
	v_pk_mul_f32 v[232:233], v[232:233], v[6:7]
	s_waitcnt lgkmcnt(1)
	v_pk_mul_f32 v[36:37], v[36:37], v[10:11]
	v_pk_mul_f32 v[228:229], v[228:229], v[10:11]
	v_pk_mul_f32 v[46:47], v[46:47], v[4:5]
	v_pk_mul_f32 v[238:239], v[238:239], v[4:5]
	v_pk_mul_f32 v[42:43], v[42:43], v[8:9]
	v_pk_mul_f32 v[234:235], v[234:235], v[8:9]
	v_pk_mul_f32 v[38:39], v[38:39], v[12:13]
	v_pk_mul_f32 v[230:231], v[230:231], v[12:13]
	s_waitcnt lgkmcnt(0)
	v_pk_mul_f32 v[34:35], v[34:35], v[98:99]
	v_pk_mul_f32 v[226:227], v[226:227], v[98:99]
	v_pk_mul_f32 v[32:33], v[32:33], v[96:97]
	v_pk_mul_f32 v[224:225], v[224:225], v[96:97]
	v_pk_mul_f32 v[28:29], v[28:29], v[2:3]
	v_pk_mul_f32 v[252:253], v[252:253], v[2:3]
	v_pk_mul_f32 v[24:25], v[24:25], v[6:7]
	v_pk_mul_f32 v[248:249], v[248:249], v[6:7]
	v_pk_mul_f32 v[20:21], v[20:21], v[10:11]
	v_pk_mul_f32 v[244:245], v[244:245], v[10:11]
	v_pk_mul_f32 v[30:31], v[30:31], v[4:5]
	v_pk_mul_f32 v[254:255], v[254:255], v[4:5]
	v_pk_mul_f32 v[26:27], v[26:27], v[8:9]
	v_pk_mul_f32 v[250:251], v[250:251], v[8:9]
	v_pk_mul_f32 v[22:23], v[22:23], v[12:13]
	v_pk_mul_f32 v[246:247], v[246:247], v[12:13]
	v_pk_mul_f32 v[18:19], v[18:19], v[98:99]
	v_pk_mul_f32 v[242:243], v[242:243], v[98:99]
	v_pk_mul_f32 v[16:17], v[16:17], v[96:97]
	v_pk_mul_f32 v[240:241], v[240:241], v[96:97]

.LBB0_1734:
	v_add_u32_e32 v4, s45, v221
	s_mov_b32 s98, s45
	ds_read_b64_tr_b16 v[196:197], v4 offset:24576
	ds_read_b64_tr_b16 v[198:199], v4 offset:25088
	s_waitcnt lgkmcnt(9)
	v_mfma_f32_32x32x16_bf16 v[112:127], v[188:191], v[144:147], v[48:63]
	v_add_f32_e32 v2, v80, v81
	v_add_f32_e32 v2, v82, v2
	v_add_f32_e32 v2, v83, v2
	v_add_f32_e32 v2, v84, v2
	v_add_f32_e32 v2, v85, v2
	v_cvt_pk_bf16_f32 v156, v80, v81
	v_cvt_pk_bf16_f32 v157, v82, v83
	ds_read_b64_tr_b16 v[188:189], v4 offset:28672
	ds_read_b64_tr_b16 v[190:191], v4 offset:29184
	s_waitcnt lgkmcnt(10)
	v_mfma_f32_32x32x16_bf16 v[96:111], v[184:187], v[144:147], v[48:63]
	v_add_f32_e32 v2, v86, v2
	v_add_f32_e32 v2, v87, v2
	v_add_f32_e32 v2, v88, v2
	v_add_f32_e32 v2, v89, v2
	v_cvt_pk_bf16_f32 v158, v84, v85
	v_cvt_pk_bf16_f32 v159, v86, v87
	ds_read_b64_tr_b16 v[192:193], v4 offset:25600
	ds_read_b64_tr_b16 v[194:195], v4 offset:26112
	s_waitcnt lgkmcnt(11)
	v_mfma_f32_32x32x16_bf16 v[112:127], v[180:183], v[136:139], v[112:127]
	v_add_f32_e32 v2, v90, v2
	v_add_f32_e32 v2, v91, v2
	v_add_f32_e32 v2, v92, v2
	v_add_f32_e32 v2, v93, v2
	v_cvt_pk_bf16_f32 v152, v88, v89
	v_cvt_pk_bf16_f32 v153, v90, v91
	ds_read_b64_tr_b16 v[84:85], v4 offset:29696
	ds_read_b64_tr_b16 v[86:87], v4 offset:30208
	s_waitcnt lgkmcnt(12)
	v_mfma_f32_32x32x16_bf16 v[96:111], v[176:179], v[136:139], v[96:111]
	v_add_f32_e32 v2, v94, v2
	v_add_f32_e32 v2, v95, v2
	v_add_f32_e32 v2, v64, v2
	v_add_f32_e32 v2, v65, v2
	v_cvt_pk_bf16_f32 v154, v92, v93
	v_cvt_pk_bf16_f32 v155, v94, v95
	ds_read_b64_tr_b16 v[80:81], v4 offset:26624
	ds_read_b64_tr_b16 v[82:83], v4 offset:27136
	s_waitcnt lgkmcnt(13)
	v_mfma_f32_32x32x16_bf16 v[112:127], v[172:175], v[132:135], v[112:127]
	v_add_f32_e32 v2, v66, v2
	v_add_f32_e32 v2, v67, v2
	v_add_f32_e32 v2, v68, v2
	v_add_f32_e32 v2, v69, v2
	v_cvt_pk_bf16_f32 v148, v64, v65
	v_cvt_pk_bf16_f32 v149, v66, v67
	ds_read_b64_tr_b16 v[10:11], v4 offset:30720
	ds_read_b64_tr_b16 v[12:13], v4 offset:31232
	s_waitcnt lgkmcnt(14)
	v_mfma_f32_32x32x16_bf16 v[96:111], v[168:171], v[132:135], v[96:111]
	v_add_f32_e32 v2, v70, v2
	v_add_f32_e32 v2, v71, v2
	v_add_f32_e32 v2, v72, v2
	v_add_f32_e32 v2, v73, v2
	v_cvt_pk_bf16_f32 v150, v68, v69
	v_cvt_pk_bf16_f32 v151, v70, v71
	ds_read_b64_tr_b16 v[6:7], v4 offset:27648
	ds_read_b64_tr_b16 v[8:9], v4 offset:28160
	s_waitcnt lgkmcnt(14)
	v_mfma_f32_32x32x16_bf16 v[112:127], v[164:167], v[128:131], v[112:127]
	v_add_f32_e32 v2, v74, v2
	v_add_f32_e32 v2, v75, v2
	v_add_f32_e32 v2, v76, v2
	v_add_f32_e32 v64, v77, v2
	v_cvt_pk_bf16_f32 v140, v72, v73
	v_cvt_pk_bf16_f32 v141, v74, v75
	ds_read_b64_tr_b16 v[2:3], v4 offset:31744
	ds_read_b64_tr_b16 v[4:5], v4 offset:32256
	v_mfma_f32_32x32x16_bf16 v[96:111], v[160:163], v[128:131], v[96:111]
	v_add_f32_e32 v64, v78, v64
	v_add_f32_e32 v64, v79, v64
	v_add_f32_e32 v64, 0, v64
	v_cvt_pk_bf16_f32 v142, v76, v77
	v_cvt_pk_bf16_f32 v143, v78, v79
	s_add_i32 s2, s46, 1
	s_cmp_ge_u32 s2, s63
	s_cselect_b64 s[2:3], -1, 0
	s_and_b64 vcc, exec, s[2:3]
	s_cbranch_vccnz .LBB0_1736
	s_add_i32 s6, s64, s61
	v_lshl_add_u64 v[66:67], v[204:205], 0, s[26:27]
	s_mov_b32 s7, m0
	s_mov_b32 m0, s6
	s_nop 0
	global_load_lds_dwordx4 v[66:67], off
	s_mov_b32 m0, s7
.LBB0_1736:
	s_add_i32 s8, s67, s46
	s_add_i32 s6, s65, s62
	s_add_i32 s100, s65, s99
	s_add_i32 s7, s8, 2
	s_cmp_lt_i32 s7, 0
	s_mov_b32 s7, m0
	s_mov_b32 m0, s6
	s_nop 0
	global_load_lds_dwordx4 v[14:15], off
	s_mov_b32 m0, s100
	v_lshl_add_u64 v[66:67], v[14:15], 0, 64
	v_lshl_add_u64 v[66:67], v[66:67], 0, 64
	global_load_lds_dwordx4 v[66:67], off
	s_mov_b32 m0, s7
	s_cbranch_scc1 .LBB0_1738
	v_add_u32_e32 v66, 0xffffffa5, v0
	v_add_u32_e32 v65, 0xffffff85, v0
	v_cmp_le_i32_e32 vcc, v66, v218
	s_nop 1
	v_cndmask_b32_e32 v96, v208, v96, vcc
	v_cmp_lt_i32_e32 vcc, v65, v218
	s_nop 1
	v_cndmask_b32_e32 v113, v208, v113, vcc
	v_cmp_le_i32_e32 vcc, v65, v218
	v_add_u32_e32 v65, 0xffffffa6, v0
	s_nop 0
	v_cndmask_b32_e32 v112, v208, v112, vcc
	v_cmp_le_i32_e32 vcc, v65, v218
	v_add_u32_e32 v65, 0xffffff87, v0
	s_nop 0
	v_cndmask_b32_e32 v97, v208, v97, vcc
	v_cmp_le_i32_e32 vcc, v65, v218
	v_add_u32_e32 v65, 0xffffffa7, v0
	s_nop 0
	v_cndmask_b32_e32 v114, v208, v114, vcc
	v_cmp_le_i32_e32 vcc, v65, v218
	v_add_u32_e32 v65, 0xffffff88, v0
	s_nop 0
	v_cndmask_b32_e32 v98, v208, v98, vcc
	v_cmp_le_i32_e32 vcc, v65, v218
	v_add_u32_e32 v65, 0xffffffa8, v0
	s_nop 0
	v_cndmask_b32_e32 v115, v208, v115, vcc
	v_cmp_le_i32_e32 vcc, v65, v218
	v_add_u32_e32 v65, 0xffffff8d, v0
	s_nop 0
	v_cndmask_b32_e32 v99, v208, v99, vcc
	v_cmp_le_i32_e32 vcc, v65, v218
	v_add_u32_e32 v65, 0xffffffad, v0
	s_nop 0
	v_cndmask_b32_e32 v116, v208, v116, vcc
	v_cmp_le_i32_e32 vcc, v65, v218
	v_add_u32_e32 v65, 0xffffff8e, v0
	s_nop 0
	v_cndmask_b32_e32 v100, v208, v100, vcc
	v_cmp_le_i32_e32 vcc, v65, v218
	v_add_u32_e32 v65, 0xffffffae, v0
	s_nop 0
	v_cndmask_b32_e32 v117, v208, v117, vcc
	v_cmp_le_i32_e32 vcc, v65, v218
	v_add_u32_e32 v65, 0xffffff8f, v0
	s_nop 0
	v_cndmask_b32_e32 v101, v208, v101, vcc
	v_cmp_le_i32_e32 vcc, v65, v218
	v_add_u32_e32 v65, 0xffffffaf, v0
	s_nop 0
	v_cndmask_b32_e32 v118, v208, v118, vcc
	v_cmp_le_i32_e32 vcc, v65, v218
	v_add_u32_e32 v65, 0xffffff90, v0
	s_nop 0
	v_cndmask_b32_e32 v102, v208, v102, vcc
	v_cmp_le_i32_e32 vcc, v65, v218
	v_add_u32_e32 v65, 0xffffffb0, v0
	s_nop 0
	v_cndmask_b32_e32 v119, v208, v119, vcc
	v_cmp_le_i32_e32 vcc, v65, v218
	v_add_u32_e32 v65, 0xffffff95, v0
	s_nop 0
	v_cndmask_b32_e32 v103, v208, v103, vcc
	v_cmp_le_i32_e32 vcc, v65, v218
	v_add_u32_e32 v65, 0xffffffb5, v0
	s_nop 0
	v_cndmask_b32_e32 v120, v208, v120, vcc
	v_cmp_le_i32_e32 vcc, v65, v218
	v_add_u32_e32 v65, 0xffffff96, v0
	s_nop 0
	v_cndmask_b32_e32 v104, v208, v104, vcc
	v_cmp_le_i32_e32 vcc, v65, v218
	v_add_u32_e32 v65, 0xffffffb6, v0
	s_nop 0
	v_cndmask_b32_e32 v121, v208, v121, vcc
	v_cmp_le_i32_e32 vcc, v65, v218
	v_add_u32_e32 v65, 0xffffff97, v0
	s_nop 0
	v_cndmask_b32_e32 v105, v208, v105, vcc
	v_cmp_le_i32_e32 vcc, v65, v218
	v_add_u32_e32 v65, 0xffffffb7, v0
	s_nop 0
	v_cndmask_b32_e32 v122, v208, v122, vcc
	v_cmp_le_i32_e32 vcc, v65, v218
	v_add_u32_e32 v65, 0xffffff98, v0
	s_nop 0
	v_cndmask_b32_e32 v106, v208, v106, vcc
	v_cmp_le_i32_e32 vcc, v65, v218
	v_add_u32_e32 v65, 0xffffffb8, v0
	s_nop 0
	v_cndmask_b32_e32 v123, v208, v123, vcc
	v_cmp_le_i32_e32 vcc, v65, v218
	v_add_u32_e32 v65, 0xffffff9d, v0
	s_nop 0
	v_cndmask_b32_e32 v107, v208, v107, vcc
	v_cmp_le_i32_e32 vcc, v65, v218
	v_add_u32_e32 v65, 0xffffffbd, v0
	s_nop 0
	v_cndmask_b32_e32 v124, v208, v124, vcc
	v_cmp_le_i32_e32 vcc, v65, v218
	v_add_u32_e32 v65, 0xffffff9e, v0
	s_nop 0
	v_cndmask_b32_e32 v108, v208, v108, vcc
	v_cmp_le_i32_e32 vcc, v65, v218
	v_add_u32_e32 v65, 0xffffffbe, v0
	s_nop 0
	v_cndmask_b32_e32 v125, v208, v125, vcc
	v_cmp_le_i32_e32 vcc, v65, v218
	v_add_u32_e32 v65, 0xffffff9f, v0
	s_nop 0
	v_cndmask_b32_e32 v109, v208, v109, vcc
	v_cmp_le_i32_e32 vcc, v65, v218
	v_add_u32_e32 v65, 0xffffffbf, v0
	s_nop 0
	v_cndmask_b32_e32 v126, v208, v126, vcc
	v_cmp_le_i32_e32 vcc, v65, v218
	v_add_u32_e32 v65, 0xffffffa0, v0
	s_nop 0
	v_cndmask_b32_e32 v110, v208, v110, vcc
	v_cmp_le_i32_e32 vcc, v65, v218
	v_subrev_u32_e32 v65, 64, v0
	s_nop 0
	v_cndmask_b32_e32 v127, v208, v127, vcc
	v_cmp_le_i32_e32 vcc, v65, v218
	s_nop 1
	v_cndmask_b32_e32 v111, v208, v111, vcc

.LBB0_1739:
	s_waitcnt lgkmcnt(14)
	v_mfma_f32_32x32x16_bf16 v[32:47], v[156:159], v[196:199], v[32:47]
	v_exp_f32_e32 v112, v112
	v_exp_f32_e32 v113, v113
	v_exp_f32_e32 v114, v114
	v_exp_f32_e32 v115, v115
	s_waitcnt lgkmcnt(12)
	v_mfma_f32_32x32x16_bf16 v[16:31], v[156:159], v[188:191], v[16:31]
	v_exp_f32_e32 v116, v116
	v_exp_f32_e32 v117, v117
	v_exp_f32_e32 v118, v118
	v_exp_f32_e32 v119, v119
	v_add_u32_e32 v64, s65, v220
	ds_read_b128 v[188:191], v64
	ds_read_b128 v[184:187], v64 offset:512
	s_waitcnt lgkmcnt(12)
	v_mfma_f32_32x32x16_bf16 v[32:47], v[152:155], v[192:195], v[32:47]
	v_exp_f32_e32 v120, v120
	v_exp_f32_e32 v121, v121
	v_exp_f32_e32 v122, v122
	v_exp_f32_e32 v123, v123
	ds_read_b128 v[180:183], v64 offset:2048
	ds_read_b128 v[176:179], v64 offset:2560
	s_waitcnt lgkmcnt(12)
	v_mfma_f32_32x32x16_bf16 v[16:31], v[152:155], v[84:87], v[16:31]
	v_exp_f32_e32 v124, v124
	v_exp_f32_e32 v125, v125
	v_exp_f32_e32 v126, v126
	v_exp_f32_e32 v127, v127
	ds_read_b128 v[172:175], v64 offset:4096
	ds_read_b128 v[168:171], v64 offset:4608
	s_waitcnt lgkmcnt(12)
	v_mfma_f32_32x32x16_bf16 v[32:47], v[148:151], v[80:83], v[32:47]
	v_exp_f32_e32 v96, v96
	v_exp_f32_e32 v97, v97
	v_exp_f32_e32 v98, v98
	v_exp_f32_e32 v99, v99
	ds_read_b128 v[164:167], v64 offset:6144
	ds_read_b128 v[160:163], v64 offset:6656
	s_waitcnt lgkmcnt(12)
	v_mfma_f32_32x32x16_bf16 v[16:31], v[148:151], v[10:13], v[16:31]
	v_exp_f32_e32 v100, v100
	v_exp_f32_e32 v101, v101
	v_exp_f32_e32 v102, v102
	v_exp_f32_e32 v103, v103
	s_waitcnt lgkmcnt(10)
	v_mfma_f32_32x32x16_bf16 v[32:47], v[140:143], v[6:9], v[32:47]
	v_exp_f32_e32 v104, v104
	v_exp_f32_e32 v105, v105
	v_exp_f32_e32 v106, v106
	v_exp_f32_e32 v107, v107
	s_waitcnt lgkmcnt(8)
	v_mfma_f32_32x32x16_bf16 v[16:31], v[140:143], v[2:5], v[16:31]
	v_add_u32_e32 v84, s98, v221
	v_add_u32_e32 v84, 0xf000, v84
	ds_read_b64_tr_b16 v[2:3], v84 offset:24576
	ds_read_b64_tr_b16 v[4:5], v84 offset:25088
	ds_read_b64_tr_b16 v[6:7], v84 offset:28672
	ds_read_b64_tr_b16 v[8:9], v84 offset:29184
	ds_read_b64_tr_b16 v[10:11], v84 offset:25600
	ds_read_b64_tr_b16 v[12:13], v84 offset:26112
	ds_read_b64_tr_b16 v[64:65], v84 offset:29696
	ds_read_b64_tr_b16 v[66:67], v84 offset:30208
	ds_read_b64_tr_b16 v[68:69], v84 offset:26624
	ds_read_b64_tr_b16 v[70:71], v84 offset:27136
	ds_read_b64_tr_b16 v[72:73], v84 offset:30720
	ds_read_b64_tr_b16 v[74:75], v84 offset:31232
	ds_read_b64_tr_b16 v[76:77], v84 offset:27648
	ds_read_b64_tr_b16 v[78:79], v84 offset:28160
	ds_read_b64_tr_b16 v[80:81], v84 offset:31744
	ds_read_b64_tr_b16 v[82:83], v84 offset:32256
	s_waitcnt lgkmcnt(14)
	v_mfma_f32_32x32x16_bf16 v[224:239], v[156:159], v[2:5], v[224:239]
	s_waitcnt lgkmcnt(12)
	v_mfma_f32_32x32x16_bf16 v[240:255], v[156:159], v[6:9], v[240:255]
	s_waitcnt lgkmcnt(10)
	v_mfma_f32_32x32x16_bf16 v[224:239], v[152:155], v[10:13], v[224:239]
	s_waitcnt lgkmcnt(8)
	v_mfma_f32_32x32x16_bf16 v[240:255], v[152:155], v[64:67], v[240:255]
	s_waitcnt lgkmcnt(6)
	v_mfma_f32_32x32x16_bf16 v[224:239], v[148:151], v[68:71], v[224:239]
	s_waitcnt lgkmcnt(4)
	v_mfma_f32_32x32x16_bf16 v[240:255], v[148:151], v[72:75], v[240:255]
	s_waitcnt lgkmcnt(2)
	v_mfma_f32_32x32x16_bf16 v[224:239], v[140:143], v[76:79], v[224:239]
	s_waitcnt lgkmcnt(0)
	v_mfma_f32_32x32x16_bf16 v[240:255], v[140:143], v[80:83], v[240:255]
	v_exp_f32_e32 v108, v108
	v_exp_f32_e32 v109, v109
	v_exp_f32_e32 v110, v110
	v_exp_f32_e32 v111, v111
	s_mov_b64 s[44:45], -1
	s_and_b64 vcc, exec, s[2:3]
	s_cbranch_vccz .LBB0_1772
	s_add_i32 s44, s46, -2
	s_cmp_ge_u32 s44, s66
	s_mov_b64 s[44:45], -1
	s_cbranch_scc0 .LBB0_1742
	s_waitcnt vmcnt(0) lgkmcnt(0)
	s_barrier
	s_mov_b64 s[44:45], 0

.LBB0_1745:
	s_andn2_b64 vcc, exec, s[6:7]
	v_add_u32_e32 v207, s60, v222
	s_cbranch_vccnz .LBB0_1747
.LBB0_1746:
	s_waitcnt lgkmcnt(0)
	ds_read_b128 v[2:5], v207 offset:49248
	ds_read_b128 v[6:9], v207 offset:49216
	ds_read_b128 v[10:13], v207 offset:49184
	ds_read_b128 v[64:67], v207 offset:49152
	s_waitcnt lgkmcnt(3)
	v_pk_mul_f32 v[44:45], v[44:45], v[2:3]
	v_pk_mul_f32 v[236:237], v[236:237], v[2:3]
	s_waitcnt lgkmcnt(2)
	v_pk_mul_f32 v[40:41], v[40:41], v[6:7]
	v_pk_mul_f32 v[232:233], v[232:233], v[6:7]
	s_waitcnt lgkmcnt(1)
	v_pk_mul_f32 v[36:37], v[36:37], v[10:11]
	v_pk_mul_f32 v[228:229], v[228:229], v[10:11]
	v_pk_mul_f32 v[46:47], v[46:47], v[4:5]
	v_pk_mul_f32 v[238:239], v[238:239], v[4:5]
	v_pk_mul_f32 v[42:43], v[42:43], v[8:9]
	v_pk_mul_f32 v[234:235], v[234:235], v[8:9]
	v_pk_mul_f32 v[38:39], v[38:39], v[12:13]
	v_pk_mul_f32 v[230:231], v[230:231], v[12:13]
	s_waitcnt lgkmcnt(0)
	v_pk_mul_f32 v[34:35], v[34:35], v[66:67]
	v_pk_mul_f32 v[226:227], v[226:227], v[66:67]
	v_pk_mul_f32 v[32:33], v[32:33], v[64:65]
	v_pk_mul_f32 v[224:225], v[224:225], v[64:65]
	v_pk_mul_f32 v[28:29], v[28:29], v[2:3]
	v_pk_mul_f32 v[252:253], v[252:253], v[2:3]
	v_pk_mul_f32 v[24:25], v[24:25], v[6:7]
	v_pk_mul_f32 v[248:249], v[248:249], v[6:7]
	v_pk_mul_f32 v[20:21], v[20:21], v[10:11]
	v_pk_mul_f32 v[244:245], v[244:245], v[10:11]
	v_pk_mul_f32 v[30:31], v[30:31], v[4:5]
	v_pk_mul_f32 v[254:255], v[254:255], v[4:5]
	v_pk_mul_f32 v[26:27], v[26:27], v[8:9]
	v_pk_mul_f32 v[250:251], v[250:251], v[8:9]
	v_pk_mul_f32 v[22:23], v[22:23], v[12:13]
	v_pk_mul_f32 v[246:247], v[246:247], v[12:13]
	v_pk_mul_f32 v[18:19], v[18:19], v[66:67]
	v_pk_mul_f32 v[242:243], v[242:243], v[66:67]
	v_pk_mul_f32 v[16:17], v[16:17], v[64:65]
	v_pk_mul_f32 v[240:241], v[240:241], v[64:65]
.LBB0_1747:
	v_add_u32_e32 v4, s64, v221
	s_mov_b32 s98, s64
	ds_read_b64_tr_b16 v[200:201], v4 offset:24576
	ds_read_b64_tr_b16 v[202:203], v4 offset:25088
	s_waitcnt lgkmcnt(9)
	v_mfma_f32_32x32x16_bf16 v[80:95], v[188:191], v[144:147], v[48:63]
	v_add_f32_e32 v2, v112, v113
	v_add_f32_e32 v2, v114, v2
	v_add_f32_e32 v2, v115, v2
	v_add_f32_e32 v2, v116, v2
	v_add_f32_e32 v2, v117, v2
	v_cvt_pk_bf16_f32 v156, v112, v113
	v_cvt_pk_bf16_f32 v157, v114, v115
	ds_read_b64_tr_b16 v[196:197], v4 offset:28672
	ds_read_b64_tr_b16 v[198:199], v4 offset:29184
	s_waitcnt lgkmcnt(10)
	v_mfma_f32_32x32x16_bf16 v[64:79], v[184:187], v[144:147], v[48:63]
	v_add_f32_e32 v2, v118, v2
	v_add_f32_e32 v2, v119, v2
	v_add_f32_e32 v2, v120, v2
	v_add_f32_e32 v2, v121, v2
	v_cvt_pk_bf16_f32 v158, v116, v117
	v_cvt_pk_bf16_f32 v159, v118, v119
	ds_read_b64_tr_b16 v[192:193], v4 offset:25600
	ds_read_b64_tr_b16 v[194:195], v4 offset:26112
	s_waitcnt lgkmcnt(11)
	v_mfma_f32_32x32x16_bf16 v[80:95], v[180:183], v[136:139], v[80:95]
	v_add_f32_e32 v2, v122, v2
	v_add_f32_e32 v2, v123, v2
	v_add_f32_e32 v2, v124, v2
	v_add_f32_e32 v2, v125, v2
	v_cvt_pk_bf16_f32 v152, v120, v121
	v_cvt_pk_bf16_f32 v153, v122, v123
	ds_read_b64_tr_b16 v[116:117], v4 offset:29696
	ds_read_b64_tr_b16 v[118:119], v4 offset:30208
	s_waitcnt lgkmcnt(12)
	v_mfma_f32_32x32x16_bf16 v[64:79], v[176:179], v[136:139], v[64:79]
	v_add_f32_e32 v2, v126, v2
	v_add_f32_e32 v2, v127, v2
	v_add_f32_e32 v2, v96, v2
	v_add_f32_e32 v2, v97, v2
	v_cvt_pk_bf16_f32 v154, v124, v125
	v_cvt_pk_bf16_f32 v155, v126, v127
	ds_read_b64_tr_b16 v[112:113], v4 offset:26624
	ds_read_b64_tr_b16 v[114:115], v4 offset:27136
	s_waitcnt lgkmcnt(13)
	v_mfma_f32_32x32x16_bf16 v[80:95], v[172:175], v[132:135], v[80:95]
	v_add_f32_e32 v2, v98, v2
	v_add_f32_e32 v2, v99, v2
	v_add_f32_e32 v2, v100, v2
	v_add_f32_e32 v2, v101, v2
	v_cvt_pk_bf16_f32 v148, v96, v97
	v_cvt_pk_bf16_f32 v149, v98, v99
	ds_read_b64_tr_b16 v[10:11], v4 offset:30720
	ds_read_b64_tr_b16 v[12:13], v4 offset:31232
	s_waitcnt lgkmcnt(14)
	v_mfma_f32_32x32x16_bf16 v[64:79], v[168:171], v[132:135], v[64:79]
	v_add_f32_e32 v2, v102, v2
	v_add_f32_e32 v2, v103, v2
	v_add_f32_e32 v2, v104, v2
	v_add_f32_e32 v2, v105, v2
	v_cvt_pk_bf16_f32 v150, v100, v101
	v_cvt_pk_bf16_f32 v151, v102, v103
	ds_read_b64_tr_b16 v[6:7], v4 offset:27648
	ds_read_b64_tr_b16 v[8:9], v4 offset:28160
	s_waitcnt lgkmcnt(14)
	v_mfma_f32_32x32x16_bf16 v[80:95], v[164:167], v[128:131], v[80:95]
	v_add_f32_e32 v2, v106, v2
	v_add_f32_e32 v2, v107, v2
	v_add_f32_e32 v2, v108, v2
	v_add_f32_e32 v96, v109, v2
	v_cvt_pk_bf16_f32 v140, v104, v105
	v_cvt_pk_bf16_f32 v141, v106, v107
	ds_read_b64_tr_b16 v[2:3], v4 offset:31744
	ds_read_b64_tr_b16 v[4:5], v4 offset:32256
	v_mfma_f32_32x32x16_bf16 v[64:79], v[160:163], v[128:131], v[64:79]
	v_add_f32_e32 v96, v110, v96
	v_add_f32_e32 v96, v111, v96
	v_add_f32_e32 v96, 0, v96
	v_cvt_pk_bf16_f32 v142, v108, v109
	v_cvt_pk_bf16_f32 v143, v110, v111
	s_add_i32 s68, s46, 2
	s_cmp_ge_u32 s68, s63
	s_cselect_b64 s[44:45], -1, 0
	s_and_b64 vcc, exec, s[44:45]
	s_cbranch_vccnz .LBB0_1749
	s_add_i32 s6, s65, s61
	s_mov_b32 s7, m0
	s_mov_b32 m0, s6
	s_nop 0
	global_load_lds_dwordx4 v[204:205], off
	s_mov_b32 m0, s7

.LBB0_1762:
	s_waitcnt lgkmcnt(4)
	v_mfma_f32_32x32x16_bf16 v[16:31], v[148:151], v[10:13], v[16:31]
	v_exp_f32_e32 v68, v68
	v_exp_f32_e32 v69, v69
	v_exp_f32_e32 v70, v70
	v_exp_f32_e32 v71, v71
	s_waitcnt lgkmcnt(2)
	v_mfma_f32_32x32x16_bf16 v[32:47], v[140:143], v[6:9], v[32:47]
	v_exp_f32_e32 v72, v72
	v_exp_f32_e32 v73, v73
	v_exp_f32_e32 v74, v74
	v_exp_f32_e32 v75, v75
	s_waitcnt lgkmcnt(0)
	v_mfma_f32_32x32x16_bf16 v[16:31], v[140:143], v[2:5], v[16:31]
	v_add_u32_e32 v116, s98, v221
	v_add_u32_e32 v116, 0xf000, v116
	ds_read_b64_tr_b16 v[2:3], v116 offset:24576
	ds_read_b64_tr_b16 v[4:5], v116 offset:25088
	ds_read_b64_tr_b16 v[6:7], v116 offset:28672
	ds_read_b64_tr_b16 v[8:9], v116 offset:29184
	ds_read_b64_tr_b16 v[10:11], v116 offset:25600
	ds_read_b64_tr_b16 v[12:13], v116 offset:26112
	ds_read_b64_tr_b16 v[96:97], v116 offset:29696
	ds_read_b64_tr_b16 v[98:99], v116 offset:30208
	ds_read_b64_tr_b16 v[100:101], v116 offset:26624
	ds_read_b64_tr_b16 v[102:103], v116 offset:27136
	ds_read_b64_tr_b16 v[104:105], v116 offset:30720
	ds_read_b64_tr_b16 v[106:107], v116 offset:31232
	ds_read_b64_tr_b16 v[108:109], v116 offset:27648
	ds_read_b64_tr_b16 v[110:111], v116 offset:28160
	ds_read_b64_tr_b16 v[112:113], v116 offset:31744
	ds_read_b64_tr_b16 v[114:115], v116 offset:32256
	s_waitcnt lgkmcnt(14)
	v_mfma_f32_32x32x16_bf16 v[224:239], v[156:159], v[2:5], v[224:239]
	s_waitcnt lgkmcnt(12)
	v_mfma_f32_32x32x16_bf16 v[240:255], v[156:159], v[6:9], v[240:255]
	s_waitcnt lgkmcnt(10)
	v_mfma_f32_32x32x16_bf16 v[224:239], v[152:155], v[10:13], v[224:239]
	s_waitcnt lgkmcnt(8)
	v_mfma_f32_32x32x16_bf16 v[240:255], v[152:155], v[96:99], v[240:255]
	s_waitcnt lgkmcnt(6)
	v_mfma_f32_32x32x16_bf16 v[224:239], v[148:151], v[100:103], v[224:239]
	s_waitcnt lgkmcnt(4)
	v_mfma_f32_32x32x16_bf16 v[240:255], v[148:151], v[104:107], v[240:255]
	s_waitcnt lgkmcnt(2)
	v_mfma_f32_32x32x16_bf16 v[224:239], v[140:143], v[108:111], v[224:239]
	s_waitcnt lgkmcnt(0)
	v_mfma_f32_32x32x16_bf16 v[240:255], v[140:143], v[112:115], v[240:255]
	v_exp_f32_e32 v76, v76
	v_exp_f32_e32 v77, v77
	v_exp_f32_e32 v78, v78
	v_exp_f32_e32 v79, v79
	s_mov_b64 s[6:7], -1
	s_and_b64 vcc, exec, s[44:45]
	s_cbranch_vccz .LBB0_1774
	s_and_b64 vcc, exec, s[2:3]
	s_cbranch_vccz .LBB0_1765
	s_waitcnt vmcnt(0) lgkmcnt(0)
	s_barrier
	s_mov_b64 s[6:7], 0

.LBB0_1769:
	s_waitcnt lgkmcnt(0)
	ds_read_b128 v[2:5], v207 offset:49248
	ds_read_b128 v[6:9], v207 offset:49216
	ds_read_b128 v[10:13], v207 offset:49184
	ds_read_b128 v[96:99], v207 offset:49152
	s_waitcnt lgkmcnt(3)
	v_pk_mul_f32 v[44:45], v[44:45], v[2:3]
	v_pk_mul_f32 v[236:237], v[236:237], v[2:3]
	s_waitcnt lgkmcnt(2)
	v_pk_mul_f32 v[40:41], v[40:41], v[6:7]
	v_pk_mul_f32 v[232:233], v[232:233], v[6:7]
	s_waitcnt lgkmcnt(1)
	v_pk_mul_f32 v[36:37], v[36:37], v[10:11]
	v_pk_mul_f32 v[228:229], v[228:229], v[10:11]
	v_pk_mul_f32 v[46:47], v[46:47], v[4:5]
	v_pk_mul_f32 v[238:239], v[238:239], v[4:5]
	v_pk_mul_f32 v[42:43], v[42:43], v[8:9]
	v_pk_mul_f32 v[234:235], v[234:235], v[8:9]
	v_pk_mul_f32 v[38:39], v[38:39], v[12:13]
	v_pk_mul_f32 v[230:231], v[230:231], v[12:13]
	s_waitcnt lgkmcnt(0)
	v_pk_mul_f32 v[34:35], v[34:35], v[98:99]
	v_pk_mul_f32 v[226:227], v[226:227], v[98:99]
	v_pk_mul_f32 v[32:33], v[32:33], v[96:97]
	v_pk_mul_f32 v[224:225], v[224:225], v[96:97]
	v_pk_mul_f32 v[28:29], v[28:29], v[2:3]
	v_pk_mul_f32 v[252:253], v[252:253], v[2:3]
	v_pk_mul_f32 v[24:25], v[24:25], v[6:7]
	v_pk_mul_f32 v[248:249], v[248:249], v[6:7]
	v_pk_mul_f32 v[20:21], v[20:21], v[10:11]
	v_pk_mul_f32 v[244:245], v[244:245], v[10:11]
	v_pk_mul_f32 v[30:31], v[30:31], v[4:5]
	v_pk_mul_f32 v[254:255], v[254:255], v[4:5]
	v_pk_mul_f32 v[26:27], v[26:27], v[8:9]
	v_pk_mul_f32 v[250:251], v[250:251], v[8:9]
	v_pk_mul_f32 v[22:23], v[22:23], v[12:13]
	v_pk_mul_f32 v[246:247], v[246:247], v[12:13]
	v_pk_mul_f32 v[18:19], v[18:19], v[98:99]
	v_pk_mul_f32 v[242:243], v[242:243], v[98:99]
	v_pk_mul_f32 v[16:17], v[16:17], v[96:97]
	v_pk_mul_f32 v[240:241], v[240:241], v[96:97]

.LBB0_1773:
	s_waitcnt vmcnt(2) lgkmcnt(0)
	s_barrier
	s_andn2_b64 vcc, exec, s[6:7]
	v_add_u32_e32 v207, s60, v222
	s_cbranch_vccz .LBB0_1746
	s_branch .LBB0_1747

.LBB0_1783:
	v_add_u32_e32 v0, s65, v221
	s_mov_b32 s98, s65
	ds_read_b64_tr_b16 v[192:193], v0 offset:24576
	ds_read_b64_tr_b16 v[194:195], v0 offset:25088
	v_add_f32_e32 v2, v80, v81
	v_add_f32_e32 v2, v82, v2
	v_add_f32_e32 v2, v83, v2
	v_add_f32_e32 v2, v84, v2
	v_add_f32_e32 v2, v85, v2
	v_cvt_pk_bf16_f32 v156, v80, v81
	v_cvt_pk_bf16_f32 v157, v82, v83
	s_waitcnt lgkmcnt(9)
	v_mfma_f32_32x32x16_bf16 v[96:111], v[188:191], v[144:147], v[48:63]
	ds_read_b64_tr_b16 v[124:125], v0 offset:28672
	ds_read_b64_tr_b16 v[126:127], v0 offset:29184
	s_waitcnt lgkmcnt(10)
	v_mfma_f32_32x32x16_bf16 v[48:63], v[184:187], v[144:147], v[48:63]
	v_add_f32_e32 v2, v86, v2
	v_add_f32_e32 v2, v87, v2
	v_add_f32_e32 v2, v88, v2
	v_add_f32_e32 v2, v89, v2
	v_cvt_pk_bf16_f32 v158, v84, v85
	v_cvt_pk_bf16_f32 v159, v86, v87
	ds_read_b64_tr_b16 v[120:121], v0 offset:25600
	ds_read_b64_tr_b16 v[122:123], v0 offset:26112
	v_add_f32_e32 v2, v90, v2
	v_add_f32_e32 v2, v91, v2
	v_add_f32_e32 v2, v92, v2
	v_add_f32_e32 v2, v93, v2
	v_cvt_pk_bf16_f32 v152, v88, v89
	v_cvt_pk_bf16_f32 v153, v90, v91
	s_waitcnt lgkmcnt(11)
	v_mfma_f32_32x32x16_bf16 v[96:111], v[180:183], v[136:139], v[96:111]
	ds_read_b64_tr_b16 v[116:117], v0 offset:29696
	ds_read_b64_tr_b16 v[118:119], v0 offset:30208
	s_waitcnt lgkmcnt(12)
	v_mfma_f32_32x32x16_bf16 v[48:63], v[176:179], v[136:139], v[48:63]
	v_add_f32_e32 v2, v94, v2
	v_add_f32_e32 v2, v95, v2
	v_add_f32_e32 v2, v64, v2
	v_add_f32_e32 v2, v65, v2
	v_cvt_pk_bf16_f32 v154, v92, v93
	v_cvt_pk_bf16_f32 v155, v94, v95
	ds_read_b64_tr_b16 v[112:113], v0 offset:26624
	ds_read_b64_tr_b16 v[114:115], v0 offset:27136
	v_add_f32_e32 v2, v66, v2
	v_add_f32_e32 v2, v67, v2
	v_add_f32_e32 v2, v68, v2
	v_add_f32_e32 v2, v69, v2
	v_cvt_pk_bf16_f32 v148, v64, v65
	v_cvt_pk_bf16_f32 v149, v66, v67
	s_waitcnt lgkmcnt(13)
	v_mfma_f32_32x32x16_bf16 v[96:111], v[172:175], v[132:135], v[96:111]
	ds_read_b64_tr_b16 v[10:11], v0 offset:30720
	ds_read_b64_tr_b16 v[12:13], v0 offset:31232
	s_waitcnt lgkmcnt(14)
	v_mfma_f32_32x32x16_bf16 v[48:63], v[168:171], v[132:135], v[48:63]
	v_add_f32_e32 v2, v70, v2
	v_add_f32_e32 v2, v71, v2
	v_add_f32_e32 v2, v72, v2
	v_add_f32_e32 v2, v73, v2
	v_cvt_pk_bf16_f32 v150, v68, v69
	v_cvt_pk_bf16_f32 v151, v70, v71
	ds_read_b64_tr_b16 v[6:7], v0 offset:27648
	ds_read_b64_tr_b16 v[8:9], v0 offset:28160
	v_add_f32_e32 v2, v74, v2
	v_add_f32_e32 v2, v75, v2
	v_add_f32_e32 v2, v76, v2
	v_add_f32_e32 v14, v77, v2
	v_cvt_pk_bf16_f32 v140, v72, v73
	v_cvt_pk_bf16_f32 v141, v74, v75
	s_waitcnt lgkmcnt(14)
	v_mfma_f32_32x32x16_bf16 v[96:111], v[164:167], v[128:131], v[96:111]
	ds_read_b64_tr_b16 v[2:3], v0 offset:31744
	ds_read_b64_tr_b16 v[4:5], v0 offset:32256
	v_mfma_f32_32x32x16_bf16 v[48:63], v[160:163], v[128:131], v[48:63]
	v_add_f32_e32 v0, v78, v14
	v_add_f32_e32 v0, v79, v0
	v_add_f32_e32 v0, 0, v0
	v_cvt_pk_bf16_f32 v142, v76, v77
	v_cvt_pk_bf16_f32 v143, v78, v79
	v_or_b32_e32 v15, 0xe0, v215
	v_or_b32_e32 v14, 0xc0, v215
	v_cmp_le_i32_e32 vcc, v15, v218
	v_add_f32_e32 v0, v223, v0
	s_nop 2
	v_cndmask_b32_e32 v48, v208, v48, vcc
	v_cmp_lt_i32_e32 vcc, v14, v218
	s_nop 1
	v_cndmask_b32_e32 v65, v208, v97, vcc
	v_cmp_le_i32_e32 vcc, v14, v218
	v_or_b32_e32 v14, 0xe1, v215
	s_nop 0
	v_cndmask_b32_e32 v64, v208, v96, vcc
	v_cmp_le_i32_e32 vcc, v14, v218
	v_or_b32_e32 v14, 0xc2, v215
	v_max_f32_e32 v15, v64, v64
	v_cndmask_b32_e32 v49, v208, v49, vcc
	v_cmp_le_i32_e32 vcc, v14, v218
	v_or_b32_e32 v14, 0xe2, v215
	s_nop 0
	v_cndmask_b32_e32 v66, v208, v98, vcc
	v_cmp_le_i32_e32 vcc, v14, v218
	v_or_b32_e32 v14, 0xc3, v215
	s_nop 0
	v_cndmask_b32_e32 v50, v208, v50, vcc
	v_cmp_le_i32_e32 vcc, v14, v218
	v_or_b32_e32 v14, 0xe3, v215
	s_nop 0
	v_cndmask_b32_e32 v67, v208, v99, vcc
	v_cmp_le_i32_e32 vcc, v14, v218
	v_or_b32_e32 v14, 0xc8, v215
	s_nop 0
	v_cndmask_b32_e32 v51, v208, v51, vcc
	v_cmp_le_i32_e32 vcc, v14, v218
	v_or_b32_e32 v14, 0xe8, v215
	s_nop 0
	v_cndmask_b32_e32 v68, v208, v100, vcc
	v_cmp_le_i32_e32 vcc, v14, v218
	v_or_b32_e32 v14, 0xc9, v215
	s_nop 0
	v_cndmask_b32_e32 v52, v208, v52, vcc
	v_cmp_le_i32_e32 vcc, v14, v218
	v_or_b32_e32 v14, 0xe9, v215
	s_nop 0
	v_cndmask_b32_e32 v69, v208, v101, vcc
	v_cmp_le_i32_e32 vcc, v14, v218
	v_or_b32_e32 v14, 0xca, v215
	s_nop 0
	v_cndmask_b32_e32 v53, v208, v53, vcc
	v_cmp_le_i32_e32 vcc, v14, v218
	v_or_b32_e32 v14, 0xea, v215
	s_nop 0
	v_cndmask_b32_e32 v70, v208, v102, vcc
	v_cmp_le_i32_e32 vcc, v14, v218
	v_or_b32_e32 v14, 0xcb, v215
	s_nop 0
	v_cndmask_b32_e32 v54, v208, v54, vcc
	v_cmp_le_i32_e32 vcc, v14, v218
	v_or_b32_e32 v14, 0xeb, v215
	s_nop 0
	v_cndmask_b32_e32 v71, v208, v103, vcc
	v_cmp_le_i32_e32 vcc, v14, v218
	v_or_b32_e32 v14, 0xd0, v215
	s_nop 0
	v_cndmask_b32_e32 v55, v208, v55, vcc
	v_cmp_le_i32_e32 vcc, v14, v218
	v_or_b32_e32 v14, 0xf0, v215
	s_nop 0
	v_cndmask_b32_e32 v72, v208, v104, vcc
	v_cmp_le_i32_e32 vcc, v14, v218
	v_or_b32_e32 v14, 0xd1, v215
	s_nop 0
	v_cndmask_b32_e32 v56, v208, v56, vcc
	v_cmp_le_i32_e32 vcc, v14, v218
	v_or_b32_e32 v14, 0xf1, v215
	s_nop 0
	v_cndmask_b32_e32 v73, v208, v105, vcc
	v_cmp_le_i32_e32 vcc, v14, v218
	v_or_b32_e32 v14, 0xd2, v215
	s_nop 0
	v_cndmask_b32_e32 v57, v208, v57, vcc
	v_cmp_le_i32_e32 vcc, v14, v218
	v_or_b32_e32 v14, 0xf2, v215
	s_nop 0
	v_cndmask_b32_e32 v74, v208, v106, vcc
	v_cmp_le_i32_e32 vcc, v14, v218
	v_or_b32_e32 v14, 0xd3, v215
	s_nop 0
	v_cndmask_b32_e32 v58, v208, v58, vcc
	v_cmp_le_i32_e32 vcc, v14, v218
	v_or_b32_e32 v14, 0xf3, v215
	s_nop 0
	v_cndmask_b32_e32 v75, v208, v107, vcc
	v_cmp_le_i32_e32 vcc, v14, v218
	v_or_b32_e32 v14, 0xd8, v215
	s_nop 0
	v_cndmask_b32_e32 v59, v208, v59, vcc
	v_cmp_le_i32_e32 vcc, v14, v218
	v_or_b32_e32 v14, 0xf8, v215
	s_nop 0
	v_cndmask_b32_e32 v76, v208, v108, vcc
	v_cmp_le_i32_e32 vcc, v14, v218
	v_or_b32_e32 v14, 0xd9, v215
	s_nop 0
	v_cndmask_b32_e32 v60, v208, v60, vcc
	v_cmp_le_i32_e32 vcc, v14, v218
	v_or_b32_e32 v14, 0xf9, v215
	s_nop 0
	v_cndmask_b32_e32 v77, v208, v109, vcc
	v_cmp_le_i32_e32 vcc, v14, v218
	v_or_b32_e32 v14, 0xda, v215
	s_nop 0
	v_cndmask_b32_e32 v61, v208, v61, vcc
	v_cmp_le_i32_e32 vcc, v14, v218
	v_or_b32_e32 v14, 0xfa, v215
	s_nop 0
	v_cndmask_b32_e32 v78, v208, v110, vcc
	v_cmp_le_i32_e32 vcc, v14, v218
	v_or_b32_e32 v14, 0xdb, v215
	s_nop 0
	v_cndmask_b32_e32 v62, v208, v62, vcc
	v_cmp_le_i32_e32 vcc, v14, v218
	v_or_b32_e32 v14, 0xfb, v215
	s_nop 0
	v_cndmask_b32_e32 v79, v208, v111, vcc
	v_cmp_le_i32_e32 vcc, v14, v218
	v_max_f32_e32 v14, v65, v65
	v_max_f32_e32 v14, v15, v14
	v_max3_f32 v15, v66, v67, v49
	v_max3_f32 v14, v14, v48, v50
	v_max3_f32 v14, v14, v51, v68
	v_max3_f32 v15, v15, v70, v71
	v_max3_f32 v14, v14, v69, v52
	v_max3_f32 v15, v15, v54, v55
	v_max3_f32 v14, v14, v53, v72
	v_max3_f32 v15, v15, v74, v75
	v_max3_f32 v14, v14, v73, v56
	v_max3_f32 v15, v15, v58, v59
	v_cndmask_b32_e32 v63, v208, v63, vcc
	v_max3_f32 v14, v14, v57, v76
	v_max3_f32 v15, v15, v78, v79
	v_max3_f32 v14, v14, v77, v60
	v_max3_f32 v15, v15, v62, v63
	v_max3_f32 v14, v14, v61, v15
	v_mov_b32_e32 v15, v14
	s_nop 1
	v_permlane32_swap_b32_e32 v14, v15
	v_max_f32_e32 v15, v15, v15
	v_max_f32_e32 v14, v14, v14
	v_max_f32_e32 v14, v14, v15
	v_cmp_lt_f32_e32 vcc, s52, v14
	s_cmp_lg_u64 vcc, 0
	s_cselect_b64 s[2:3], -1, 0
	s_cbranch_vccnz .LBB0_1788
.LBB0_1784:
	s_waitcnt lgkmcnt(14)
	v_mfma_f32_32x32x16_bf16 v[32:47], v[156:159], v[192:195], v[32:47]
	v_exp_f32_e32 v64, v64
	v_exp_f32_e32 v65, v65
	v_exp_f32_e32 v66, v66
	v_exp_f32_e32 v67, v67
	s_waitcnt lgkmcnt(12)
	v_mfma_f32_32x32x16_bf16 v[16:31], v[156:159], v[124:127], v[16:31]
	v_exp_f32_e32 v68, v68
	v_exp_f32_e32 v69, v69
	v_exp_f32_e32 v70, v70
	v_exp_f32_e32 v71, v71
	s_waitcnt lgkmcnt(10)
	v_mfma_f32_32x32x16_bf16 v[32:47], v[152:155], v[120:123], v[32:47]
	v_exp_f32_e32 v72, v72
	v_exp_f32_e32 v73, v73
	v_exp_f32_e32 v74, v74
	v_exp_f32_e32 v75, v75
	s_waitcnt lgkmcnt(8)
	v_mfma_f32_32x32x16_bf16 v[16:31], v[152:155], v[116:119], v[16:31]
	v_exp_f32_e32 v76, v76
	v_exp_f32_e32 v77, v77
	v_exp_f32_e32 v78, v78
	v_exp_f32_e32 v79, v79
	s_waitcnt lgkmcnt(6)
	v_mfma_f32_32x32x16_bf16 v[32:47], v[148:151], v[112:115], v[32:47]
	v_exp_f32_e32 v48, v48
	v_exp_f32_e32 v49, v49
	v_exp_f32_e32 v50, v50
	v_exp_f32_e32 v51, v51
	s_waitcnt lgkmcnt(4)
	v_mfma_f32_32x32x16_bf16 v[16:31], v[148:151], v[10:13], v[16:31]
	v_exp_f32_e32 v52, v52
	v_exp_f32_e32 v53, v53
	v_exp_f32_e32 v54, v54
	v_exp_f32_e32 v55, v55
	s_waitcnt lgkmcnt(2)
	v_mfma_f32_32x32x16_bf16 v[32:47], v[140:143], v[6:9], v[32:47]
	v_exp_f32_e32 v56, v56
	v_exp_f32_e32 v57, v57
	v_exp_f32_e32 v58, v58
	v_exp_f32_e32 v59, v59
	s_waitcnt lgkmcnt(0)
	v_mfma_f32_32x32x16_bf16 v[16:31], v[140:143], v[2:5], v[16:31]
	v_add_u32_e32 v14, s98, v221
	v_add_u32_e32 v14, 0xf000, v14
	ds_read_b64_tr_b16 v[2:3], v14 offset:24576
	ds_read_b64_tr_b16 v[4:5], v14 offset:25088
	ds_read_b64_tr_b16 v[6:7], v14 offset:28672
	ds_read_b64_tr_b16 v[8:9], v14 offset:29184
	ds_read_b64_tr_b16 v[10:11], v14 offset:25600
	ds_read_b64_tr_b16 v[12:13], v14 offset:26112
	ds_read_b64_tr_b16 v[80:81], v14 offset:29696
	ds_read_b64_tr_b16 v[82:83], v14 offset:30208
	ds_read_b64_tr_b16 v[84:85], v14 offset:26624
	ds_read_b64_tr_b16 v[86:87], v14 offset:27136
	ds_read_b64_tr_b16 v[88:89], v14 offset:30720
	ds_read_b64_tr_b16 v[90:91], v14 offset:31232
	ds_read_b64_tr_b16 v[92:93], v14 offset:27648
	ds_read_b64_tr_b16 v[94:95], v14 offset:28160
	ds_read_b64_tr_b16 v[96:97], v14 offset:31744
	ds_read_b64_tr_b16 v[98:99], v14 offset:32256
	s_waitcnt lgkmcnt(14)
	v_mfma_f32_32x32x16_bf16 v[224:239], v[156:159], v[2:5], v[224:239]
	s_waitcnt lgkmcnt(12)
	v_mfma_f32_32x32x16_bf16 v[240:255], v[156:159], v[6:9], v[240:255]
	s_waitcnt lgkmcnt(10)
	v_mfma_f32_32x32x16_bf16 v[224:239], v[152:155], v[10:13], v[224:239]
	s_waitcnt lgkmcnt(8)
	v_mfma_f32_32x32x16_bf16 v[240:255], v[152:155], v[80:83], v[240:255]
	s_waitcnt lgkmcnt(6)
	v_mfma_f32_32x32x16_bf16 v[224:239], v[148:151], v[84:87], v[224:239]
	s_waitcnt lgkmcnt(4)
	v_mfma_f32_32x32x16_bf16 v[240:255], v[148:151], v[88:91], v[240:255]
	s_waitcnt lgkmcnt(2)
	v_mfma_f32_32x32x16_bf16 v[224:239], v[140:143], v[92:95], v[224:239]
	s_waitcnt lgkmcnt(0)
	v_mfma_f32_32x32x16_bf16 v[240:255], v[140:143], v[96:99], v[240:255]
	v_exp_f32_e32 v60, v60
	v_exp_f32_e32 v61, v61
	v_exp_f32_e32 v62, v62
	v_exp_f32_e32 v63, v63
	s_andn2_b64 vcc, exec, s[2:3]
	v_lshl_add_u32 v2, v215, 2, s60
	s_cbranch_vccnz .LBB0_1786
	s_waitcnt lgkmcnt(0)
	ds_read_b128 v[4:7], v2 offset:49248
	ds_read_b128 v[8:11], v2 offset:49216
	ds_read_b128 v[12:15], v2 offset:49184
	ds_read_b128 v[80:83], v2 offset:49152
	s_waitcnt lgkmcnt(3)
	v_pk_mul_f32 v[46:47], v[46:47], v[6:7]
	v_pk_mul_f32 v[238:239], v[238:239], v[6:7]
	s_waitcnt lgkmcnt(2)
	v_pk_mul_f32 v[42:43], v[42:43], v[10:11]
	v_pk_mul_f32 v[234:235], v[234:235], v[10:11]
	s_waitcnt lgkmcnt(1)
	v_pk_mul_f32 v[38:39], v[38:39], v[14:15]
	v_pk_mul_f32 v[230:231], v[230:231], v[14:15]
	s_waitcnt lgkmcnt(0)
	v_pk_mul_f32 v[34:35], v[34:35], v[82:83]
	v_pk_mul_f32 v[226:227], v[226:227], v[82:83]
	v_pk_mul_f32 v[44:45], v[44:45], v[4:5]
	v_pk_mul_f32 v[236:237], v[236:237], v[4:5]
	v_pk_mul_f32 v[40:41], v[40:41], v[8:9]
	v_pk_mul_f32 v[232:233], v[232:233], v[8:9]
	v_pk_mul_f32 v[36:37], v[36:37], v[12:13]
	v_pk_mul_f32 v[228:229], v[228:229], v[12:13]
	v_pk_mul_f32 v[32:33], v[32:33], v[80:81]
	v_pk_mul_f32 v[224:225], v[224:225], v[80:81]
	v_pk_mul_f32 v[30:31], v[30:31], v[6:7]
	v_pk_mul_f32 v[254:255], v[254:255], v[6:7]
	v_pk_mul_f32 v[26:27], v[26:27], v[10:11]
	v_pk_mul_f32 v[250:251], v[250:251], v[10:11]
	v_pk_mul_f32 v[22:23], v[22:23], v[14:15]
	v_pk_mul_f32 v[246:247], v[246:247], v[14:15]
	v_pk_mul_f32 v[18:19], v[18:19], v[82:83]
	v_pk_mul_f32 v[242:243], v[242:243], v[82:83]
	v_pk_mul_f32 v[28:29], v[28:29], v[4:5]
	v_pk_mul_f32 v[252:253], v[252:253], v[4:5]
	v_pk_mul_f32 v[24:25], v[24:25], v[8:9]
	v_pk_mul_f32 v[248:249], v[248:249], v[8:9]
	v_pk_mul_f32 v[20:21], v[20:21], v[12:13]
	v_pk_mul_f32 v[244:245], v[244:245], v[12:13]
	v_pk_mul_f32 v[16:17], v[16:17], v[80:81]
	v_pk_mul_f32 v[240:241], v[240:241], v[80:81]
.LBB0_1786:
	v_add_f32_e32 v4, v64, v65
	v_add_f32_e32 v4, v66, v4
	v_add_f32_e32 v4, v67, v4
	v_add_f32_e32 v4, v68, v4
	v_add_f32_e32 v4, v69, v4
	v_add_f32_e32 v4, v70, v4
	v_add_f32_e32 v4, v71, v4
	v_add_f32_e32 v4, v72, v4
	v_add_f32_e32 v4, v73, v4
	v_add_f32_e32 v4, v74, v4
	v_add_f32_e32 v4, v75, v4
	v_add_f32_e32 v4, v76, v4
	v_add_f32_e32 v4, v77, v4
	v_add_f32_e32 v4, v78, v4
	v_add_f32_e32 v4, v79, v4
	v_add_f32_e32 v4, v48, v4
	v_add_f32_e32 v4, v49, v4
	v_add_f32_e32 v4, v50, v4
	v_add_f32_e32 v4, v51, v4
	v_add_f32_e32 v4, v52, v4
	v_add_f32_e32 v4, v53, v4
	v_add_f32_e32 v4, v54, v4
	v_add_f32_e32 v4, v55, v4
	v_add_f32_e32 v4, v56, v4
	v_add_f32_e32 v4, v57, v4
	v_add_f32_e32 v4, v58, v4
	v_add_f32_e32 v4, v59, v4
	v_add_f32_e32 v4, v60, v4
	s_cmp_lg_u32 0, -1
	v_add_f32_e32 v4, v61, v4
	s_cselect_b32 s2, 0, 0
	v_add_f32_e32 v4, v62, v4
	s_addk_i32 s2, 0x6000
	v_add_f32_e32 v4, v63, v4
	v_add3_u32 v3, v216, s2, v213
	v_add_f32_e32 v0, v0, v4
	v_cvt_pk_bf16_f32 v4, v64, v65
	v_cvt_pk_bf16_f32 v5, v66, v67
	v_cvt_pk_bf16_f32 v6, v68, v69
	v_cvt_pk_bf16_f32 v7, v70, v71
	v_cvt_pk_bf16_f32 v8, v72, v73
	v_cvt_pk_bf16_f32 v9, v74, v75
	v_cvt_pk_bf16_f32 v10, v76, v77
	v_cvt_pk_bf16_f32 v11, v78, v79
	v_cvt_pk_bf16_f32 v12, v48, v49
	v_cvt_pk_bf16_f32 v13, v50, v51
	v_cvt_pk_bf16_f32 v14, v52, v53
	v_cvt_pk_bf16_f32 v15, v54, v55
	v_cvt_pk_bf16_f32 v48, v56, v57
	v_cvt_pk_bf16_f32 v49, v58, v59
	v_cvt_pk_bf16_f32 v50, v60, v61
	v_cvt_pk_bf16_f32 v51, v62, v63
	v_add3_u32 v3, v3, v214, s64
	v_add_u32_e32 v84, 0xf000, v3
	ds_read_b64_tr_b16 v[52:53],v3 offset:0
	ds_read_b64_tr_b16 v[54:55],v3 offset:512
	ds_read_b64_tr_b16 v[56:57],v3 offset:1024
	ds_read_b64_tr_b16 v[58:59],v3 offset:1536
	ds_read_b64_tr_b16 v[60:61],v3 offset:2048
	ds_read_b64_tr_b16 v[62:63],v3 offset:2560
	ds_read_b64_tr_b16 v[64:65],v3 offset:3072
	ds_read_b64_tr_b16 v[66:67],v3 offset:3584
	s_waitcnt lgkmcnt(0)
	s_nop 0
	v_mfma_f32_32x32x16_bf16 v[32:47], v[4:7], v[52:55], v[32:47]
	ds_read_b64_tr_b16 v[52:53],v3 offset:4096
	ds_read_b64_tr_b16 v[54:55],v3 offset:4608
	v_mfma_f32_32x32x16_bf16 v[32:47], v[8:11], v[56:59], v[32:47]
	ds_read_b64_tr_b16 v[56:57],v3 offset:5120
	ds_read_b64_tr_b16 v[58:59],v3 offset:5632
	v_mfma_f32_32x32x16_bf16 v[32:47], v[12:15], v[60:63], v[32:47]
	ds_read_b64_tr_b16 v[60:61],v3 offset:6144
	ds_read_b64_tr_b16 v[62:63],v3 offset:6656
	ds_read_b64_tr_b16 v[68:69],v3 offset:7168
	ds_read_b64_tr_b16 v[70:71],v3 offset:7680
	s_waitcnt lgkmcnt(0)
	v_mfma_f32_32x32x16_bf16 v[32:47], v[48:51], v[64:67], v[32:47]
	v_mfma_f32_32x32x16_bf16 v[16:31], v[4:7], v[52:55], v[16:31]
	v_mov_b32_e32 v3, v0
	s_nop 1
	v_permlane32_swap_b32_e32 v0, v3
	v_cmp_gt_u32_e32 vcc, 32, v209
	v_mfma_f32_32x32x16_bf16 v[16:31], v[8:11], v[56:59], v[16:31]
	v_mfma_f32_32x32x16_bf16 v[16:31], v[12:15], v[60:63], v[16:31]
	v_mfma_f32_32x32x16_bf16 v[16:31], v[48:51], v[68:71], v[16:31]
	ds_read_b64_tr_b16 v[52:53], v84 offset:0
	ds_read_b64_tr_b16 v[54:55], v84 offset:512
	ds_read_b64_tr_b16 v[56:57], v84 offset:1024
	ds_read_b64_tr_b16 v[58:59], v84 offset:1536
	ds_read_b64_tr_b16 v[60:61], v84 offset:2048
	ds_read_b64_tr_b16 v[62:63], v84 offset:2560
	ds_read_b64_tr_b16 v[64:65], v84 offset:3072
	ds_read_b64_tr_b16 v[66:67], v84 offset:3584
	ds_read_b64_tr_b16 v[68:69], v84 offset:4096
	ds_read_b64_tr_b16 v[70:71], v84 offset:4608
	ds_read_b64_tr_b16 v[72:73], v84 offset:5120
	ds_read_b64_tr_b16 v[74:75], v84 offset:5632
	ds_read_b64_tr_b16 v[76:77], v84 offset:6144
	ds_read_b64_tr_b16 v[78:79], v84 offset:6656
	ds_read_b64_tr_b16 v[80:81], v84 offset:7168
	ds_read_b64_tr_b16 v[82:83], v84 offset:7680
	s_waitcnt lgkmcnt(14)
	v_mfma_f32_32x32x16_bf16 v[224:239], v[4:7], v[52:55], v[224:239]
	s_waitcnt lgkmcnt(12)
	v_mfma_f32_32x32x16_bf16 v[224:239], v[8:11], v[56:59], v[224:239]
	s_waitcnt lgkmcnt(10)
	v_mfma_f32_32x32x16_bf16 v[224:239], v[12:15], v[60:63], v[224:239]
	s_waitcnt lgkmcnt(8)
	v_mfma_f32_32x32x16_bf16 v[224:239], v[48:51], v[64:67], v[224:239]
	s_waitcnt lgkmcnt(6)
	v_mfma_f32_32x32x16_bf16 v[240:255], v[4:7], v[68:71], v[240:255]
	s_waitcnt lgkmcnt(4)
	v_mfma_f32_32x32x16_bf16 v[240:255], v[8:11], v[72:75], v[240:255]
	s_waitcnt lgkmcnt(2)
	v_mfma_f32_32x32x16_bf16 v[240:255], v[12:15], v[76:79], v[240:255]
	s_waitcnt lgkmcnt(0)
	v_mfma_f32_32x32x16_bf16 v[240:255], v[48:51], v[80:83], v[240:255]
	s_and_saveexec_b64 s[2:3], vcc
	s_cbranch_execz .LBB0_1712
	v_add_f32_e32 v0, v0, v3
	ds_write_b32 v217, v0 offset:49280
	s_branch .LBB0_1712

	.amdhsa_kernel _ZN2mk3fwdENS_6ParamsE
		.amdhsa_group_segment_fixed_size 0
		.amdhsa_private_segment_fixed_size 0
		.amdhsa_kernarg_size 504
		.amdhsa_user_sgpr_count 2
		.amdhsa_user_sgpr_dispatch_ptr 0
		.amdhsa_user_sgpr_queue_ptr 0
		.amdhsa_user_sgpr_kernarg_segment_ptr 1
		.amdhsa_user_sgpr_dispatch_id 0
		.amdhsa_user_sgpr_kernarg_preload_length 0
		.amdhsa_user_sgpr_kernarg_preload_offset 0
		.amdhsa_user_sgpr_private_segment_size 0
		.amdhsa_uses_dynamic_stack 0
		.amdhsa_enable_private_segment 0
		.amdhsa_system_sgpr_workgroup_id_x 1
		.amdhsa_system_sgpr_workgroup_id_y 0
		.amdhsa_system_sgpr_workgroup_id_z 0
		.amdhsa_system_sgpr_workgroup_info 0
		.amdhsa_system_vgpr_workitem_id 2
		.amdhsa_next_free_vgpr 256
		.amdhsa_next_free_sgpr 102
		.amdhsa_accum_offset 256
		.amdhsa_reserve_vcc 1
		.amdhsa_float_round_mode_32 0
		.amdhsa_float_round_mode_16_64 0
		.amdhsa_float_denorm_mode_32 3
		.amdhsa_float_denorm_mode_16_64 3
		.amdhsa_dx10_clamp 1
		.amdhsa_ieee_mode 1
		.amdhsa_fp16_overflow 0
		.amdhsa_tg_split 0
		.amdhsa_exception_fp_ieee_invalid_op 0
		.amdhsa_exception_fp_denorm_src 0
		.amdhsa_exception_fp_ieee_div_zero 0
		.amdhsa_exception_fp_ieee_overflow 0
		.amdhsa_exception_fp_ieee_underflow 0
		.amdhsa_exception_fp_ieee_inexact 0
		.amdhsa_exception_int_div_zero 0
	.end_amdhsa_kernel

amdhsa.kernels:
  - .agpr_count:     0
    .args:
      - .offset:         0
        .size:           248
        .value_kind:     by_value
      - .offset:         248
        .size:           4
        .value_kind:     hidden_block_count_x
      - .offset:         252
        .size:           4
        .value_kind:     hidden_block_count_y
      - .offset:         256
        .size:           4
        .value_kind:     hidden_block_count_z
      - .offset:         260
        .size:           2
        .value_kind:     hidden_group_size_x
      - .offset:         262
        .size:           2
        .value_kind:     hidden_group_size_y
      - .offset:         264
        .size:           2
        .value_kind:     hidden_group_size_z
      - .offset:         266
        .size:           2
        .value_kind:     hidden_remainder_x
      - .offset:         268
        .size:           2
        .value_kind:     hidden_remainder_y
      - .offset:         270
        .size:           2
        .value_kind:     hidden_remainder_z
      - .offset:         288
        .size:           8
        .value_kind:     hidden_global_offset_x
      - .offset:         296
        .size:           8
        .value_kind:     hidden_global_offset_y
      - .offset:         304
        .size:           8
        .value_kind:     hidden_global_offset_z
      - .offset:         312
        .size:           2
        .value_kind:     hidden_grid_dims
      - .offset:         336
        .size:           8
        .value_kind:     hidden_multigrid_sync_arg
      - .offset:         368
        .size:           4
        .value_kind:     hidden_dynamic_lds_size
    .group_segment_fixed_size: 0
    .kernarg_segment_align: 8
    .kernarg_segment_size: 504
    .language:       OpenCL C
    .language_version:
      - 2
      - 0
    .max_flat_workgroup_size: 512
    .name:           _ZN2mk3fwdENS_6ParamsE
    .private_segment_fixed_size: 0
    .sgpr_count:     108
    .sgpr_spill_count: 33
    .symbol:         _ZN2mk3fwdENS_6ParamsE.kd
    .uniform_work_group_size: 1
    .uses_dynamic_stack: false
    .vgpr_count:     256
    .vgpr_spill_count: 0
    .wavefront_size: 64
